# fox Fc reads hoisted; redundant post-asm pads in select removed; score loop 3x unrolled with key fragments prefetched two tiles ahead
# speedup vs baseline: 1.0092x; 1.0053x over previous
; #define AT_STAGE(tile) do { const int _i = (tile) < nkt ? (tile) : (nkt - 1); const int _t = AT_TILE(_i); char* _s = dynsmem + ((tile) & 3) * 32768 + tid * 16; \
;     const u16* _kg = Kg0 + (size_t)_t * 64 * ldk; const u16* _vg = Vg0 + _t * 64; \
;     AT_GLDS(_kg, _s); AT_GLDS(_kg + k32, _s + 8192); AT_GLDS(_vg, _s + 16384); AT_GLDS(_vg + v64, _s + 16384 + 8192); } while (0)
; template <int MODE>
; DI void attn_item(const u16* Qp, int ldq, const u16* Kp, int ldk, const u16* VTp, int ldv, u16* Op, int ldo,
;                   int q0, int nkt, const float* Fc, const unsigned* BM, float kmaxn, char* smem) {
;     ...
;   for (int kt = 0; kt < nkt; ++kt) {
;     const char* sKn = smem + ((kt + 1) & 3) * 32768;
;     const char* sV = smem + (kt & 3) * 32768 + 16384;
;     const float* sF = fct + (kt & 3) * 64;
;     const int ts = AT_TILE(kt) * 64;
;     const bool more1 = (kt + 1 < nkt);
;     uint2 bwn = make_uint2(0xffffffffu, 0xffffffffu);
;     const int tn = AT_TILE(more1 ? (kt + 1) : kt);
;     float flast = 0.f;
;     if (MODE == 1) { rf = *(const f32x4*)(Fc + tn * 64 + (tid & 15) * 4); flast = Fc[tn * 64 + 63]; }
;     if (MODE == 2) bwn = *(const uint2*)(bmq + tn * 2);
;     AT_STAGE(kt + 3);
;     const bool diag = (MODE == 1) && (ts + 63 > qw);
;     float mx = -1e30f;
;     if (MODE == 1) {
; #pragma unroll
;       for (int k2 = 0; k2 < 2; ++k2)
; #pragma unroll
;         for (int j = 0; j < 4; ++j) {
;           const int kl = 32 * k2 + 16 * (j >> 1) + 8 * h + 4 * (j & 1);
;           const f32x4 f4 = *(const f32x4*)(sF + kl);
; #pragma unroll
;           for (int i = 0; i < 4; ++i) {
;             float x = sc[k2][j * 4 + i] * c1 + (fcq - f4[i]);
;             if (diag && (ts + kl + i > q)) x = -1e30f;
;             sc[k2][j * 4 + i] = x;
;             mx = fmaxf(mx, x);
;           }
;         }
.LBB0_475:
	s_add_i32 s18, s14, 1
	s_and_b32 s15, s14, 3
	s_cmp_lt_i32 s18, s63
	s_cselect_b32 s10, s18, s14
	s_sub_i32 s10, s51, s10
	s_lshl_b32 s10, s10, 6
	s_ashr_i32 s11, s10, 31
	s_lshl_b64 s[10:11], s[10:11], 2
	s_add_u32 s10, s38, s10
	s_addc_u32 s11, s39, s11
	global_load_dwordx4 v[130:133], v142, s[10:11]
	global_load_dword v165, v1, s[10:11] offset:252
	s_add_i32 s10, s14, 3
	s_min_i32 s10, s10, s51
	s_sub_i32 s14, s51, s10
	s_and_b32 s10, s17, 0x18000
	v_add_u32_e32 v170, s10, v144
	v_mad_i64_i32 v[166:167], s[10:11], s14, v211, v[136:137]
	s_lshl_b32 s10, s14, 6
	s_ashr_i32 s11, s10, 31
	v_lshl_add_u64 v[168:169], s[10:11], 1, v[138:139]
	v_readfirstlane_b32 s10, v170
	v_add_u32_e32 v171, 0x2000, v170
	s_mov_b32 m0, s10
	v_readfirstlane_b32 s10, v171
	global_load_lds_dwordx4 v[166:167], off
	v_lshl_add_u64 v[166:167], v[166:167], 0, s[84:85]
	s_mov_b32 m0, s10
	v_add_u32_e32 v171, s16, v0
	global_load_lds_dwordx4 v[166:167], off
	v_add_u32_e32 v166, 0x4000, v170
	v_subrev_u32_e32 v176, 63, v171
	v_readfirstlane_b32 s10, v166
	s_mov_b32 m0, s10
	v_lshl_add_u64 v[166:167], v[168:169], 0, s[86:87]
	global_load_lds_dwordx4 v[168:169], off
	v_add_u32_e32 v168, 0x6000, v170
	v_lshl_add_u32 v170, s15, 8, v162
	v_readfirstlane_b32 s10, v168
	s_mov_b32 m0, s10
	v_cmp_gt_i32_e64 s[10:11], s16, v140
	global_load_lds_dwordx4 v[166:167], off
	ds_read_b128 v[166:169], v170
	ds_read_b128 v[172:175], v170 offset:16
	ds_read_b128 v[212:215], v170 offset:64
	ds_read_b128 v[234:237], v170 offset:80
	ds_read_b128 v[238:241], v170 offset:128
	ds_read_b128 v[242:245], v170 offset:144
	ds_read_b128 v[246:249], v170 offset:192
	ds_read_b128 v[250:253], v170 offset:208
	v_cmp_gt_i32_e32 vcc, v176, v134
	s_and_b64 vcc, s[10:11], vcc
	s_mov_b32 s14, 0xf149f2ca
	s_waitcnt lgkmcnt(0)
	v_sub_f32_e32 v166, v141, v166
	v_fmac_f32_e32 v166, 0x3e0293ee, v66
	v_sub_f32_e32 v66, v141, v167
	v_cndmask_b32_e32 v185, v166, v219, vcc
	v_fmac_f32_e32 v66, 0x3e0293ee, v67
	v_cmp_ge_i32_e32 vcc, v176, v134
	v_sub_f32_e32 v67, v141, v168
	s_and_b64 vcc, s[10:11], vcc
	v_fmac_f32_e32 v67, 0x3e0293ee, v68
	v_subrev_u32_e32 v68, 61, v171
	v_cndmask_b32_e32 v191, v66, v219, vcc
	v_cmp_gt_i32_e32 vcc, v68, v134
	s_and_b64 vcc, s[10:11], vcc
	v_subrev_u32_e32 v68, 60, v171
	v_cndmask_b32_e32 v192, v67, v219, vcc
	v_sub_f32_e32 v67, v141, v169
	v_cmp_gt_i32_e32 vcc, v68, v134
	v_fmac_f32_e32 v67, 0x3e0293ee, v69
	s_and_b64 vcc, s[10:11], vcc
	v_cndmask_b32_e32 v193, v67, v219, vcc
	v_subrev_u32_e32 v67, 59, v171
	v_sub_f32_e32 v68, v141, v172
	v_cmp_gt_i32_e32 vcc, v67, v134
	v_fmac_f32_e32 v68, 0x3e0293ee, v70
	s_and_b64 vcc, s[10:11], vcc
	v_cndmask_b32_e32 v198, v68, v219, vcc
	v_sub_f32_e32 v68, v141, v173
	v_cmp_ge_i32_e32 vcc, v67, v134
	v_fmac_f32_e32 v68, 0x3e0293ee, v71
	s_and_b64 vcc, s[10:11], vcc
	v_cndmask_b32_e32 v197, v68, v219, vcc
	v_subrev_u32_e32 v68, 57, v171
	v_sub_f32_e32 v67, v141, v174
	v_cmp_gt_i32_e32 vcc, v68, v134
	v_fmac_f32_e32 v67, 0x3e0293ee, v72
	s_and_b64 vcc, s[10:11], vcc
	v_subrev_u32_e32 v68, 56, v171
	v_max3_f32 v66, v185, s14, v191
	v_cndmask_b32_e32 v195, v67, v219, vcc
	v_sub_f32_e32 v67, v141, v175
	v_cmp_gt_i32_e32 vcc, v68, v134
	v_max3_f32 v66, v66, v192, v193
	v_fmac_f32_e32 v67, 0x3e0293ee, v73
	s_and_b64 vcc, s[10:11], vcc
	v_max3_f32 v66, v66, v198, v197
	v_cndmask_b32_e32 v196, v67, v219, vcc
	v_max3_f32 v70, v66, v195, v196
	v_subrev_u32_e32 v71, 47, v171
	v_cmp_gt_i32_e32 vcc, v71, v134
	s_and_b64 vcc, s[10:11], vcc
	s_waitcnt lgkmcnt(0)
	v_sub_f32_e32 v66, v141, v212
	v_fmac_f32_e32 v66, 0x3e0293ee, v74
	v_cndmask_b32_e32 v184, v66, v219, vcc
	v_sub_f32_e32 v66, v141, v213
	v_cmp_ge_i32_e32 vcc, v71, v134
	v_fmac_f32_e32 v66, 0x3e0293ee, v75
	s_and_b64 vcc, s[10:11], vcc
	v_sub_f32_e32 v67, v141, v214
	v_subrev_u32_e32 v68, 45, v171
	v_cndmask_b32_e32 v183, v66, v219, vcc
	v_cmp_gt_i32_e32 vcc, v68, v134
	v_fmac_f32_e32 v67, 0x3e0293ee, v76
	s_and_b64 vcc, s[10:11], vcc
	v_subrev_u32_e32 v68, 44, v171
	v_cndmask_b32_e32 v182, v67, v219, vcc
	v_sub_f32_e32 v67, v141, v215
	v_cmp_gt_i32_e32 vcc, v68, v134
	v_fmac_f32_e32 v67, 0x3e0293ee, v77
	s_and_b64 vcc, s[10:11], vcc
	v_max3_f32 v66, v70, v184, v183
	v_cndmask_b32_e32 v179, v67, v219, vcc
	v_max3_f32 v70, v66, v182, v179
	v_subrev_u32_e32 v71, 43, v171
	v_cmp_gt_i32_e32 vcc, v71, v134
	s_and_b64 vcc, s[10:11], vcc
	s_waitcnt lgkmcnt(0)
	v_sub_f32_e32 v66, v141, v234
	v_fmac_f32_e32 v66, 0x3e0293ee, v78
	v_cndmask_b32_e32 v194, v66, v219, vcc
	v_sub_f32_e32 v66, v141, v235
	v_cmp_ge_i32_e32 vcc, v71, v134
	v_fmac_f32_e32 v66, 0x3e0293ee, v79
	s_and_b64 vcc, s[10:11], vcc
	v_sub_f32_e32 v67, v141, v236
	v_subrev_u32_e32 v68, 41, v171
	v_cndmask_b32_e32 v188, v66, v219, vcc
	v_cmp_gt_i32_e32 vcc, v68, v134
	v_fmac_f32_e32 v67, 0x3e0293ee, v80
	s_and_b64 vcc, s[10:11], vcc
	v_subrev_u32_e32 v68, 40, v171
	v_cndmask_b32_e32 v186, v67, v219, vcc
	v_sub_f32_e32 v67, v141, v237
	v_cmp_gt_i32_e32 vcc, v68, v134
	v_fmac_f32_e32 v67, 0x3e0293ee, v81
	s_and_b64 vcc, s[10:11], vcc
	v_max3_f32 v66, v70, v194, v188
	v_cndmask_b32_e32 v187, v67, v219, vcc
	v_max3_f32 v70, v66, v186, v187
	v_subrev_u32_e32 v71, 31, v171
	v_cmp_gt_i32_e32 vcc, v71, v134
	s_and_b64 vcc, s[10:11], vcc
	s_waitcnt lgkmcnt(0)
; DI float shflx(float v, int m, int lane) { return __int_as_float(__builtin_amdgcn_ds_bpermute((lane ^ m) << 2, __float_as_int(v))); }
; template <int MODE>
; DI void attn_item(const u16* Qp, int ldq, const u16* Kp, int ldk, const u16* VTp, int ldv, u16* Op, int ldo,
;                   int q0, int nkt, const float* Fc, const unsigned* BM, float kmaxn, char* smem) {
;     ...
;     const bool diag = (MODE == 1) && (ts + 63 > qw);
;     float mx = -1e30f;
;     if (MODE == 1) {
; #pragma unroll
;       for (int k2 = 0; k2 < 2; ++k2)
; #pragma unroll
;         for (int j = 0; j < 4; ++j) {
;           const int kl = 32 * k2 + 16 * (j >> 1) + 8 * h + 4 * (j & 1);
;           const f32x4 f4 = *(const f32x4*)(sF + kl);
; #pragma unroll
;           for (int i = 0; i < 4; ++i) {
;             float x = sc[k2][j * 4 + i] * c1 + (fcq - f4[i]);
;             if (diag && (ts + kl + i > q)) x = -1e30f;
;             sc[k2][j * 4 + i] = x;
;             mx = fmaxf(mx, x);
;           }
;         }
;     } else {
; #pragma unroll
;       for (int k2 = 0; k2 < 2; ++k2)
; #pragma unroll
;         for (int e = 0; e < 16; ++e) mx = fmaxf(mx, sc[k2][e]);
;       mx *= c1;
;     }
;     mx = fmaxf(mx, shflx(mx, 32, lane));
;     if (__any(mx > m_run + 8.f)) {
;       const float m_new = fmaxf(m_run, mx);
;       const float alpha = __builtin_amdgcn_exp2f(m_run - m_new);
;       m_run = m_new; l_run *= alpha;
; #pragma unroll
;       for (int i = 0; i < 4; ++i)
; #pragma unroll
;         for (int e = 0; e < 16; ++e) o[i][e] *= alpha;
;     }
	v_sub_f32_e32 v66, v141, v238
	v_fmac_f32_e32 v66, 0x3e0293ee, v82
	v_cndmask_b32_e32 v176, v66, v219, vcc
	v_sub_f32_e32 v66, v141, v239
	v_cmp_ge_i32_e32 vcc, v71, v134
	v_fmac_f32_e32 v66, 0x3e0293ee, v83
	s_and_b64 vcc, s[10:11], vcc
	v_sub_f32_e32 v67, v141, v240
	v_subrev_u32_e32 v68, 29, v171
	v_cndmask_b32_e32 v175, v66, v219, vcc
	v_cmp_gt_i32_e32 vcc, v68, v134
	v_fmac_f32_e32 v67, 0x3e0293ee, v84
	s_and_b64 vcc, s[10:11], vcc
	v_subrev_u32_e32 v68, 28, v171
	v_cndmask_b32_e32 v174, v67, v219, vcc
	v_sub_f32_e32 v67, v141, v241
	v_cmp_gt_i32_e32 vcc, v68, v134
	v_fmac_f32_e32 v67, 0x3e0293ee, v85
	s_and_b64 vcc, s[10:11], vcc
	v_max3_f32 v66, v70, v176, v175
	v_cndmask_b32_e32 v173, v67, v219, vcc
	v_max3_f32 v70, v66, v174, v173
	v_subrev_u32_e32 v71, 27, v171
	v_cmp_gt_i32_e32 vcc, v71, v134
	s_and_b64 vcc, s[10:11], vcc
	s_waitcnt lgkmcnt(0)
	v_sub_f32_e32 v66, v141, v242
	v_fmac_f32_e32 v66, 0x3e0293ee, v86
	v_cndmask_b32_e32 v190, v66, v219, vcc
	v_sub_f32_e32 v66, v141, v243
	v_cmp_ge_i32_e32 vcc, v71, v134
	v_fmac_f32_e32 v66, 0x3e0293ee, v87
	s_and_b64 vcc, s[10:11], vcc
	v_sub_f32_e32 v67, v141, v244
	v_subrev_u32_e32 v68, 25, v171
	v_cndmask_b32_e32 v180, v66, v219, vcc
	v_cmp_gt_i32_e32 vcc, v68, v134
	v_fmac_f32_e32 v67, 0x3e0293ee, v88
	s_and_b64 vcc, s[10:11], vcc
	v_subrev_u32_e32 v68, 24, v171
	v_cndmask_b32_e32 v177, v67, v219, vcc
	v_sub_f32_e32 v67, v141, v245
	v_cmp_gt_i32_e32 vcc, v68, v134
	v_fmac_f32_e32 v67, 0x3e0293ee, v89
	s_and_b64 vcc, s[10:11], vcc
	v_max3_f32 v66, v70, v190, v180
	v_cndmask_b32_e32 v178, v67, v219, vcc
	v_max3_f32 v70, v66, v177, v178
	v_add_u32_e32 v71, -15, v171
	v_cmp_gt_i32_e32 vcc, v71, v134
	s_and_b64 vcc, s[10:11], vcc
	s_waitcnt lgkmcnt(0)
	v_sub_f32_e32 v66, v141, v246
	v_fmac_f32_e32 v66, 0x3e0293ee, v90
	v_cndmask_b32_e32 v169, v66, v219, vcc
	v_sub_f32_e32 v66, v141, v247
	v_cmp_ge_i32_e32 vcc, v71, v134
	v_fmac_f32_e32 v66, 0x3e0293ee, v91
	s_and_b64 vcc, s[10:11], vcc
	v_sub_f32_e32 v67, v141, v248
	v_add_u32_e32 v68, -13, v171
	v_cndmask_b32_e32 v168, v66, v219, vcc
	v_cmp_gt_i32_e32 vcc, v68, v134
	v_fmac_f32_e32 v67, 0x3e0293ee, v92
	s_and_b64 vcc, s[10:11], vcc
	v_add_u32_e32 v68, -12, v171
	v_cndmask_b32_e32 v167, v67, v219, vcc
	v_sub_f32_e32 v67, v141, v249
	v_cmp_gt_i32_e32 vcc, v68, v134
	v_fmac_f32_e32 v67, 0x3e0293ee, v93
	s_and_b64 vcc, s[10:11], vcc
	v_max3_f32 v66, v70, v169, v168
	v_cndmask_b32_e32 v166, v67, v219, vcc
	v_max3_f32 v70, v66, v167, v166
	v_add_u32_e32 v71, -11, v171
	v_cmp_gt_i32_e32 vcc, v71, v134
	s_and_b64 vcc, s[10:11], vcc
	s_waitcnt lgkmcnt(0)
	v_sub_f32_e32 v66, v141, v250
	v_fmac_f32_e32 v66, 0x3e0293ee, v94
	v_cndmask_b32_e32 v181, v66, v219, vcc
	v_sub_f32_e32 v66, v141, v251
	v_cmp_ge_i32_e32 vcc, v71, v134
	v_fmac_f32_e32 v66, 0x3e0293ee, v95
	s_and_b64 vcc, s[10:11], vcc
	v_sub_f32_e32 v67, v141, v252
	v_add_u32_e32 v68, -9, v171
	v_cndmask_b32_e32 v172, v66, v219, vcc
	v_cmp_gt_i32_e32 vcc, v68, v134
	v_fmac_f32_e32 v67, 0x3e0293ee, v96
	s_and_b64 vcc, s[10:11], vcc
	v_add_u32_e32 v68, -8, v171
	v_cndmask_b32_e32 v170, v67, v219, vcc
	v_sub_f32_e32 v67, v141, v253
	v_cmp_gt_i32_e32 vcc, v68, v134
	v_fmac_f32_e32 v67, 0x3e0293ee, v97
	s_and_b64 vcc, s[10:11], vcc
	v_max3_f32 v66, v70, v181, v172
	v_cndmask_b32_e32 v171, v67, v219, vcc
	v_max3_f32 v66, v66, v170, v171
	ds_bpermute_b32 v67, v143, v66
	s_waitcnt lgkmcnt(0)
	v_max_f32_e32 v67, v67, v67
	v_max_f32_e32 v66, v66, v67
	v_add_f32_e32 v67, 0x41000000, v164
	v_cmp_gt_f32_e32 vcc, v66, v67
	s_cbranch_vccz .LBB0_477
	v_max_f32_e32 v66, v66, v66
	v_max_f32_e32 v67, v164, v164
	v_max_f32_e32 v67, v67, v66
	v_sub_f32_e32 v66, v164, v67
	v_exp_f32_e32 v66, v66
	v_mov_b32_e32 v164, v67
	v_pk_mul_f32 v[64:65], v[64:65], v[66:67] op_sel_hi:[1,0]
	v_pk_mul_f32 v[62:63], v[62:63], v[66:67] op_sel_hi:[1,0]
	v_pk_mul_f32 v[60:61], v[60:61], v[66:67] op_sel_hi:[1,0]
	v_pk_mul_f32 v[58:59], v[58:59], v[66:67] op_sel_hi:[1,0]
	v_pk_mul_f32 v[56:57], v[56:57], v[66:67] op_sel_hi:[1,0]
	v_pk_mul_f32 v[54:55], v[54:55], v[66:67] op_sel_hi:[1,0]
	v_pk_mul_f32 v[52:53], v[52:53], v[66:67] op_sel_hi:[1,0]
	v_pk_mul_f32 v[50:51], v[50:51], v[66:67] op_sel_hi:[1,0]
	v_pk_mul_f32 v[48:49], v[48:49], v[66:67] op_sel_hi:[1,0]
	v_pk_mul_f32 v[46:47], v[46:47], v[66:67] op_sel_hi:[1,0]
	v_pk_mul_f32 v[44:45], v[44:45], v[66:67] op_sel_hi:[1,0]
	v_pk_mul_f32 v[42:43], v[42:43], v[66:67] op_sel_hi:[1,0]
	v_pk_mul_f32 v[40:41], v[40:41], v[66:67] op_sel_hi:[1,0]
	v_pk_mul_f32 v[38:39], v[38:39], v[66:67] op_sel_hi:[1,0]
	v_pk_mul_f32 v[36:37], v[36:37], v[66:67] op_sel_hi:[1,0]
	v_pk_mul_f32 v[34:35], v[34:35], v[66:67] op_sel_hi:[1,0]
	v_pk_mul_f32 v[32:33], v[32:33], v[66:67] op_sel_hi:[1,0]
	v_pk_mul_f32 v[30:31], v[30:31], v[66:67] op_sel_hi:[1,0]
	v_pk_mul_f32 v[28:29], v[28:29], v[66:67] op_sel_hi:[1,0]
	v_pk_mul_f32 v[26:27], v[26:27], v[66:67] op_sel_hi:[1,0]
	v_pk_mul_f32 v[24:25], v[24:25], v[66:67] op_sel_hi:[1,0]
	v_pk_mul_f32 v[22:23], v[22:23], v[66:67] op_sel_hi:[1,0]
	v_pk_mul_f32 v[20:21], v[20:21], v[66:67] op_sel_hi:[1,0]
	v_pk_mul_f32 v[18:19], v[18:19], v[66:67] op_sel_hi:[1,0]
	v_pk_mul_f32 v[16:17], v[16:17], v[66:67] op_sel_hi:[1,0]
	v_pk_mul_f32 v[14:15], v[14:15], v[66:67] op_sel_hi:[1,0]
	v_pk_mul_f32 v[12:13], v[12:13], v[66:67] op_sel_hi:[1,0]
	v_pk_mul_f32 v[10:11], v[10:11], v[66:67] op_sel_hi:[1,0]
	v_pk_mul_f32 v[8:9], v[8:9], v[66:67] op_sel_hi:[1,0]
	v_pk_mul_f32 v[6:7], v[6:7], v[66:67] op_sel_hi:[1,0]
	v_pk_mul_f32 v[4:5], v[4:5], v[66:67] op_sel_hi:[1,0]
	v_pk_mul_f32 v[2:3], v[2:3], v[66:67] op_sel_hi:[1,0]
	v_mul_f32_e32 v161, v161, v66

; template <int NJ>
; DI void select_row(const float* row, int n, u64* bmrow, int lane) {
;     ...
;     unsigned cand = km & 0xff800000u;
; #pragma unroll 1
;     for (int pr = 0; pr < 4; ++pr) {
;       if (cand <= lo || cand >= hi) break;
;       int c = 0;
; #pragma unroll
;       for (int jj = 0; jj < NJ; ++jj)
;         asm volatile("v_cmp_le_u32 vcc, %1, %2\n\tv_addc_co_u32 %0, vcc, 0, %0, vcc" : "+v"(c) : "s"(cand), "v"(key[jj]) : "vcc");
;       c = wave_sum_i(c, lane);
;       if (c == 256) { T = cand; exact = true; break; }
;       if (c > 256) { lo = cand; break; }
;       hi = cand;
;       if (cand < 0x00800000u) break;
;       cand -= 0x00800000u;
;     }
;   }
.LBB0_638:
	v_cmp_gt_u32_e32 vcc, v231, v230
	v_cmp_lt_u32_e64 s[6:7], v231, v34
	s_and_b64 s[40:41], vcc, s[6:7]
	s_andn2_b64 s[6:7], s[26:27], exec
	s_and_b64 s[26:27], s[38:39], exec
	s_or_b64 s[26:27], s[6:7], s[26:27]
	s_or_b64 s[24:25], s[24:25], exec
	s_and_saveexec_b64 s[6:7], s[40:41]
	s_cbranch_execz .LBB0_637
	v_mov_b32_e32 v38, v1
	v_cmp_le_u32 vcc, v231, v79
	v_addc_co_u32 v38, vcc, 0, v38, vcc
	s_movk_i32 s40, 0x100
	v_cmp_le_u32 vcc, v231, v77
	v_addc_co_u32 v38, vcc, 0, v38, vcc
	s_mov_b64 s[44:45], -1
	v_cmp_le_u32 vcc, v231, v75
	v_addc_co_u32 v38, vcc, 0, v38, vcc
	s_mov_b64 s[42:43], -1
	v_cmp_le_u32 vcc, v231, v73
	v_addc_co_u32 v38, vcc, 0, v38, vcc
	v_cmp_le_u32 vcc, v231, v71
	v_addc_co_u32 v38, vcc, 0, v38, vcc
	v_cmp_le_u32 vcc, v231, v69
	v_addc_co_u32 v38, vcc, 0, v38, vcc
	v_cmp_le_u32 vcc, v231, v67
	v_addc_co_u32 v38, vcc, 0, v38, vcc
	v_cmp_le_u32 vcc, v231, v65
	v_addc_co_u32 v38, vcc, 0, v38, vcc
	v_cmp_le_u32 vcc, v231, v63
	v_addc_co_u32 v38, vcc, 0, v38, vcc
	v_cmp_le_u32 vcc, v231, v61
	v_addc_co_u32 v38, vcc, 0, v38, vcc
	v_cmp_le_u32 vcc, v231, v59
	v_addc_co_u32 v38, vcc, 0, v38, vcc
	v_cmp_le_u32 vcc, v231, v57
	v_addc_co_u32 v38, vcc, 0, v38, vcc
	v_cmp_le_u32 vcc, v231, v55
	v_addc_co_u32 v38, vcc, 0, v38, vcc
	v_cmp_le_u32 vcc, v231, v51
	v_addc_co_u32 v38, vcc, 0, v38, vcc
	v_cmp_le_u32 vcc, v231, v53
	v_addc_co_u32 v38, vcc, 0, v38, vcc
	v_cmp_le_u32 vcc, v231, v49
	v_addc_co_u32 v38, vcc, 0, v38, vcc
	v_cmp_le_u32 vcc, v231, v47
	v_addc_co_u32 v38, vcc, 0, v38, vcc
	v_cmp_le_u32 vcc, v231, v45
	v_addc_co_u32 v38, vcc, 0, v38, vcc
	v_cmp_le_u32 vcc, v231, v43
	v_addc_co_u32 v38, vcc, 0, v38, vcc
	v_cmp_le_u32 vcc, v231, v41
	v_addc_co_u32 v38, vcc, 0, v38, vcc
	v_cmp_le_u32 vcc, v231, v39
	v_addc_co_u32 v38, vcc, 0, v38, vcc
	v_cmp_le_u32 vcc, v231, v37
	v_addc_co_u32 v38, vcc, 0, v38, vcc
	v_cmp_le_u32 vcc, v231, v35
	v_addc_co_u32 v38, vcc, 0, v38, vcc
	v_cmp_le_u32 vcc, v231, v33
	v_addc_co_u32 v38, vcc, 0, v38, vcc
	v_cmp_le_u32 vcc, v231, v31
	v_addc_co_u32 v38, vcc, 0, v38, vcc
	v_cmp_le_u32 vcc, v231, v29
	v_addc_co_u32 v38, vcc, 0, v38, vcc
	v_cmp_le_u32 vcc, v231, v27
	v_addc_co_u32 v38, vcc, 0, v38, vcc
	v_cmp_le_u32 vcc, v231, v25
	v_addc_co_u32 v38, vcc, 0, v38, vcc
	v_cmp_le_u32 vcc, v231, v23
	v_addc_co_u32 v38, vcc, 0, v38, vcc
	v_cmp_le_u32 vcc, v231, v21
	v_addc_co_u32 v38, vcc, 0, v38, vcc
	v_cmp_le_u32 vcc, v231, v19
	v_addc_co_u32 v38, vcc, 0, v38, vcc
	v_cmp_le_u32 vcc, v231, v17
	v_addc_co_u32 v38, vcc, 0, v38, vcc
	v_cmp_le_u32 vcc, v231, v30
	v_addc_co_u32 v38, vcc, 0, v38, vcc
	v_cmp_le_u32 vcc, v231, v28
	v_addc_co_u32 v38, vcc, 0, v38, vcc
	v_cmp_le_u32 vcc, v231, v26
	v_addc_co_u32 v38, vcc, 0, v38, vcc
	v_cmp_le_u32 vcc, v231, v24
	v_addc_co_u32 v38, vcc, 0, v38, vcc
	v_cmp_le_u32 vcc, v231, v22
	v_addc_co_u32 v38, vcc, 0, v38, vcc
	v_cmp_le_u32 vcc, v231, v20
	v_addc_co_u32 v38, vcc, 0, v38, vcc
	v_cmp_le_u32 vcc, v231, v18
	v_addc_co_u32 v38, vcc, 0, v38, vcc
	v_cmp_le_u32 vcc, v231, v16
	v_addc_co_u32 v38, vcc, 0, v38, vcc
	v_cmp_le_u32 vcc, v231, v14
	v_addc_co_u32 v38, vcc, 0, v38, vcc
	v_cmp_le_u32 vcc, v231, v12
	v_addc_co_u32 v38, vcc, 0, v38, vcc
	v_cmp_le_u32 vcc, v231, v10
	v_addc_co_u32 v38, vcc, 0, v38, vcc
	v_cmp_le_u32 vcc, v231, v8
	v_addc_co_u32 v38, vcc, 0, v38, vcc
	v_cmp_le_u32 vcc, v231, v6
	v_addc_co_u32 v38, vcc, 0, v38, vcc
	v_cmp_le_u32 vcc, v231, v4
	v_addc_co_u32 v38, vcc, 0, v38, vcc
	v_cmp_le_u32 vcc, v231, v240
	v_addc_co_u32 v38, vcc, 0, v38, vcc
	v_cmp_le_u32 vcc, v231, v236
	v_addc_co_u32 v38, vcc, 0, v38, vcc
	v_cmp_le_u32 vcc, v231, v211
	v_addc_co_u32 v38, vcc, 0, v38, vcc
	v_cmp_le_u32 vcc, v231, v239
	v_addc_co_u32 v38, vcc, 0, v38, vcc
	v_cmp_le_u32 vcc, v231, v227
	v_addc_co_u32 v38, vcc, 0, v38, vcc
	v_cmp_le_u32 vcc, v231, v253
	v_addc_co_u32 v38, vcc, 0, v38, vcc
	v_cmp_le_u32 vcc, v231, v252
	v_addc_co_u32 v38, vcc, 0, v38, vcc
	v_cmp_le_u32 vcc, v231, v251
	v_addc_co_u32 v38, vcc, 0, v38, vcc
	v_cmp_le_u32 vcc, v231, v250
	v_addc_co_u32 v38, vcc, 0, v38, vcc
	v_cmp_le_u32 vcc, v231, v249
	v_addc_co_u32 v38, vcc, 0, v38, vcc
	v_cmp_le_u32 vcc, v231, v248
	v_addc_co_u32 v38, vcc, 0, v38, vcc
	v_cmp_le_u32 vcc, v231, v247
	v_addc_co_u32 v38, vcc, 0, v38, vcc
	v_cmp_le_u32 vcc, v231, v246
	v_addc_co_u32 v38, vcc, 0, v38, vcc
	v_cmp_le_u32 vcc, v231, v245
	v_addc_co_u32 v38, vcc, 0, v38, vcc
	v_cmp_le_u32 vcc, v231, v244
	v_addc_co_u32 v38, vcc, 0, v38, vcc
	v_cmp_le_u32 vcc, v231, v233
	v_addc_co_u32 v38, vcc, 0, v38, vcc
	v_cmp_le_u32 vcc, v231, v232
	v_addc_co_u32 v38, vcc, 0, v38, vcc
	v_cmp_le_u32 vcc, v231, v0
	v_addc_co_u32 v38, vcc, 0, v38, vcc
	v_cmp_le_u32 vcc, v231, v83
	v_addc_co_u32 v38, vcc, 0, v38, vcc
	v_cmp_le_u32 vcc, v231, v81
	v_addc_co_u32 v38, vcc, 0, v38, vcc
	v_cmp_le_u32 vcc, v231, v87
	v_addc_co_u32 v38, vcc, 0, v38, vcc
	v_cmp_le_u32 vcc, v231, v85
	v_addc_co_u32 v38, vcc, 0, v38, vcc
	v_cmp_le_u32 vcc, v231, v91
	v_addc_co_u32 v38, vcc, 0, v38, vcc
; DI int shflxi(int v, int m, int lane) { return __builtin_amdgcn_ds_bpermute((lane ^ m) << 2, v); }
; DI int wave_sum_i(int v, int lane) {
; #pragma unroll
;   for (int o = 32; o > 0; o >>= 1) v += shflxi(v, o, lane);
;   return v;
; }
; template <int NJ>
; DI void select_row(const float* row, int n, u64* bmrow, int lane) {
;     ...
;     unsigned cand = km & 0xff800000u;
; #pragma unroll 1
;     for (int pr = 0; pr < 4; ++pr) {
;       if (cand <= lo || cand >= hi) break;
;       int c = 0;
; #pragma unroll
;       for (int jj = 0; jj < NJ; ++jj)
;         asm volatile("v_cmp_le_u32 vcc, %1, %2\n\tv_addc_co_u32 %0, vcc, 0, %0, vcc" : "+v"(c) : "s"(cand), "v"(key[jj]) : "vcc");
;       c = wave_sum_i(c, lane);
;       if (c == 256) { T = cand; exact = true; break; }
;       if (c > 256) { lo = cand; break; }
;       hi = cand;
;       if (cand < 0x00800000u) break;
;       cand -= 0x00800000u;
;     }
;   }
	v_cmp_le_u32 vcc, v231, v89
	v_addc_co_u32 v38, vcc, 0, v38, vcc
	v_cmp_le_u32 vcc, v231, v95
	v_addc_co_u32 v38, vcc, 0, v38, vcc
	v_cmp_le_u32 vcc, v231, v93
	v_addc_co_u32 v38, vcc, 0, v38, vcc
	v_cmp_le_u32 vcc, v231, v99
	v_addc_co_u32 v38, vcc, 0, v38, vcc
	v_cmp_le_u32 vcc, v231, v97
	v_addc_co_u32 v38, vcc, 0, v38, vcc
	v_cmp_le_u32 vcc, v231, v103
	v_addc_co_u32 v38, vcc, 0, v38, vcc
	v_cmp_le_u32 vcc, v231, v101
	v_addc_co_u32 v38, vcc, 0, v38, vcc
	v_cmp_le_u32 vcc, v231, v107
	v_addc_co_u32 v38, vcc, 0, v38, vcc
	v_cmp_le_u32 vcc, v231, v105
	v_addc_co_u32 v38, vcc, 0, v38, vcc
	v_cmp_le_u32 vcc, v231, v111
	v_addc_co_u32 v38, vcc, 0, v38, vcc
	v_cmp_le_u32 vcc, v231, v109
	v_addc_co_u32 v38, vcc, 0, v38, vcc
	v_cmp_le_u32 vcc, v231, v115
	v_addc_co_u32 v38, vcc, 0, v38, vcc
	v_cmp_le_u32 vcc, v231, v113
	v_addc_co_u32 v38, vcc, 0, v38, vcc
	v_cmp_le_u32 vcc, v231, v119
	v_addc_co_u32 v38, vcc, 0, v38, vcc
	v_cmp_le_u32 vcc, v231, v117
	v_addc_co_u32 v38, vcc, 0, v38, vcc
	v_cmp_le_u32 vcc, v231, v123
	v_addc_co_u32 v38, vcc, 0, v38, vcc
	v_cmp_le_u32 vcc, v231, v121
	v_addc_co_u32 v38, vcc, 0, v38, vcc
	v_cmp_le_u32 vcc, v231, v127
	v_addc_co_u32 v38, vcc, 0, v38, vcc
	v_cmp_le_u32 vcc, v231, v125
	v_addc_co_u32 v38, vcc, 0, v38, vcc
	v_cmp_le_u32 vcc, v231, v131
	v_addc_co_u32 v38, vcc, 0, v38, vcc
	v_cmp_le_u32 vcc, v231, v129
	v_addc_co_u32 v38, vcc, 0, v38, vcc
	v_cmp_le_u32 vcc, v231, v135
	v_addc_co_u32 v38, vcc, 0, v38, vcc
	v_cmp_le_u32 vcc, v231, v133
	v_addc_co_u32 v38, vcc, 0, v38, vcc
	v_cmp_le_u32 vcc, v231, v139
	v_addc_co_u32 v38, vcc, 0, v38, vcc
	v_cmp_le_u32 vcc, v231, v137
	v_addc_co_u32 v38, vcc, 0, v38, vcc
	v_cmp_le_u32 vcc, v231, v143
	v_addc_co_u32 v38, vcc, 0, v38, vcc
	v_cmp_le_u32 vcc, v231, v141
	v_addc_co_u32 v38, vcc, 0, v38, vcc
	v_cmp_le_u32 vcc, v231, v147
	v_addc_co_u32 v38, vcc, 0, v38, vcc
	v_cmp_le_u32 vcc, v231, v145
	v_addc_co_u32 v38, vcc, 0, v38, vcc
	v_cmp_le_u32 vcc, v231, v151
	v_addc_co_u32 v38, vcc, 0, v38, vcc
	v_cmp_le_u32 vcc, v231, v149
	v_addc_co_u32 v38, vcc, 0, v38, vcc
	v_cmp_le_u32 vcc, v231, v155
	v_addc_co_u32 v38, vcc, 0, v38, vcc
	v_cmp_le_u32 vcc, v231, v153
	v_addc_co_u32 v38, vcc, 0, v38, vcc
	v_cmp_le_u32 vcc, v231, v159
	v_addc_co_u32 v38, vcc, 0, v38, vcc
	v_cmp_le_u32 vcc, v231, v157
	v_addc_co_u32 v38, vcc, 0, v38, vcc
	v_cmp_le_u32 vcc, v231, v163
	v_addc_co_u32 v38, vcc, 0, v38, vcc
	v_cmp_le_u32 vcc, v231, v161
	v_addc_co_u32 v38, vcc, 0, v38, vcc
	v_cmp_le_u32 vcc, v231, v167
	v_addc_co_u32 v38, vcc, 0, v38, vcc
	v_cmp_le_u32 vcc, v231, v165
	v_addc_co_u32 v38, vcc, 0, v38, vcc
	v_cmp_le_u32 vcc, v231, v171
	v_addc_co_u32 v38, vcc, 0, v38, vcc
	v_cmp_le_u32 vcc, v231, v169
	v_addc_co_u32 v38, vcc, 0, v38, vcc
	v_cmp_le_u32 vcc, v231, v175
	v_addc_co_u32 v38, vcc, 0, v38, vcc
	v_cmp_le_u32 vcc, v231, v173
	v_addc_co_u32 v38, vcc, 0, v38, vcc
	v_cmp_le_u32 vcc, v231, v179
	v_addc_co_u32 v38, vcc, 0, v38, vcc
	v_cmp_le_u32 vcc, v231, v177
	v_addc_co_u32 v38, vcc, 0, v38, vcc
	v_cmp_le_u32 vcc, v231, v183
	v_addc_co_u32 v38, vcc, 0, v38, vcc
	v_cmp_le_u32 vcc, v231, v181
	v_addc_co_u32 v38, vcc, 0, v38, vcc
	v_cmp_le_u32 vcc, v231, v187
	v_addc_co_u32 v38, vcc, 0, v38, vcc
	v_cmp_le_u32 vcc, v231, v185
	v_addc_co_u32 v38, vcc, 0, v38, vcc
	v_cmp_le_u32 vcc, v231, v191
	v_addc_co_u32 v38, vcc, 0, v38, vcc
	v_cmp_le_u32 vcc, v231, v189
	v_addc_co_u32 v38, vcc, 0, v38, vcc
	v_cmp_le_u32 vcc, v231, v195
	v_addc_co_u32 v38, vcc, 0, v38, vcc
	v_cmp_le_u32 vcc, v231, v193
	v_addc_co_u32 v38, vcc, 0, v38, vcc
	v_cmp_le_u32 vcc, v231, v199
	v_addc_co_u32 v38, vcc, 0, v38, vcc
	v_cmp_le_u32 vcc, v231, v197
	v_addc_co_u32 v38, vcc, 0, v38, vcc
	v_cmp_le_u32 vcc, v231, v235
	v_addc_co_u32 v38, vcc, 0, v38, vcc
	v_cmp_le_u32 vcc, v231, v234
	v_addc_co_u32 v38, vcc, 0, v38, vcc
	v_cmp_le_u32 vcc, v231, v243
	v_addc_co_u32 v38, vcc, 0, v38, vcc
	v_cmp_le_u32 vcc, v231, v242
	v_addc_co_u32 v38, vcc, 0, v38, vcc
	s_nop 1
	v_add_u32_dpp v38, v38, v38 row_shr:1 row_mask:0xf bank_mask:0xf bound_ctrl:0
	s_nop 1
	v_add_u32_dpp v38, v38, v38 row_shr:2 row_mask:0xf bank_mask:0xf bound_ctrl:0
	s_nop 1
	v_add_u32_dpp v38, v38, v38 row_shr:4 row_mask:0xf bank_mask:0xf bound_ctrl:0
	s_nop 1
	v_add_u32_dpp v38, v38, v38 row_shr:8 row_mask:0xf bank_mask:0xf bound_ctrl:0
	s_nop 1
	v_add_u32_dpp v38, v38, v38 row_bcast:15 row_mask:0xa bank_mask:0xf
	s_nop 1
	v_add_u32_dpp v38, v38, v38 row_bcast:31 row_mask:0xc bank_mask:0xf
	s_nop 1
	v_readlane_b32 s98, v38, 63
	s_nop 1
	v_mov_b32_e32 v40, s98
	v_mov_b32_e32 v38, s98
	v_cmp_ne_u32_e32 vcc, s40, v40
	v_mov_b32_e32 v38, v231
	s_and_saveexec_b64 s[40:41], vcc
	s_cbranch_execz .LBB0_636
	s_movk_i32 s42, 0x101
	v_cmp_gt_i32_e32 vcc, s42, v40
	v_mov_b32_e32 v38, v231
	s_and_saveexec_b64 s[42:43], vcc
	s_cbranch_execz .LBB0_635
	v_subrev_co_u32_e32 v34, vcc, 0x800000, v231
	s_orn2_b64 s[44:45], vcc, exec
	s_nop 0
	v_cndmask_b32_e32 v38, v34, v231, vcc
	v_mov_b32_e32 v34, v231
	v_mov_b32_e32 v231, v230
	s_branch .LBB0_635

; template <int NJ>
; DI void select_row(const float* row, int n, u64* bmrow, int lane) {
;     ...
; #pragma unroll 1
;   while (!exact && hi - lo > 1u) {
;     const unsigned cand = lo + ((hi - lo) >> 1);
;     int c = 0;
; #pragma unroll
;     for (int jj = 0; jj < NJ; ++jj)
;       asm volatile("v_cmp_le_u32 vcc, %1, %2\n\tv_addc_co_u32 %0, vcc, 0, %0, vcc" : "+v"(c) : "s"(cand), "v"(key[jj]) : "vcc");
;     c = wave_sum_i(c, lane);
;     if (c == 256) { T = cand; exact = true; }
;     else if (c > 256) lo = cand; else hi = cand;
;   }
.LBB0_644:
	v_lshrrev_b32_e32 v36, 1, v36
	v_mov_b32_e32 v38, v1
	v_add_u32_e32 v36, v230, v36
	v_cmp_le_u32 vcc, v36, v79
	v_addc_co_u32 v38, vcc, 0, v38, vcc
	v_cmp_le_u32 vcc, v36, v77
	v_addc_co_u32 v38, vcc, 0, v38, vcc
	v_cmp_le_u32 vcc, v36, v75
	v_addc_co_u32 v38, vcc, 0, v38, vcc
	v_cmp_le_u32 vcc, v36, v73
	v_addc_co_u32 v38, vcc, 0, v38, vcc
	v_cmp_le_u32 vcc, v36, v71
	v_addc_co_u32 v38, vcc, 0, v38, vcc
	v_cmp_le_u32 vcc, v36, v69
	v_addc_co_u32 v38, vcc, 0, v38, vcc
	v_cmp_le_u32 vcc, v36, v67
	v_addc_co_u32 v38, vcc, 0, v38, vcc
	v_cmp_le_u32 vcc, v36, v65
	v_addc_co_u32 v38, vcc, 0, v38, vcc
	v_cmp_le_u32 vcc, v36, v63
	v_addc_co_u32 v38, vcc, 0, v38, vcc
	v_cmp_le_u32 vcc, v36, v61
	v_addc_co_u32 v38, vcc, 0, v38, vcc
	v_cmp_le_u32 vcc, v36, v59
	v_addc_co_u32 v38, vcc, 0, v38, vcc
	v_cmp_le_u32 vcc, v36, v57
	v_addc_co_u32 v38, vcc, 0, v38, vcc
	v_cmp_le_u32 vcc, v36, v55
	v_addc_co_u32 v38, vcc, 0, v38, vcc
	v_cmp_le_u32 vcc, v36, v51
	v_addc_co_u32 v38, vcc, 0, v38, vcc
	v_cmp_le_u32 vcc, v36, v53
	v_addc_co_u32 v38, vcc, 0, v38, vcc
	v_cmp_le_u32 vcc, v36, v49
	v_addc_co_u32 v38, vcc, 0, v38, vcc
	v_cmp_le_u32 vcc, v36, v47
	v_addc_co_u32 v38, vcc, 0, v38, vcc
	v_cmp_le_u32 vcc, v36, v45
	v_addc_co_u32 v38, vcc, 0, v38, vcc
	v_cmp_le_u32 vcc, v36, v43
	v_addc_co_u32 v38, vcc, 0, v38, vcc
	v_cmp_le_u32 vcc, v36, v41
	v_addc_co_u32 v38, vcc, 0, v38, vcc
	v_cmp_le_u32 vcc, v36, v39
	v_addc_co_u32 v38, vcc, 0, v38, vcc
	v_cmp_le_u32 vcc, v36, v37
	v_addc_co_u32 v38, vcc, 0, v38, vcc
	v_cmp_le_u32 vcc, v36, v35
	v_addc_co_u32 v38, vcc, 0, v38, vcc
	v_cmp_le_u32 vcc, v36, v33
	v_addc_co_u32 v38, vcc, 0, v38, vcc
	v_cmp_le_u32 vcc, v36, v31
	v_addc_co_u32 v38, vcc, 0, v38, vcc
	v_cmp_le_u32 vcc, v36, v29
	v_addc_co_u32 v38, vcc, 0, v38, vcc
	v_cmp_le_u32 vcc, v36, v27
	v_addc_co_u32 v38, vcc, 0, v38, vcc
	v_cmp_le_u32 vcc, v36, v25
	v_addc_co_u32 v38, vcc, 0, v38, vcc
	v_cmp_le_u32 vcc, v36, v23
	v_addc_co_u32 v38, vcc, 0, v38, vcc
	v_cmp_le_u32 vcc, v36, v21
	v_addc_co_u32 v38, vcc, 0, v38, vcc
	v_cmp_le_u32 vcc, v36, v19
	v_addc_co_u32 v38, vcc, 0, v38, vcc
	v_cmp_le_u32 vcc, v36, v17
	v_addc_co_u32 v38, vcc, 0, v38, vcc
	v_cmp_le_u32 vcc, v36, v30
	v_addc_co_u32 v38, vcc, 0, v38, vcc
	v_cmp_le_u32 vcc, v36, v28
	v_addc_co_u32 v38, vcc, 0, v38, vcc
	v_cmp_le_u32 vcc, v36, v26
	v_addc_co_u32 v38, vcc, 0, v38, vcc
	v_cmp_le_u32 vcc, v36, v24
	v_addc_co_u32 v38, vcc, 0, v38, vcc
	v_cmp_le_u32 vcc, v36, v22
	v_addc_co_u32 v38, vcc, 0, v38, vcc
	v_cmp_le_u32 vcc, v36, v20
	v_addc_co_u32 v38, vcc, 0, v38, vcc
	v_cmp_le_u32 vcc, v36, v18
	v_addc_co_u32 v38, vcc, 0, v38, vcc
	v_cmp_le_u32 vcc, v36, v16
	v_addc_co_u32 v38, vcc, 0, v38, vcc
	v_cmp_le_u32 vcc, v36, v14
	v_addc_co_u32 v38, vcc, 0, v38, vcc
	v_cmp_le_u32 vcc, v36, v12
	v_addc_co_u32 v38, vcc, 0, v38, vcc
	v_cmp_le_u32 vcc, v36, v10
	v_addc_co_u32 v38, vcc, 0, v38, vcc
	v_cmp_le_u32 vcc, v36, v8
	v_addc_co_u32 v38, vcc, 0, v38, vcc
	v_cmp_le_u32 vcc, v36, v6
	v_addc_co_u32 v38, vcc, 0, v38, vcc
	v_cmp_le_u32 vcc, v36, v4
	v_addc_co_u32 v38, vcc, 0, v38, vcc
	v_cmp_le_u32 vcc, v36, v240
	v_addc_co_u32 v38, vcc, 0, v38, vcc
	v_cmp_le_u32 vcc, v36, v236
	v_addc_co_u32 v38, vcc, 0, v38, vcc
	v_cmp_le_u32 vcc, v36, v211
	v_addc_co_u32 v38, vcc, 0, v38, vcc
	v_cmp_le_u32 vcc, v36, v239
	v_addc_co_u32 v38, vcc, 0, v38, vcc
	v_cmp_le_u32 vcc, v36, v227
	v_addc_co_u32 v38, vcc, 0, v38, vcc
	v_cmp_le_u32 vcc, v36, v253
	v_addc_co_u32 v38, vcc, 0, v38, vcc
	v_cmp_le_u32 vcc, v36, v252
	v_addc_co_u32 v38, vcc, 0, v38, vcc
	v_cmp_le_u32 vcc, v36, v251
	v_addc_co_u32 v38, vcc, 0, v38, vcc
	v_cmp_le_u32 vcc, v36, v250
	v_addc_co_u32 v38, vcc, 0, v38, vcc
	v_cmp_le_u32 vcc, v36, v249
	v_addc_co_u32 v38, vcc, 0, v38, vcc
	v_cmp_le_u32 vcc, v36, v248
	v_addc_co_u32 v38, vcc, 0, v38, vcc
	v_cmp_le_u32 vcc, v36, v247
	v_addc_co_u32 v38, vcc, 0, v38, vcc
	v_cmp_le_u32 vcc, v36, v246
	v_addc_co_u32 v38, vcc, 0, v38, vcc
	v_cmp_le_u32 vcc, v36, v245
	v_addc_co_u32 v38, vcc, 0, v38, vcc
	v_cmp_le_u32 vcc, v36, v244
	v_addc_co_u32 v38, vcc, 0, v38, vcc
	v_cmp_le_u32 vcc, v36, v233
	v_addc_co_u32 v38, vcc, 0, v38, vcc
	v_cmp_le_u32 vcc, v36, v232
	v_addc_co_u32 v38, vcc, 0, v38, vcc
	v_cmp_le_u32 vcc, v36, v0
	v_addc_co_u32 v38, vcc, 0, v38, vcc
	v_cmp_le_u32 vcc, v36, v83
	v_addc_co_u32 v38, vcc, 0, v38, vcc
	v_cmp_le_u32 vcc, v36, v81
	v_addc_co_u32 v38, vcc, 0, v38, vcc
	v_cmp_le_u32 vcc, v36, v87
	v_addc_co_u32 v38, vcc, 0, v38, vcc
	v_cmp_le_u32 vcc, v36, v85
	v_addc_co_u32 v38, vcc, 0, v38, vcc
	v_cmp_le_u32 vcc, v36, v91
	v_addc_co_u32 v38, vcc, 0, v38, vcc
	v_cmp_le_u32 vcc, v36, v89
	v_addc_co_u32 v38, vcc, 0, v38, vcc
	v_cmp_le_u32 vcc, v36, v95
	v_addc_co_u32 v38, vcc, 0, v38, vcc
	v_cmp_le_u32 vcc, v36, v93
	v_addc_co_u32 v38, vcc, 0, v38, vcc
	v_cmp_le_u32 vcc, v36, v99
	v_addc_co_u32 v38, vcc, 0, v38, vcc
	v_cmp_le_u32 vcc, v36, v97
	v_addc_co_u32 v38, vcc, 0, v38, vcc
	v_cmp_le_u32 vcc, v36, v103
	v_addc_co_u32 v38, vcc, 0, v38, vcc
	v_cmp_le_u32 vcc, v36, v101
	v_addc_co_u32 v38, vcc, 0, v38, vcc
	v_cmp_le_u32 vcc, v36, v107
	v_addc_co_u32 v38, vcc, 0, v38, vcc
	v_cmp_le_u32 vcc, v36, v105
	v_addc_co_u32 v38, vcc, 0, v38, vcc
	v_cmp_le_u32 vcc, v36, v111
	v_addc_co_u32 v38, vcc, 0, v38, vcc
	v_cmp_le_u32 vcc, v36, v109
	v_addc_co_u32 v38, vcc, 0, v38, vcc
	v_cmp_le_u32 vcc, v36, v115
	v_addc_co_u32 v38, vcc, 0, v38, vcc
	v_cmp_le_u32 vcc, v36, v113
	v_addc_co_u32 v38, vcc, 0, v38, vcc
	v_cmp_le_u32 vcc, v36, v119
	v_addc_co_u32 v38, vcc, 0, v38, vcc
	v_cmp_le_u32 vcc, v36, v117
	v_addc_co_u32 v38, vcc, 0, v38, vcc
	v_cmp_le_u32 vcc, v36, v123
	v_addc_co_u32 v38, vcc, 0, v38, vcc
; DI int shflxi(int v, int m, int lane) { return __builtin_amdgcn_ds_bpermute((lane ^ m) << 2, v); }
; DI int wave_sum_i(int v, int lane) {
; #pragma unroll
;   for (int o = 32; o > 0; o >>= 1) v += shflxi(v, o, lane);
;   return v;
; }
; template <int NJ>
; DI void select_row(const float* row, int n, u64* bmrow, int lane) {
;     ...
; #pragma unroll 1
;   while (!exact && hi - lo > 1u) {
;     const unsigned cand = lo + ((hi - lo) >> 1);
;     int c = 0;
; #pragma unroll
;     for (int jj = 0; jj < NJ; ++jj)
;       asm volatile("v_cmp_le_u32 vcc, %1, %2\n\tv_addc_co_u32 %0, vcc, 0, %0, vcc" : "+v"(c) : "s"(cand), "v"(key[jj]) : "vcc");
;     c = wave_sum_i(c, lane);
;     if (c == 256) { T = cand; exact = true; }
;     else if (c > 256) lo = cand; else hi = cand;
;   }
	v_cmp_le_u32 vcc, v36, v121
	v_addc_co_u32 v38, vcc, 0, v38, vcc
	v_cmp_le_u32 vcc, v36, v127
	v_addc_co_u32 v38, vcc, 0, v38, vcc
	v_cmp_le_u32 vcc, v36, v125
	v_addc_co_u32 v38, vcc, 0, v38, vcc
	v_cmp_le_u32 vcc, v36, v131
	v_addc_co_u32 v38, vcc, 0, v38, vcc
	v_cmp_le_u32 vcc, v36, v129
	v_addc_co_u32 v38, vcc, 0, v38, vcc
	v_cmp_le_u32 vcc, v36, v135
	v_addc_co_u32 v38, vcc, 0, v38, vcc
	v_cmp_le_u32 vcc, v36, v133
	v_addc_co_u32 v38, vcc, 0, v38, vcc
	v_cmp_le_u32 vcc, v36, v139
	v_addc_co_u32 v38, vcc, 0, v38, vcc
	v_cmp_le_u32 vcc, v36, v137
	v_addc_co_u32 v38, vcc, 0, v38, vcc
	v_cmp_le_u32 vcc, v36, v143
	v_addc_co_u32 v38, vcc, 0, v38, vcc
	v_cmp_le_u32 vcc, v36, v141
	v_addc_co_u32 v38, vcc, 0, v38, vcc
	v_cmp_le_u32 vcc, v36, v147
	v_addc_co_u32 v38, vcc, 0, v38, vcc
	v_cmp_le_u32 vcc, v36, v145
	v_addc_co_u32 v38, vcc, 0, v38, vcc
	v_cmp_le_u32 vcc, v36, v151
	v_addc_co_u32 v38, vcc, 0, v38, vcc
	v_cmp_le_u32 vcc, v36, v149
	v_addc_co_u32 v38, vcc, 0, v38, vcc
	v_cmp_le_u32 vcc, v36, v155
	v_addc_co_u32 v38, vcc, 0, v38, vcc
	v_cmp_le_u32 vcc, v36, v153
	v_addc_co_u32 v38, vcc, 0, v38, vcc
	v_cmp_le_u32 vcc, v36, v159
	v_addc_co_u32 v38, vcc, 0, v38, vcc
	v_cmp_le_u32 vcc, v36, v157
	v_addc_co_u32 v38, vcc, 0, v38, vcc
	v_cmp_le_u32 vcc, v36, v163
	v_addc_co_u32 v38, vcc, 0, v38, vcc
	v_cmp_le_u32 vcc, v36, v161
	v_addc_co_u32 v38, vcc, 0, v38, vcc
	v_cmp_le_u32 vcc, v36, v167
	v_addc_co_u32 v38, vcc, 0, v38, vcc
	v_cmp_le_u32 vcc, v36, v165
	v_addc_co_u32 v38, vcc, 0, v38, vcc
	v_cmp_le_u32 vcc, v36, v171
	v_addc_co_u32 v38, vcc, 0, v38, vcc
	v_cmp_le_u32 vcc, v36, v169
	v_addc_co_u32 v38, vcc, 0, v38, vcc
	v_cmp_le_u32 vcc, v36, v175
	v_addc_co_u32 v38, vcc, 0, v38, vcc
	v_cmp_le_u32 vcc, v36, v173
	v_addc_co_u32 v38, vcc, 0, v38, vcc
	v_cmp_le_u32 vcc, v36, v179
	v_addc_co_u32 v38, vcc, 0, v38, vcc
	v_cmp_le_u32 vcc, v36, v177
	v_addc_co_u32 v38, vcc, 0, v38, vcc
	v_cmp_le_u32 vcc, v36, v183
	v_addc_co_u32 v38, vcc, 0, v38, vcc
	v_cmp_le_u32 vcc, v36, v181
	v_addc_co_u32 v38, vcc, 0, v38, vcc
	v_cmp_le_u32 vcc, v36, v187
	v_addc_co_u32 v38, vcc, 0, v38, vcc
	v_cmp_le_u32 vcc, v36, v185
	v_addc_co_u32 v38, vcc, 0, v38, vcc
	v_cmp_le_u32 vcc, v36, v191
	v_addc_co_u32 v38, vcc, 0, v38, vcc
	v_cmp_le_u32 vcc, v36, v189
	v_addc_co_u32 v38, vcc, 0, v38, vcc
	v_cmp_le_u32 vcc, v36, v195
	v_addc_co_u32 v38, vcc, 0, v38, vcc
	v_cmp_le_u32 vcc, v36, v193
	v_addc_co_u32 v38, vcc, 0, v38, vcc
	v_cmp_le_u32 vcc, v36, v199
	v_addc_co_u32 v38, vcc, 0, v38, vcc
	v_cmp_le_u32 vcc, v36, v197
	v_addc_co_u32 v38, vcc, 0, v38, vcc
	v_cmp_le_u32 vcc, v36, v235
	v_addc_co_u32 v38, vcc, 0, v38, vcc
	v_cmp_le_u32 vcc, v36, v234
	v_addc_co_u32 v38, vcc, 0, v38, vcc
	v_cmp_le_u32 vcc, v36, v243
	v_addc_co_u32 v38, vcc, 0, v38, vcc
	v_cmp_le_u32 vcc, v36, v242
	v_addc_co_u32 v38, vcc, 0, v38, vcc
	s_nop 1
	v_add_u32_dpp v38, v38, v38 row_shr:1 row_mask:0xf bank_mask:0xf bound_ctrl:0
	s_nop 1
	v_add_u32_dpp v38, v38, v38 row_shr:2 row_mask:0xf bank_mask:0xf bound_ctrl:0
	s_nop 1
	v_add_u32_dpp v38, v38, v38 row_shr:4 row_mask:0xf bank_mask:0xf bound_ctrl:0
	s_nop 1
	v_add_u32_dpp v38, v38, v38 row_shr:8 row_mask:0xf bank_mask:0xf bound_ctrl:0
	s_nop 1
	v_add_u32_dpp v38, v38, v38 row_bcast:15 row_mask:0xa bank_mask:0xf
	s_nop 1
	v_add_u32_dpp v38, v38, v38 row_bcast:31 row_mask:0xc bank_mask:0xf
	s_nop 1
	v_readlane_b32 s98, v38, 63
	s_nop 1
	v_mov_b32_e32 v38, s98
	v_cmp_lt_i32_e32 vcc, s38, v38
	s_nop 1
	v_cndmask_b32_e32 v40, v230, v36, vcc
	v_cmp_lt_i32_e32 vcc, s39, v38
	s_nop 1
	v_cndmask_b32_e32 v34, v36, v34, vcc
	v_cmp_eq_u32_e32 vcc, s38, v38
	s_nop 1
	v_cndmask_b32_e32 v230, v40, v230, vcc
	v_cndmask_b32_e32 v32, v32, v36, vcc
	v_sub_u32_e32 v36, v34, v230
	v_cmp_gt_u32_e64 s[6:7], 2, v36
	s_or_b64 s[6:7], vcc, s[6:7]
	s_and_b64 s[6:7], exec, s[6:7]
	s_or_b64 s[24:25], s[6:7], s[24:25]
	s_andn2_b64 s[6:7], s[26:27], exec
	s_and_b64 s[26:27], vcc, exec
	s_or_b64 s[26:27], s[6:7], s[26:27]
	s_andn2_b64 exec, exec, s[24:25]
	s_cbranch_execnz .LBB0_644
	s_or_b64 exec, exec, s[24:25]
	s_andn2_b64 s[6:7], s[20:21], exec
	s_and_b64 s[20:21], s[26:27], exec
	s_or_b64 s[20:21], s[6:7], s[20:21]
.LBB0_646:
	s_or_b64 exec, exec, s[22:23]
	s_xor_b64 s[20:21], s[20:21], -1
	v_mov_b32_e32 v34, -1
	s_and_saveexec_b64 s[6:7], s[20:21]
	s_cbranch_execz .LBB0_651
; template <int NJ>
; DI void select_row(const float* row, int n, u64* bmrow, int lane) {
;     ...
;   if (!exact) {
;     int cgt = 0, ceq = 0;
; #pragma unroll
;     for (int jj = 0; jj < NJ; ++jj) {
;       asm volatile("v_cmp_lt_u32 vcc, %1, %2\n\tv_addc_co_u32 %0, vcc, 0, %0, vcc" : "+v"(cgt) : "s"(T), "v"(key[jj]) : "vcc");
;       asm volatile("v_cmp_eq_u32 vcc, %1, %2\n\tv_addc_co_u32 %0, vcc, 0, %0, vcc" : "+v"(ceq) : "s"(T), "v"(key[jj]) : "vcc");
;     }
;     cgt = wave_sum_i(cgt, lane); ceq = wave_sum_i(ceq, lane);
	v_mov_b32_e32 v32, v1
	v_cmp_lt_u32 vcc, v230, v79
	v_addc_co_u32 v32, vcc, 0, v32, vcc
	v_mov_b32_e32 v34, v1
	v_cmp_eq_u32 vcc, v230, v79
	v_addc_co_u32 v34, vcc, 0, v34, vcc
	v_cmp_lt_u32 vcc, v230, v77
	v_addc_co_u32 v32, vcc, 0, v32, vcc
	v_cmp_eq_u32 vcc, v230, v77
	v_addc_co_u32 v34, vcc, 0, v34, vcc
	v_cmp_lt_u32 vcc, v230, v75
	v_addc_co_u32 v32, vcc, 0, v32, vcc
	v_cmp_eq_u32 vcc, v230, v75
	v_addc_co_u32 v34, vcc, 0, v34, vcc
	v_cmp_lt_u32 vcc, v230, v73
	v_addc_co_u32 v32, vcc, 0, v32, vcc
	v_cmp_eq_u32 vcc, v230, v73
	v_addc_co_u32 v34, vcc, 0, v34, vcc
	v_cmp_lt_u32 vcc, v230, v71
	v_addc_co_u32 v32, vcc, 0, v32, vcc
	v_cmp_eq_u32 vcc, v230, v71
	v_addc_co_u32 v34, vcc, 0, v34, vcc
	v_cmp_lt_u32 vcc, v230, v69
	v_addc_co_u32 v32, vcc, 0, v32, vcc
	v_cmp_eq_u32 vcc, v230, v69
	v_addc_co_u32 v34, vcc, 0, v34, vcc
	v_cmp_lt_u32 vcc, v230, v67
	v_addc_co_u32 v32, vcc, 0, v32, vcc
	v_cmp_eq_u32 vcc, v230, v67
	v_addc_co_u32 v34, vcc, 0, v34, vcc
	v_cmp_lt_u32 vcc, v230, v65
	v_addc_co_u32 v32, vcc, 0, v32, vcc
	v_cmp_eq_u32 vcc, v230, v65
	v_addc_co_u32 v34, vcc, 0, v34, vcc
	v_cmp_lt_u32 vcc, v230, v63
	v_addc_co_u32 v32, vcc, 0, v32, vcc
	v_cmp_eq_u32 vcc, v230, v63
	v_addc_co_u32 v34, vcc, 0, v34, vcc
	v_cmp_lt_u32 vcc, v230, v61
	v_addc_co_u32 v32, vcc, 0, v32, vcc
	v_cmp_eq_u32 vcc, v230, v61
	v_addc_co_u32 v34, vcc, 0, v34, vcc
	v_cmp_lt_u32 vcc, v230, v59
	v_addc_co_u32 v32, vcc, 0, v32, vcc
	v_cmp_eq_u32 vcc, v230, v59
	v_addc_co_u32 v34, vcc, 0, v34, vcc
	v_cmp_lt_u32 vcc, v230, v57
	v_addc_co_u32 v32, vcc, 0, v32, vcc
	v_cmp_eq_u32 vcc, v230, v57
	v_addc_co_u32 v34, vcc, 0, v34, vcc
	v_cmp_lt_u32 vcc, v230, v55
	v_addc_co_u32 v32, vcc, 0, v32, vcc
	v_cmp_eq_u32 vcc, v230, v55
	v_addc_co_u32 v34, vcc, 0, v34, vcc
	v_cmp_lt_u32 vcc, v230, v51
	v_addc_co_u32 v32, vcc, 0, v32, vcc
	v_cmp_eq_u32 vcc, v230, v51
	v_addc_co_u32 v34, vcc, 0, v34, vcc
	v_cmp_lt_u32 vcc, v230, v53
	v_addc_co_u32 v32, vcc, 0, v32, vcc
	v_cmp_eq_u32 vcc, v230, v53
	v_addc_co_u32 v34, vcc, 0, v34, vcc
	v_cmp_lt_u32 vcc, v230, v49
	v_addc_co_u32 v32, vcc, 0, v32, vcc
	v_cmp_eq_u32 vcc, v230, v49
	v_addc_co_u32 v34, vcc, 0, v34, vcc
	v_cmp_lt_u32 vcc, v230, v47
	v_addc_co_u32 v32, vcc, 0, v32, vcc
	v_cmp_eq_u32 vcc, v230, v47
	v_addc_co_u32 v34, vcc, 0, v34, vcc
	v_cmp_lt_u32 vcc, v230, v45
	v_addc_co_u32 v32, vcc, 0, v32, vcc
	v_cmp_eq_u32 vcc, v230, v45
	v_addc_co_u32 v34, vcc, 0, v34, vcc
	v_cmp_lt_u32 vcc, v230, v43
	v_addc_co_u32 v32, vcc, 0, v32, vcc
	v_cmp_eq_u32 vcc, v230, v43
	v_addc_co_u32 v34, vcc, 0, v34, vcc
	v_cmp_lt_u32 vcc, v230, v41
	v_addc_co_u32 v32, vcc, 0, v32, vcc
	v_cmp_eq_u32 vcc, v230, v41
	v_addc_co_u32 v34, vcc, 0, v34, vcc
	v_cmp_lt_u32 vcc, v230, v39
	v_addc_co_u32 v32, vcc, 0, v32, vcc
	v_cmp_eq_u32 vcc, v230, v39
	v_addc_co_u32 v34, vcc, 0, v34, vcc
	v_cmp_lt_u32 vcc, v230, v37
	v_addc_co_u32 v32, vcc, 0, v32, vcc
	v_cmp_eq_u32 vcc, v230, v37
	v_addc_co_u32 v34, vcc, 0, v34, vcc
	v_cmp_lt_u32 vcc, v230, v35
	v_addc_co_u32 v32, vcc, 0, v32, vcc
	v_cmp_eq_u32 vcc, v230, v35
	v_addc_co_u32 v34, vcc, 0, v34, vcc
	v_cmp_lt_u32 vcc, v230, v33
	v_addc_co_u32 v32, vcc, 0, v32, vcc
	v_cmp_eq_u32 vcc, v230, v33
	v_addc_co_u32 v34, vcc, 0, v34, vcc
	v_cmp_lt_u32 vcc, v230, v31
	v_addc_co_u32 v32, vcc, 0, v32, vcc
	v_cmp_eq_u32 vcc, v230, v31
	v_addc_co_u32 v34, vcc, 0, v34, vcc
	v_cmp_lt_u32 vcc, v230, v29
	v_addc_co_u32 v32, vcc, 0, v32, vcc
	v_cmp_eq_u32 vcc, v230, v29
	v_addc_co_u32 v34, vcc, 0, v34, vcc
	v_cmp_lt_u32 vcc, v230, v27
	v_addc_co_u32 v32, vcc, 0, v32, vcc
	v_cmp_eq_u32 vcc, v230, v27
	v_addc_co_u32 v34, vcc, 0, v34, vcc
	v_cmp_lt_u32 vcc, v230, v25
	v_addc_co_u32 v32, vcc, 0, v32, vcc
	v_cmp_eq_u32 vcc, v230, v25
	v_addc_co_u32 v34, vcc, 0, v34, vcc
	v_cmp_lt_u32 vcc, v230, v23
	v_addc_co_u32 v32, vcc, 0, v32, vcc
	v_cmp_eq_u32 vcc, v230, v23
	v_addc_co_u32 v34, vcc, 0, v34, vcc
	v_cmp_lt_u32 vcc, v230, v21
	v_addc_co_u32 v32, vcc, 0, v32, vcc
	v_cmp_eq_u32 vcc, v230, v21
	v_addc_co_u32 v34, vcc, 0, v34, vcc
	v_cmp_lt_u32 vcc, v230, v19
	v_addc_co_u32 v32, vcc, 0, v32, vcc
	v_cmp_eq_u32 vcc, v230, v19
	v_addc_co_u32 v34, vcc, 0, v34, vcc
	v_cmp_lt_u32 vcc, v230, v17
	v_addc_co_u32 v32, vcc, 0, v32, vcc
	v_cmp_eq_u32 vcc, v230, v17
	v_addc_co_u32 v34, vcc, 0, v34, vcc
	v_cmp_lt_u32 vcc, v230, v30
	v_addc_co_u32 v32, vcc, 0, v32, vcc
	v_cmp_eq_u32 vcc, v230, v30
	v_addc_co_u32 v34, vcc, 0, v34, vcc
	v_cmp_lt_u32 vcc, v230, v28
	v_addc_co_u32 v32, vcc, 0, v32, vcc
	v_cmp_eq_u32 vcc, v230, v28
	v_addc_co_u32 v34, vcc, 0, v34, vcc
	v_cmp_lt_u32 vcc, v230, v26
	v_addc_co_u32 v32, vcc, 0, v32, vcc
	v_cmp_eq_u32 vcc, v230, v26
	v_addc_co_u32 v34, vcc, 0, v34, vcc
	v_cmp_lt_u32 vcc, v230, v24
	v_addc_co_u32 v32, vcc, 0, v32, vcc
	v_cmp_eq_u32 vcc, v230, v24
	v_addc_co_u32 v34, vcc, 0, v34, vcc
	v_cmp_lt_u32 vcc, v230, v22
	v_addc_co_u32 v32, vcc, 0, v32, vcc
	v_cmp_eq_u32 vcc, v230, v22
	v_addc_co_u32 v34, vcc, 0, v34, vcc
	v_cmp_lt_u32 vcc, v230, v20
	v_addc_co_u32 v32, vcc, 0, v32, vcc
	v_cmp_eq_u32 vcc, v230, v20
	v_addc_co_u32 v34, vcc, 0, v34, vcc
	v_cmp_lt_u32 vcc, v230, v18
	v_addc_co_u32 v32, vcc, 0, v32, vcc
	v_cmp_eq_u32 vcc, v230, v18
	v_addc_co_u32 v34, vcc, 0, v34, vcc
	v_cmp_lt_u32 vcc, v230, v16
	v_addc_co_u32 v32, vcc, 0, v32, vcc
	v_cmp_eq_u32 vcc, v230, v16
	v_addc_co_u32 v34, vcc, 0, v34, vcc
	v_cmp_lt_u32 vcc, v230, v14
	v_addc_co_u32 v32, vcc, 0, v32, vcc
	v_cmp_eq_u32 vcc, v230, v14
	v_addc_co_u32 v34, vcc, 0, v34, vcc
	v_cmp_lt_u32 vcc, v230, v12
	v_addc_co_u32 v32, vcc, 0, v32, vcc
	v_cmp_eq_u32 vcc, v230, v12
	v_addc_co_u32 v34, vcc, 0, v34, vcc
	v_cmp_lt_u32 vcc, v230, v10
	v_addc_co_u32 v32, vcc, 0, v32, vcc
; template <int NJ>
; DI void select_row(const float* row, int n, u64* bmrow, int lane) {
;     ...
; #pragma unroll
;     for (int jj = 0; jj < NJ; ++jj) {
;       asm volatile("v_cmp_lt_u32 vcc, %1, %2\n\tv_addc_co_u32 %0, vcc, 0, %0, vcc" : "+v"(cgt) : "s"(T), "v"(key[jj]) : "vcc");
;       asm volatile("v_cmp_eq_u32 vcc, %1, %2\n\tv_addc_co_u32 %0, vcc, 0, %0, vcc" : "+v"(ceq) : "s"(T), "v"(key[jj]) : "vcc");
;     }
	v_cmp_eq_u32 vcc, v230, v10
	v_addc_co_u32 v34, vcc, 0, v34, vcc
	v_cmp_lt_u32 vcc, v230, v8
	v_addc_co_u32 v32, vcc, 0, v32, vcc
	v_cmp_eq_u32 vcc, v230, v8
	v_addc_co_u32 v34, vcc, 0, v34, vcc
	v_cmp_lt_u32 vcc, v230, v6
	v_addc_co_u32 v32, vcc, 0, v32, vcc
	v_cmp_eq_u32 vcc, v230, v6
	v_addc_co_u32 v34, vcc, 0, v34, vcc
	v_cmp_lt_u32 vcc, v230, v4
	v_addc_co_u32 v32, vcc, 0, v32, vcc
	v_cmp_eq_u32 vcc, v230, v4
	v_addc_co_u32 v34, vcc, 0, v34, vcc
	v_cmp_lt_u32 vcc, v230, v240
	v_addc_co_u32 v32, vcc, 0, v32, vcc
	v_cmp_eq_u32 vcc, v230, v240
	v_addc_co_u32 v34, vcc, 0, v34, vcc
	v_cmp_lt_u32 vcc, v230, v236
	v_addc_co_u32 v32, vcc, 0, v32, vcc
	v_cmp_eq_u32 vcc, v230, v236
	v_addc_co_u32 v34, vcc, 0, v34, vcc
	v_cmp_lt_u32 vcc, v230, v211
	v_addc_co_u32 v32, vcc, 0, v32, vcc
	v_cmp_eq_u32 vcc, v230, v211
	v_addc_co_u32 v34, vcc, 0, v34, vcc
	v_cmp_lt_u32 vcc, v230, v239
	v_addc_co_u32 v32, vcc, 0, v32, vcc
	v_cmp_eq_u32 vcc, v230, v239
	v_addc_co_u32 v34, vcc, 0, v34, vcc
	v_cmp_lt_u32 vcc, v230, v227
	v_addc_co_u32 v32, vcc, 0, v32, vcc
	v_cmp_eq_u32 vcc, v230, v227
	v_addc_co_u32 v34, vcc, 0, v34, vcc
	v_cmp_lt_u32 vcc, v230, v253
	v_addc_co_u32 v32, vcc, 0, v32, vcc
	v_cmp_eq_u32 vcc, v230, v253
	v_addc_co_u32 v34, vcc, 0, v34, vcc
	v_cmp_lt_u32 vcc, v230, v252
	v_addc_co_u32 v32, vcc, 0, v32, vcc
	v_cmp_eq_u32 vcc, v230, v252
	v_addc_co_u32 v34, vcc, 0, v34, vcc
	v_cmp_lt_u32 vcc, v230, v251
	v_addc_co_u32 v32, vcc, 0, v32, vcc
	v_cmp_eq_u32 vcc, v230, v251
	v_addc_co_u32 v34, vcc, 0, v34, vcc
	v_cmp_lt_u32 vcc, v230, v250
	v_addc_co_u32 v32, vcc, 0, v32, vcc
	v_cmp_eq_u32 vcc, v230, v250
	v_addc_co_u32 v34, vcc, 0, v34, vcc
	v_cmp_lt_u32 vcc, v230, v249
	v_addc_co_u32 v32, vcc, 0, v32, vcc
	v_cmp_eq_u32 vcc, v230, v249
	v_addc_co_u32 v34, vcc, 0, v34, vcc
	v_cmp_lt_u32 vcc, v230, v248
	v_addc_co_u32 v32, vcc, 0, v32, vcc
	v_cmp_eq_u32 vcc, v230, v248
	v_addc_co_u32 v34, vcc, 0, v34, vcc
	v_cmp_lt_u32 vcc, v230, v247
	v_addc_co_u32 v32, vcc, 0, v32, vcc
	v_cmp_eq_u32 vcc, v230, v247
	v_addc_co_u32 v34, vcc, 0, v34, vcc
	v_cmp_lt_u32 vcc, v230, v246
	v_addc_co_u32 v32, vcc, 0, v32, vcc
	v_cmp_eq_u32 vcc, v230, v246
	v_addc_co_u32 v34, vcc, 0, v34, vcc
	v_cmp_lt_u32 vcc, v230, v245
	v_addc_co_u32 v32, vcc, 0, v32, vcc
	v_cmp_eq_u32 vcc, v230, v245
	v_addc_co_u32 v34, vcc, 0, v34, vcc
	v_cmp_lt_u32 vcc, v230, v244
	v_addc_co_u32 v32, vcc, 0, v32, vcc
	v_cmp_eq_u32 vcc, v230, v244
	v_addc_co_u32 v34, vcc, 0, v34, vcc
	v_cmp_lt_u32 vcc, v230, v233
	v_addc_co_u32 v32, vcc, 0, v32, vcc
	v_cmp_eq_u32 vcc, v230, v233
	v_addc_co_u32 v34, vcc, 0, v34, vcc
	v_cmp_lt_u32 vcc, v230, v232
	v_addc_co_u32 v32, vcc, 0, v32, vcc
	v_cmp_eq_u32 vcc, v230, v232
	v_addc_co_u32 v34, vcc, 0, v34, vcc
	v_cmp_lt_u32 vcc, v230, v0
	v_addc_co_u32 v32, vcc, 0, v32, vcc
	v_cmp_eq_u32 vcc, v230, v0
	v_addc_co_u32 v34, vcc, 0, v34, vcc
	v_cmp_lt_u32 vcc, v230, v83
	v_addc_co_u32 v32, vcc, 0, v32, vcc
	v_cmp_eq_u32 vcc, v230, v83
	v_addc_co_u32 v34, vcc, 0, v34, vcc
	v_cmp_lt_u32 vcc, v230, v81
	v_addc_co_u32 v32, vcc, 0, v32, vcc
	v_cmp_eq_u32 vcc, v230, v81
	v_addc_co_u32 v34, vcc, 0, v34, vcc
	v_cmp_lt_u32 vcc, v230, v87
	v_addc_co_u32 v32, vcc, 0, v32, vcc
	v_cmp_eq_u32 vcc, v230, v87
	v_addc_co_u32 v34, vcc, 0, v34, vcc
	v_cmp_lt_u32 vcc, v230, v85
	v_addc_co_u32 v32, vcc, 0, v32, vcc
	v_cmp_eq_u32 vcc, v230, v85
	v_addc_co_u32 v34, vcc, 0, v34, vcc
	v_cmp_lt_u32 vcc, v230, v91
	v_addc_co_u32 v32, vcc, 0, v32, vcc
	v_cmp_eq_u32 vcc, v230, v91
	v_addc_co_u32 v34, vcc, 0, v34, vcc
	v_cmp_lt_u32 vcc, v230, v89
	v_addc_co_u32 v32, vcc, 0, v32, vcc
	v_cmp_eq_u32 vcc, v230, v89
	v_addc_co_u32 v34, vcc, 0, v34, vcc
	v_cmp_lt_u32 vcc, v230, v95
	v_addc_co_u32 v32, vcc, 0, v32, vcc
	v_cmp_eq_u32 vcc, v230, v95
	v_addc_co_u32 v34, vcc, 0, v34, vcc
	v_cmp_lt_u32 vcc, v230, v93
	v_addc_co_u32 v32, vcc, 0, v32, vcc
	v_cmp_eq_u32 vcc, v230, v93
	v_addc_co_u32 v34, vcc, 0, v34, vcc
	v_cmp_lt_u32 vcc, v230, v99
	v_addc_co_u32 v32, vcc, 0, v32, vcc
	v_cmp_eq_u32 vcc, v230, v99
	v_addc_co_u32 v34, vcc, 0, v34, vcc
	v_cmp_lt_u32 vcc, v230, v97
	v_addc_co_u32 v32, vcc, 0, v32, vcc
	v_cmp_eq_u32 vcc, v230, v97
	v_addc_co_u32 v34, vcc, 0, v34, vcc
	v_cmp_lt_u32 vcc, v230, v103
	v_addc_co_u32 v32, vcc, 0, v32, vcc
	v_cmp_eq_u32 vcc, v230, v103
	v_addc_co_u32 v34, vcc, 0, v34, vcc
	v_cmp_lt_u32 vcc, v230, v101
	v_addc_co_u32 v32, vcc, 0, v32, vcc
	v_cmp_eq_u32 vcc, v230, v101
	v_addc_co_u32 v34, vcc, 0, v34, vcc
	v_cmp_lt_u32 vcc, v230, v107
	v_addc_co_u32 v32, vcc, 0, v32, vcc
	v_cmp_eq_u32 vcc, v230, v107
	v_addc_co_u32 v34, vcc, 0, v34, vcc
	v_cmp_lt_u32 vcc, v230, v105
	v_addc_co_u32 v32, vcc, 0, v32, vcc
	v_cmp_eq_u32 vcc, v230, v105
	v_addc_co_u32 v34, vcc, 0, v34, vcc
	v_cmp_lt_u32 vcc, v230, v111
	v_addc_co_u32 v32, vcc, 0, v32, vcc
	v_cmp_eq_u32 vcc, v230, v111
	v_addc_co_u32 v34, vcc, 0, v34, vcc
	v_cmp_lt_u32 vcc, v230, v109
	v_addc_co_u32 v32, vcc, 0, v32, vcc
	v_cmp_eq_u32 vcc, v230, v109
	v_addc_co_u32 v34, vcc, 0, v34, vcc
	v_cmp_lt_u32 vcc, v230, v115
	v_addc_co_u32 v32, vcc, 0, v32, vcc
	v_cmp_eq_u32 vcc, v230, v115
	v_addc_co_u32 v34, vcc, 0, v34, vcc
	v_cmp_lt_u32 vcc, v230, v113
	v_addc_co_u32 v32, vcc, 0, v32, vcc
	v_cmp_eq_u32 vcc, v230, v113
	v_addc_co_u32 v34, vcc, 0, v34, vcc
	v_cmp_lt_u32 vcc, v230, v119
	v_addc_co_u32 v32, vcc, 0, v32, vcc
	v_cmp_eq_u32 vcc, v230, v119
	v_addc_co_u32 v34, vcc, 0, v34, vcc
	v_cmp_lt_u32 vcc, v230, v117
	v_addc_co_u32 v32, vcc, 0, v32, vcc
	v_cmp_eq_u32 vcc, v230, v117
	v_addc_co_u32 v34, vcc, 0, v34, vcc
	v_cmp_lt_u32 vcc, v230, v123
	v_addc_co_u32 v32, vcc, 0, v32, vcc
	v_cmp_eq_u32 vcc, v230, v123
	v_addc_co_u32 v34, vcc, 0, v34, vcc
; template <int NJ>
; DI void select_row(const float* row, int n, u64* bmrow, int lane) {
;     ...
; #pragma unroll
;     for (int jj = 0; jj < NJ; ++jj) {
;       asm volatile("v_cmp_lt_u32 vcc, %1, %2\n\tv_addc_co_u32 %0, vcc, 0, %0, vcc" : "+v"(cgt) : "s"(T), "v"(key[jj]) : "vcc");
;       asm volatile("v_cmp_eq_u32 vcc, %1, %2\n\tv_addc_co_u32 %0, vcc, 0, %0, vcc" : "+v"(ceq) : "s"(T), "v"(key[jj]) : "vcc");
;     }
;     cgt = wave_sum_i(cgt, lane); ceq = wave_sum_i(ceq, lane);
;     const int need = 256 - cgt;
;     unsigned bigv = 0x7fffffffu;
;     asm volatile("" : "+v"(bigv));
;     if (ceq != need) {
;       X = 0;
; #pragma unroll 1
;     ...
;         const unsigned cand = X | (1u << bit);
	v_cmp_lt_u32 vcc, v230, v121
	v_addc_co_u32 v32, vcc, 0, v32, vcc
	v_cmp_eq_u32 vcc, v230, v121
	v_addc_co_u32 v34, vcc, 0, v34, vcc
	v_cmp_lt_u32 vcc, v230, v127
	v_addc_co_u32 v32, vcc, 0, v32, vcc
	v_cmp_eq_u32 vcc, v230, v127
	v_addc_co_u32 v34, vcc, 0, v34, vcc
	v_cmp_lt_u32 vcc, v230, v125
	v_addc_co_u32 v32, vcc, 0, v32, vcc
	v_cmp_eq_u32 vcc, v230, v125
	v_addc_co_u32 v34, vcc, 0, v34, vcc
	v_cmp_lt_u32 vcc, v230, v131
	v_addc_co_u32 v32, vcc, 0, v32, vcc
	v_cmp_eq_u32 vcc, v230, v131
	v_addc_co_u32 v34, vcc, 0, v34, vcc
	v_cmp_lt_u32 vcc, v230, v129
	v_addc_co_u32 v32, vcc, 0, v32, vcc
	v_cmp_eq_u32 vcc, v230, v129
	v_addc_co_u32 v34, vcc, 0, v34, vcc
	v_cmp_lt_u32 vcc, v230, v135
	v_addc_co_u32 v32, vcc, 0, v32, vcc
	v_cmp_eq_u32 vcc, v230, v135
	v_addc_co_u32 v34, vcc, 0, v34, vcc
	v_cmp_lt_u32 vcc, v230, v133
	v_addc_co_u32 v32, vcc, 0, v32, vcc
	v_cmp_eq_u32 vcc, v230, v133
	v_addc_co_u32 v34, vcc, 0, v34, vcc
	v_cmp_lt_u32 vcc, v230, v139
	v_addc_co_u32 v32, vcc, 0, v32, vcc
	v_cmp_eq_u32 vcc, v230, v139
	v_addc_co_u32 v34, vcc, 0, v34, vcc
	v_cmp_lt_u32 vcc, v230, v137
	v_addc_co_u32 v32, vcc, 0, v32, vcc
	v_cmp_eq_u32 vcc, v230, v137
	v_addc_co_u32 v34, vcc, 0, v34, vcc
	v_cmp_lt_u32 vcc, v230, v143
	v_addc_co_u32 v32, vcc, 0, v32, vcc
	v_cmp_eq_u32 vcc, v230, v143
	v_addc_co_u32 v34, vcc, 0, v34, vcc
	v_cmp_lt_u32 vcc, v230, v141
	v_addc_co_u32 v32, vcc, 0, v32, vcc
	v_cmp_eq_u32 vcc, v230, v141
	v_addc_co_u32 v34, vcc, 0, v34, vcc
	v_cmp_lt_u32 vcc, v230, v147
	v_addc_co_u32 v32, vcc, 0, v32, vcc
	v_cmp_eq_u32 vcc, v230, v147
	v_addc_co_u32 v34, vcc, 0, v34, vcc
	v_cmp_lt_u32 vcc, v230, v145
	v_addc_co_u32 v32, vcc, 0, v32, vcc
	v_cmp_eq_u32 vcc, v230, v145
	v_addc_co_u32 v34, vcc, 0, v34, vcc
	v_cmp_lt_u32 vcc, v230, v151
	v_addc_co_u32 v32, vcc, 0, v32, vcc
	v_cmp_eq_u32 vcc, v230, v151
	v_addc_co_u32 v34, vcc, 0, v34, vcc
	v_cmp_lt_u32 vcc, v230, v149
	v_addc_co_u32 v32, vcc, 0, v32, vcc
	v_cmp_eq_u32 vcc, v230, v149
	v_addc_co_u32 v34, vcc, 0, v34, vcc
	v_cmp_lt_u32 vcc, v230, v155
	v_addc_co_u32 v32, vcc, 0, v32, vcc
	v_cmp_eq_u32 vcc, v230, v155
	v_addc_co_u32 v34, vcc, 0, v34, vcc
	v_cmp_lt_u32 vcc, v230, v153
	v_addc_co_u32 v32, vcc, 0, v32, vcc
	v_cmp_eq_u32 vcc, v230, v153
	v_addc_co_u32 v34, vcc, 0, v34, vcc
	v_cmp_lt_u32 vcc, v230, v159
	v_addc_co_u32 v32, vcc, 0, v32, vcc
	v_cmp_eq_u32 vcc, v230, v159
	v_addc_co_u32 v34, vcc, 0, v34, vcc
	v_cmp_lt_u32 vcc, v230, v157
	v_addc_co_u32 v32, vcc, 0, v32, vcc
	v_cmp_eq_u32 vcc, v230, v157
	v_addc_co_u32 v34, vcc, 0, v34, vcc
	v_cmp_lt_u32 vcc, v230, v163
	v_addc_co_u32 v32, vcc, 0, v32, vcc
	v_cmp_eq_u32 vcc, v230, v163
	v_addc_co_u32 v34, vcc, 0, v34, vcc
	v_cmp_lt_u32 vcc, v230, v161
	v_addc_co_u32 v32, vcc, 0, v32, vcc
	v_cmp_eq_u32 vcc, v230, v161
	v_addc_co_u32 v34, vcc, 0, v34, vcc
	v_cmp_lt_u32 vcc, v230, v167
	v_addc_co_u32 v32, vcc, 0, v32, vcc
	v_cmp_eq_u32 vcc, v230, v167
	v_addc_co_u32 v34, vcc, 0, v34, vcc
	v_cmp_lt_u32 vcc, v230, v165
	v_addc_co_u32 v32, vcc, 0, v32, vcc
	v_cmp_eq_u32 vcc, v230, v165
	v_addc_co_u32 v34, vcc, 0, v34, vcc
	v_cmp_lt_u32 vcc, v230, v171
	v_addc_co_u32 v32, vcc, 0, v32, vcc
	v_cmp_eq_u32 vcc, v230, v171
	v_addc_co_u32 v34, vcc, 0, v34, vcc
	v_cmp_lt_u32 vcc, v230, v169
	v_addc_co_u32 v32, vcc, 0, v32, vcc
	v_cmp_eq_u32 vcc, v230, v169
	v_addc_co_u32 v34, vcc, 0, v34, vcc
	v_cmp_lt_u32 vcc, v230, v175
	v_addc_co_u32 v32, vcc, 0, v32, vcc
	v_cmp_eq_u32 vcc, v230, v175
	v_addc_co_u32 v34, vcc, 0, v34, vcc
	v_cmp_lt_u32 vcc, v230, v173
	v_addc_co_u32 v32, vcc, 0, v32, vcc
	v_cmp_eq_u32 vcc, v230, v173
	v_addc_co_u32 v34, vcc, 0, v34, vcc
	v_cmp_lt_u32 vcc, v230, v179
	v_addc_co_u32 v32, vcc, 0, v32, vcc
	v_cmp_eq_u32 vcc, v230, v179
	v_addc_co_u32 v34, vcc, 0, v34, vcc
	v_cmp_lt_u32 vcc, v230, v177
	v_addc_co_u32 v32, vcc, 0, v32, vcc
	v_cmp_eq_u32 vcc, v230, v177
	v_addc_co_u32 v34, vcc, 0, v34, vcc
	v_cmp_lt_u32 vcc, v230, v183
	v_addc_co_u32 v32, vcc, 0, v32, vcc
	v_cmp_eq_u32 vcc, v230, v183
	v_addc_co_u32 v34, vcc, 0, v34, vcc
	v_cmp_lt_u32 vcc, v230, v181
	v_addc_co_u32 v32, vcc, 0, v32, vcc
	v_cmp_eq_u32 vcc, v230, v181
	v_addc_co_u32 v34, vcc, 0, v34, vcc
	v_cmp_lt_u32 vcc, v230, v187
	v_addc_co_u32 v32, vcc, 0, v32, vcc
	v_cmp_eq_u32 vcc, v230, v187
	v_addc_co_u32 v34, vcc, 0, v34, vcc
	v_cmp_lt_u32 vcc, v230, v185
	v_addc_co_u32 v32, vcc, 0, v32, vcc
	v_cmp_eq_u32 vcc, v230, v185
	v_addc_co_u32 v34, vcc, 0, v34, vcc
	v_cmp_lt_u32 vcc, v230, v191
	v_addc_co_u32 v32, vcc, 0, v32, vcc
	v_cmp_eq_u32 vcc, v230, v191
	v_addc_co_u32 v34, vcc, 0, v34, vcc
	v_cmp_lt_u32 vcc, v230, v189
	v_addc_co_u32 v32, vcc, 0, v32, vcc
	v_cmp_eq_u32 vcc, v230, v189
	v_addc_co_u32 v34, vcc, 0, v34, vcc
	v_cmp_lt_u32 vcc, v230, v195
	v_addc_co_u32 v32, vcc, 0, v32, vcc
	v_cmp_eq_u32 vcc, v230, v195
	v_addc_co_u32 v34, vcc, 0, v34, vcc
	v_cmp_lt_u32 vcc, v230, v193
	v_addc_co_u32 v32, vcc, 0, v32, vcc
	v_cmp_eq_u32 vcc, v230, v193
	v_addc_co_u32 v34, vcc, 0, v34, vcc
	v_cmp_lt_u32 vcc, v230, v199
	v_addc_co_u32 v32, vcc, 0, v32, vcc
	v_cmp_eq_u32 vcc, v230, v199
	v_addc_co_u32 v34, vcc, 0, v34, vcc
	v_cmp_lt_u32 vcc, v230, v197
	v_addc_co_u32 v32, vcc, 0, v32, vcc
	v_cmp_eq_u32 vcc, v230, v197
	v_addc_co_u32 v34, vcc, 0, v34, vcc
	v_cmp_lt_u32 vcc, v230, v235
	v_addc_co_u32 v32, vcc, 0, v32, vcc
	v_cmp_eq_u32 vcc, v230, v235
	v_addc_co_u32 v34, vcc, 0, v34, vcc
	v_cmp_lt_u32 vcc, v230, v234
	v_addc_co_u32 v32, vcc, 0, v32, vcc
	v_cmp_eq_u32 vcc, v230, v234
	v_addc_co_u32 v34, vcc, 0, v34, vcc
	v_cmp_lt_u32 vcc, v230, v243
	v_addc_co_u32 v32, vcc, 0, v32, vcc
	v_cmp_eq_u32 vcc, v230, v243
	v_addc_co_u32 v34, vcc, 0, v34, vcc
	v_cmp_lt_u32 vcc, v230, v242
	v_addc_co_u32 v32, vcc, 0, v32, vcc
	ds_bpermute_b32 v36, v5, v32
	v_cmp_eq_u32 vcc, v230, v242
	v_addc_co_u32 v34, vcc, 0, v34, vcc
	ds_bpermute_b32 v38, v5, v34
	s_waitcnt lgkmcnt(1)
	v_add_u32_e32 v32, v36, v32
	ds_bpermute_b32 v36, v7, v32
	s_waitcnt lgkmcnt(1)
	v_add_u32_e32 v34, v38, v34
	ds_bpermute_b32 v38, v7, v34
	s_waitcnt lgkmcnt(1)
	v_add_u32_e32 v32, v36, v32
	ds_bpermute_b32 v36, v9, v32
	s_waitcnt lgkmcnt(1)
	v_add_u32_e32 v34, v38, v34
	ds_bpermute_b32 v38, v9, v34
	s_waitcnt lgkmcnt(1)
	v_add_u32_e32 v32, v36, v32
	ds_bpermute_b32 v36, v11, v32
	s_waitcnt lgkmcnt(1)
	v_add_u32_e32 v34, v38, v34
	ds_bpermute_b32 v38, v11, v34
	s_waitcnt lgkmcnt(1)
	v_add_u32_e32 v32, v36, v32
	ds_bpermute_b32 v36, v13, v32
	s_waitcnt lgkmcnt(1)
	v_add_u32_e32 v34, v38, v34
	ds_bpermute_b32 v38, v13, v34
	s_waitcnt lgkmcnt(1)
	v_add_u32_e32 v32, v36, v32
	s_waitcnt lgkmcnt(0)
	v_add_u32_e32 v34, v38, v34
	ds_bpermute_b32 v38, v15, v32
	ds_bpermute_b32 v36, v15, v34
	s_waitcnt lgkmcnt(1)
	v_add_u32_e32 v32, v38, v32
	s_waitcnt lgkmcnt(0)
	v_add_u32_e32 v34, v36, v34
	v_sub_u32_e32 v32, 0x100, v32
	v_bfrev_b32_e32 v36, -2
	v_cmp_ne_u32_e32 vcc, v34, v32
	v_mov_b32_e32 v34, -1
	s_and_saveexec_b64 s[20:21], vcc
	s_cbranch_execz .LBB0_650
	v_mov_b32_e32 v34, 0
	s_mov_b32 s22, 13
; template <int NJ>
; DI void select_row(const float* row, int n, u64* bmrow, int lane) {
;     ...
;         const unsigned cand = X | (1u << bit);
;         int c = 0;
; #pragma unroll
;         for (int jj = 0; jj < NJ; ++jj) {
;           unsigned tmp;
;           asm volatile("v_add_u32 %1, %7, %5\n\tv_cmp_eq_u32 vcc, %2, %3\n\tv_cndmask_b32 %1, %4, %1, vcc\n\tv_cmp_gt_u32 vcc, %6, %1\n\tv_addc_co_u32 %0, vcc, 0, %0, vcc"
;                        : "+v"(c), "=&v"(tmp) : "s"(T), "v"(key[jj]), "v"(bigv), "v"(lane), "s"(cand), "n"(jj * 64) : "vcc");
;         }
;         c = wave_sum_i(c, lane);
;         if (c <= need) X = cand;
;       }
.LBB0_649:
	v_mov_b32_e32 v38, v1
	v_lshl_or_b32 v231, 1, s22, v34
	v_add_u32 v40, 0, v2
	v_cmp_eq_u32 vcc, v230, v79
	v_cndmask_b32 v40, v36, v40, vcc
	v_cmp_gt_u32 vcc, v231, v40
	v_addc_co_u32 v38, vcc, 0, v38, vcc
	s_add_i32 s22, s22, -1
	v_add_u32 v40, 64, v2
	v_cmp_eq_u32 vcc, v230, v77
	v_cndmask_b32 v40, v36, v40, vcc
	v_cmp_gt_u32 vcc, v231, v40
	v_addc_co_u32 v38, vcc, 0, v38, vcc
	s_cmp_lg_u32 s22, -1
	v_add_u32 v40, 0x80, v2
	v_cmp_eq_u32 vcc, v230, v75
	v_cndmask_b32 v40, v36, v40, vcc
	v_cmp_gt_u32 vcc, v231, v40
	v_addc_co_u32 v38, vcc, 0, v38, vcc
	v_add_u32 v40, 0xc0, v2
	v_cmp_eq_u32 vcc, v230, v73
	v_cndmask_b32 v40, v36, v40, vcc
	v_cmp_gt_u32 vcc, v231, v40
	v_addc_co_u32 v38, vcc, 0, v38, vcc
	v_add_u32 v40, 0x100, v2
	v_cmp_eq_u32 vcc, v230, v71
	v_cndmask_b32 v40, v36, v40, vcc
	v_cmp_gt_u32 vcc, v231, v40
	v_addc_co_u32 v38, vcc, 0, v38, vcc
	v_add_u32 v40, 0x140, v2
	v_cmp_eq_u32 vcc, v230, v69
	v_cndmask_b32 v40, v36, v40, vcc
	v_cmp_gt_u32 vcc, v231, v40
	v_addc_co_u32 v38, vcc, 0, v38, vcc
	v_add_u32 v40, 0x180, v2
	v_cmp_eq_u32 vcc, v230, v67
	v_cndmask_b32 v40, v36, v40, vcc
	v_cmp_gt_u32 vcc, v231, v40
	v_addc_co_u32 v38, vcc, 0, v38, vcc
	v_add_u32 v40, 0x1c0, v2
	v_cmp_eq_u32 vcc, v230, v65
	v_cndmask_b32 v40, v36, v40, vcc
	v_cmp_gt_u32 vcc, v231, v40
	v_addc_co_u32 v38, vcc, 0, v38, vcc
	v_add_u32 v40, 0x200, v2
	v_cmp_eq_u32 vcc, v230, v63
	v_cndmask_b32 v40, v36, v40, vcc
	v_cmp_gt_u32 vcc, v231, v40
	v_addc_co_u32 v38, vcc, 0, v38, vcc
	v_add_u32 v40, 0x240, v2
	v_cmp_eq_u32 vcc, v230, v61
	v_cndmask_b32 v40, v36, v40, vcc
	v_cmp_gt_u32 vcc, v231, v40
	v_addc_co_u32 v38, vcc, 0, v38, vcc
	v_add_u32 v40, 0x280, v2
	v_cmp_eq_u32 vcc, v230, v59
	v_cndmask_b32 v40, v36, v40, vcc
	v_cmp_gt_u32 vcc, v231, v40
	v_addc_co_u32 v38, vcc, 0, v38, vcc
	v_add_u32 v40, 0x2c0, v2
	v_cmp_eq_u32 vcc, v230, v57
	v_cndmask_b32 v40, v36, v40, vcc
	v_cmp_gt_u32 vcc, v231, v40
	v_addc_co_u32 v38, vcc, 0, v38, vcc
	v_add_u32 v40, 0x300, v2
	v_cmp_eq_u32 vcc, v230, v55
	v_cndmask_b32 v40, v36, v40, vcc
	v_cmp_gt_u32 vcc, v231, v40
	v_addc_co_u32 v38, vcc, 0, v38, vcc
	v_add_u32 v40, 0x340, v2
	v_cmp_eq_u32 vcc, v230, v51
	v_cndmask_b32 v40, v36, v40, vcc
	v_cmp_gt_u32 vcc, v231, v40
	v_addc_co_u32 v38, vcc, 0, v38, vcc
	v_add_u32 v40, 0x380, v2
	v_cmp_eq_u32 vcc, v230, v53
	v_cndmask_b32 v40, v36, v40, vcc
	v_cmp_gt_u32 vcc, v231, v40
	v_addc_co_u32 v38, vcc, 0, v38, vcc
	v_add_u32 v40, 0x3c0, v2
	v_cmp_eq_u32 vcc, v230, v49
	v_cndmask_b32 v40, v36, v40, vcc
	v_cmp_gt_u32 vcc, v231, v40
	v_addc_co_u32 v38, vcc, 0, v38, vcc
	v_add_u32 v40, 0x400, v2
	v_cmp_eq_u32 vcc, v230, v47
	v_cndmask_b32 v40, v36, v40, vcc
	v_cmp_gt_u32 vcc, v231, v40
	v_addc_co_u32 v38, vcc, 0, v38, vcc
	v_add_u32 v40, 0x440, v2
	v_cmp_eq_u32 vcc, v230, v45
	v_cndmask_b32 v40, v36, v40, vcc
	v_cmp_gt_u32 vcc, v231, v40
	v_addc_co_u32 v38, vcc, 0, v38, vcc
	v_add_u32 v40, 0x480, v2
	v_cmp_eq_u32 vcc, v230, v43
	v_cndmask_b32 v40, v36, v40, vcc
	v_cmp_gt_u32 vcc, v231, v40
	v_addc_co_u32 v38, vcc, 0, v38, vcc
	v_add_u32 v40, 0x4c0, v2
	v_cmp_eq_u32 vcc, v230, v41
	v_cndmask_b32 v40, v36, v40, vcc
	v_cmp_gt_u32 vcc, v231, v40
	v_addc_co_u32 v38, vcc, 0, v38, vcc
	v_add_u32 v40, 0x500, v2
	v_cmp_eq_u32 vcc, v230, v39
	v_cndmask_b32 v40, v36, v40, vcc
	v_cmp_gt_u32 vcc, v231, v40
	v_addc_co_u32 v38, vcc, 0, v38, vcc
	v_add_u32 v40, 0x540, v2
	v_cmp_eq_u32 vcc, v230, v37
	v_cndmask_b32 v40, v36, v40, vcc
	v_cmp_gt_u32 vcc, v231, v40
	v_addc_co_u32 v38, vcc, 0, v38, vcc
	v_add_u32 v40, 0x580, v2
	v_cmp_eq_u32 vcc, v230, v35
	v_cndmask_b32 v40, v36, v40, vcc
	v_cmp_gt_u32 vcc, v231, v40
	v_addc_co_u32 v38, vcc, 0, v38, vcc
	v_add_u32 v40, 0x5c0, v2
	v_cmp_eq_u32 vcc, v230, v33
	v_cndmask_b32 v40, v36, v40, vcc
	v_cmp_gt_u32 vcc, v231, v40
	v_addc_co_u32 v38, vcc, 0, v38, vcc
	v_add_u32 v40, 0x600, v2
	v_cmp_eq_u32 vcc, v230, v31
	v_cndmask_b32 v40, v36, v40, vcc
	v_cmp_gt_u32 vcc, v231, v40
	v_addc_co_u32 v38, vcc, 0, v38, vcc
	v_add_u32 v40, 0x640, v2
	v_cmp_eq_u32 vcc, v230, v29
	v_cndmask_b32 v40, v36, v40, vcc
	v_cmp_gt_u32 vcc, v231, v40
	v_addc_co_u32 v38, vcc, 0, v38, vcc
	v_add_u32 v40, 0x680, v2
	v_cmp_eq_u32 vcc, v230, v27
	v_cndmask_b32 v40, v36, v40, vcc
	v_cmp_gt_u32 vcc, v231, v40
	v_addc_co_u32 v38, vcc, 0, v38, vcc
	v_add_u32 v40, 0x6c0, v2
	v_cmp_eq_u32 vcc, v230, v25
	v_cndmask_b32 v40, v36, v40, vcc
	v_cmp_gt_u32 vcc, v231, v40
	v_addc_co_u32 v38, vcc, 0, v38, vcc
	v_add_u32 v40, 0x700, v2
	v_cmp_eq_u32 vcc, v230, v23
	v_cndmask_b32 v40, v36, v40, vcc
	v_cmp_gt_u32 vcc, v231, v40
	v_addc_co_u32 v38, vcc, 0, v38, vcc
	v_add_u32 v40, 0x740, v2
	v_cmp_eq_u32 vcc, v230, v21
	v_cndmask_b32 v40, v36, v40, vcc
	v_cmp_gt_u32 vcc, v231, v40
	v_addc_co_u32 v38, vcc, 0, v38, vcc
	v_add_u32 v40, 0x780, v2
	v_cmp_eq_u32 vcc, v230, v19
	v_cndmask_b32 v40, v36, v40, vcc
	v_cmp_gt_u32 vcc, v231, v40
	v_addc_co_u32 v38, vcc, 0, v38, vcc
	v_add_u32 v40, 0x7c0, v2
	v_cmp_eq_u32 vcc, v230, v17
	v_cndmask_b32 v40, v36, v40, vcc
	v_cmp_gt_u32 vcc, v231, v40
	v_addc_co_u32 v38, vcc, 0, v38, vcc
	v_add_u32 v40, 0x800, v2
	v_cmp_eq_u32 vcc, v230, v30
	v_cndmask_b32 v40, v36, v40, vcc
	v_cmp_gt_u32 vcc, v231, v40
	v_addc_co_u32 v38, vcc, 0, v38, vcc
	v_add_u32 v40, 0x840, v2
	v_cmp_eq_u32 vcc, v230, v28
	v_cndmask_b32 v40, v36, v40, vcc
	v_cmp_gt_u32 vcc, v231, v40
	v_addc_co_u32 v38, vcc, 0, v38, vcc
	v_add_u32 v40, 0x880, v2
	v_cmp_eq_u32 vcc, v230, v26
	v_cndmask_b32 v40, v36, v40, vcc
	v_cmp_gt_u32 vcc, v231, v40
	v_addc_co_u32 v38, vcc, 0, v38, vcc
	v_add_u32 v40, 0x8c0, v2
	v_cmp_eq_u32 vcc, v230, v24
	v_cndmask_b32 v40, v36, v40, vcc
	v_cmp_gt_u32 vcc, v231, v40
; template <int NJ>
; DI void select_row(const float* row, int n, u64* bmrow, int lane) {
;     ...
;         const unsigned cand = X | (1u << bit);
;         int c = 0;
; #pragma unroll
;         for (int jj = 0; jj < NJ; ++jj) {
;           unsigned tmp;
;           asm volatile("v_add_u32 %1, %7, %5\n\tv_cmp_eq_u32 vcc, %2, %3\n\tv_cndmask_b32 %1, %4, %1, vcc\n\tv_cmp_gt_u32 vcc, %6, %1\n\tv_addc_co_u32 %0, vcc, 0, %0, vcc"
;                        : "+v"(c), "=&v"(tmp) : "s"(T), "v"(key[jj]), "v"(bigv), "v"(lane), "s"(cand), "n"(jj * 64) : "vcc");
;         }
;         c = wave_sum_i(c, lane);
;         if (c <= need) X = cand;
;       }
	v_addc_co_u32 v38, vcc, 0, v38, vcc
	v_add_u32 v40, 0x900, v2
	v_cmp_eq_u32 vcc, v230, v22
	v_cndmask_b32 v40, v36, v40, vcc
	v_cmp_gt_u32 vcc, v231, v40
	v_addc_co_u32 v38, vcc, 0, v38, vcc
	v_add_u32 v40, 0x940, v2
	v_cmp_eq_u32 vcc, v230, v20
	v_cndmask_b32 v40, v36, v40, vcc
	v_cmp_gt_u32 vcc, v231, v40
	v_addc_co_u32 v38, vcc, 0, v38, vcc
	v_add_u32 v40, 0x980, v2
	v_cmp_eq_u32 vcc, v230, v18
	v_cndmask_b32 v40, v36, v40, vcc
	v_cmp_gt_u32 vcc, v231, v40
	v_addc_co_u32 v38, vcc, 0, v38, vcc
	v_add_u32 v40, 0x9c0, v2
	v_cmp_eq_u32 vcc, v230, v16
	v_cndmask_b32 v40, v36, v40, vcc
	v_cmp_gt_u32 vcc, v231, v40
	v_addc_co_u32 v38, vcc, 0, v38, vcc
	v_add_u32 v40, 0xa00, v2
	v_cmp_eq_u32 vcc, v230, v14
	v_cndmask_b32 v40, v36, v40, vcc
	v_cmp_gt_u32 vcc, v231, v40
	v_addc_co_u32 v38, vcc, 0, v38, vcc
	v_add_u32 v40, 0xa40, v2
	v_cmp_eq_u32 vcc, v230, v12
	v_cndmask_b32 v40, v36, v40, vcc
	v_cmp_gt_u32 vcc, v231, v40
	v_addc_co_u32 v38, vcc, 0, v38, vcc
	v_add_u32 v40, 0xa80, v2
	v_cmp_eq_u32 vcc, v230, v10
	v_cndmask_b32 v40, v36, v40, vcc
	v_cmp_gt_u32 vcc, v231, v40
	v_addc_co_u32 v38, vcc, 0, v38, vcc
	v_add_u32 v40, 0xac0, v2
	v_cmp_eq_u32 vcc, v230, v8
	v_cndmask_b32 v40, v36, v40, vcc
	v_cmp_gt_u32 vcc, v231, v40
	v_addc_co_u32 v38, vcc, 0, v38, vcc
	v_add_u32 v40, 0xb00, v2
	v_cmp_eq_u32 vcc, v230, v6
	v_cndmask_b32 v40, v36, v40, vcc
	v_cmp_gt_u32 vcc, v231, v40
	v_addc_co_u32 v38, vcc, 0, v38, vcc
	v_add_u32 v40, 0xb40, v2
	v_cmp_eq_u32 vcc, v230, v4
	v_cndmask_b32 v40, v36, v40, vcc
	v_cmp_gt_u32 vcc, v231, v40
	v_addc_co_u32 v38, vcc, 0, v38, vcc
	v_add_u32 v40, 0xb80, v2
	v_cmp_eq_u32 vcc, v230, v240
	v_cndmask_b32 v40, v36, v40, vcc
	v_cmp_gt_u32 vcc, v231, v40
	v_addc_co_u32 v38, vcc, 0, v38, vcc
	v_add_u32 v40, 0xbc0, v2
	v_cmp_eq_u32 vcc, v230, v236
	v_cndmask_b32 v40, v36, v40, vcc
	v_cmp_gt_u32 vcc, v231, v40
	v_addc_co_u32 v38, vcc, 0, v38, vcc
	v_add_u32 v40, 0xc00, v2
	v_cmp_eq_u32 vcc, v230, v211
	v_cndmask_b32 v40, v36, v40, vcc
	v_cmp_gt_u32 vcc, v231, v40
	v_addc_co_u32 v38, vcc, 0, v38, vcc
	v_add_u32 v40, 0xc40, v2
	v_cmp_eq_u32 vcc, v230, v239
	v_cndmask_b32 v40, v36, v40, vcc
	v_cmp_gt_u32 vcc, v231, v40
	v_addc_co_u32 v38, vcc, 0, v38, vcc
	v_add_u32 v40, 0xc80, v2
	v_cmp_eq_u32 vcc, v230, v227
	v_cndmask_b32 v40, v36, v40, vcc
	v_cmp_gt_u32 vcc, v231, v40
	v_addc_co_u32 v38, vcc, 0, v38, vcc
	v_add_u32 v40, 0xcc0, v2
	v_cmp_eq_u32 vcc, v230, v253
	v_cndmask_b32 v40, v36, v40, vcc
	v_cmp_gt_u32 vcc, v231, v40
	v_addc_co_u32 v38, vcc, 0, v38, vcc
	v_add_u32 v40, 0xd00, v2
	v_cmp_eq_u32 vcc, v230, v252
	v_cndmask_b32 v40, v36, v40, vcc
	v_cmp_gt_u32 vcc, v231, v40
	v_addc_co_u32 v38, vcc, 0, v38, vcc
	v_add_u32 v40, 0xd40, v2
	v_cmp_eq_u32 vcc, v230, v251
	v_cndmask_b32 v40, v36, v40, vcc
	v_cmp_gt_u32 vcc, v231, v40
	v_addc_co_u32 v38, vcc, 0, v38, vcc
	v_add_u32 v40, 0xd80, v2
	v_cmp_eq_u32 vcc, v230, v250
	v_cndmask_b32 v40, v36, v40, vcc
	v_cmp_gt_u32 vcc, v231, v40
	v_addc_co_u32 v38, vcc, 0, v38, vcc
	v_add_u32 v40, 0xdc0, v2
	v_cmp_eq_u32 vcc, v230, v249
	v_cndmask_b32 v40, v36, v40, vcc
	v_cmp_gt_u32 vcc, v231, v40
	v_addc_co_u32 v38, vcc, 0, v38, vcc
	v_add_u32 v40, 0xe00, v2
	v_cmp_eq_u32 vcc, v230, v248
	v_cndmask_b32 v40, v36, v40, vcc
	v_cmp_gt_u32 vcc, v231, v40
	v_addc_co_u32 v38, vcc, 0, v38, vcc
	v_add_u32 v40, 0xe40, v2
	v_cmp_eq_u32 vcc, v230, v247
	v_cndmask_b32 v40, v36, v40, vcc
	v_cmp_gt_u32 vcc, v231, v40
	v_addc_co_u32 v38, vcc, 0, v38, vcc
	v_add_u32 v40, 0xe80, v2
	v_cmp_eq_u32 vcc, v230, v246
	v_cndmask_b32 v40, v36, v40, vcc
	v_cmp_gt_u32 vcc, v231, v40
	v_addc_co_u32 v38, vcc, 0, v38, vcc
	v_add_u32 v40, 0xec0, v2
	v_cmp_eq_u32 vcc, v230, v245
	v_cndmask_b32 v40, v36, v40, vcc
	v_cmp_gt_u32 vcc, v231, v40
	v_addc_co_u32 v38, vcc, 0, v38, vcc
	v_add_u32 v40, 0xf00, v2
	v_cmp_eq_u32 vcc, v230, v244
	v_cndmask_b32 v40, v36, v40, vcc
	v_cmp_gt_u32 vcc, v231, v40
	v_addc_co_u32 v38, vcc, 0, v38, vcc
	v_add_u32 v40, 0xf40, v2
	v_cmp_eq_u32 vcc, v230, v233
	v_cndmask_b32 v40, v36, v40, vcc
	v_cmp_gt_u32 vcc, v231, v40
	v_addc_co_u32 v38, vcc, 0, v38, vcc
	v_add_u32 v40, 0xf80, v2
	v_cmp_eq_u32 vcc, v230, v232
	v_cndmask_b32 v40, v36, v40, vcc
	v_cmp_gt_u32 vcc, v231, v40
	v_addc_co_u32 v38, vcc, 0, v38, vcc
	v_add_u32 v40, 0xfc0, v2
	v_cmp_eq_u32 vcc, v230, v0
	v_cndmask_b32 v40, v36, v40, vcc
	v_cmp_gt_u32 vcc, v231, v40
	v_addc_co_u32 v38, vcc, 0, v38, vcc
	v_add_u32 v40, 0x1000, v2
	v_cmp_eq_u32 vcc, v230, v83
	v_cndmask_b32 v40, v36, v40, vcc
	v_cmp_gt_u32 vcc, v231, v40
	v_addc_co_u32 v38, vcc, 0, v38, vcc
	v_add_u32 v40, 0x1040, v2
	v_cmp_eq_u32 vcc, v230, v81
	v_cndmask_b32 v40, v36, v40, vcc
	v_cmp_gt_u32 vcc, v231, v40
	v_addc_co_u32 v38, vcc, 0, v38, vcc
	v_add_u32 v40, 0x1080, v2
	v_cmp_eq_u32 vcc, v230, v87
	v_cndmask_b32 v40, v36, v40, vcc
	v_cmp_gt_u32 vcc, v231, v40
	v_addc_co_u32 v38, vcc, 0, v38, vcc
	v_add_u32 v40, 0x10c0, v2
	v_cmp_eq_u32 vcc, v230, v85
	v_cndmask_b32 v40, v36, v40, vcc
	v_cmp_gt_u32 vcc, v231, v40
	v_addc_co_u32 v38, vcc, 0, v38, vcc
	v_add_u32 v40, 0x1100, v2
	v_cmp_eq_u32 vcc, v230, v91
	v_cndmask_b32 v40, v36, v40, vcc
	v_cmp_gt_u32 vcc, v231, v40
	v_addc_co_u32 v38, vcc, 0, v38, vcc
	v_add_u32 v40, 0x1140, v2
	v_cmp_eq_u32 vcc, v230, v89
	v_cndmask_b32 v40, v36, v40, vcc
	v_cmp_gt_u32 vcc, v231, v40
	v_addc_co_u32 v38, vcc, 0, v38, vcc
	v_add_u32 v40, 0x1180, v2
	v_cmp_eq_u32 vcc, v230, v95
	v_cndmask_b32 v40, v36, v40, vcc
	v_cmp_gt_u32 vcc, v231, v40
	v_addc_co_u32 v38, vcc, 0, v38, vcc
	v_add_u32 v40, 0x11c0, v2
	v_cmp_eq_u32 vcc, v230, v93
	v_cndmask_b32 v40, v36, v40, vcc
	v_cmp_gt_u32 vcc, v231, v40
	v_addc_co_u32 v38, vcc, 0, v38, vcc
; template <int NJ>
; DI void select_row(const float* row, int n, u64* bmrow, int lane) {
;     ...
;         const unsigned cand = X | (1u << bit);
;         int c = 0;
; #pragma unroll
;         for (int jj = 0; jj < NJ; ++jj) {
;           unsigned tmp;
;           asm volatile("v_add_u32 %1, %7, %5\n\tv_cmp_eq_u32 vcc, %2, %3\n\tv_cndmask_b32 %1, %4, %1, vcc\n\tv_cmp_gt_u32 vcc, %6, %1\n\tv_addc_co_u32 %0, vcc, 0, %0, vcc"
;                        : "+v"(c), "=&v"(tmp) : "s"(T), "v"(key[jj]), "v"(bigv), "v"(lane), "s"(cand), "n"(jj * 64) : "vcc");
;         }
;         c = wave_sum_i(c, lane);
;         if (c <= need) X = cand;
;       }
	v_add_u32 v40, 0x1200, v2
	v_cmp_eq_u32 vcc, v230, v99
	v_cndmask_b32 v40, v36, v40, vcc
	v_cmp_gt_u32 vcc, v231, v40
	v_addc_co_u32 v38, vcc, 0, v38, vcc
	v_add_u32 v40, 0x1240, v2
	v_cmp_eq_u32 vcc, v230, v97
	v_cndmask_b32 v40, v36, v40, vcc
	v_cmp_gt_u32 vcc, v231, v40
	v_addc_co_u32 v38, vcc, 0, v38, vcc
	v_add_u32 v40, 0x1280, v2
	v_cmp_eq_u32 vcc, v230, v103
	v_cndmask_b32 v40, v36, v40, vcc
	v_cmp_gt_u32 vcc, v231, v40
	v_addc_co_u32 v38, vcc, 0, v38, vcc
	v_add_u32 v40, 0x12c0, v2
	v_cmp_eq_u32 vcc, v230, v101
	v_cndmask_b32 v40, v36, v40, vcc
	v_cmp_gt_u32 vcc, v231, v40
	v_addc_co_u32 v38, vcc, 0, v38, vcc
	v_add_u32 v40, 0x1300, v2
	v_cmp_eq_u32 vcc, v230, v107
	v_cndmask_b32 v40, v36, v40, vcc
	v_cmp_gt_u32 vcc, v231, v40
	v_addc_co_u32 v38, vcc, 0, v38, vcc
	v_add_u32 v40, 0x1340, v2
	v_cmp_eq_u32 vcc, v230, v105
	v_cndmask_b32 v40, v36, v40, vcc
	v_cmp_gt_u32 vcc, v231, v40
	v_addc_co_u32 v38, vcc, 0, v38, vcc
	v_add_u32 v40, 0x1380, v2
	v_cmp_eq_u32 vcc, v230, v111
	v_cndmask_b32 v40, v36, v40, vcc
	v_cmp_gt_u32 vcc, v231, v40
	v_addc_co_u32 v38, vcc, 0, v38, vcc
	v_add_u32 v40, 0x13c0, v2
	v_cmp_eq_u32 vcc, v230, v109
	v_cndmask_b32 v40, v36, v40, vcc
	v_cmp_gt_u32 vcc, v231, v40
	v_addc_co_u32 v38, vcc, 0, v38, vcc
	v_add_u32 v40, 0x1400, v2
	v_cmp_eq_u32 vcc, v230, v115
	v_cndmask_b32 v40, v36, v40, vcc
	v_cmp_gt_u32 vcc, v231, v40
	v_addc_co_u32 v38, vcc, 0, v38, vcc
	v_add_u32 v40, 0x1440, v2
	v_cmp_eq_u32 vcc, v230, v113
	v_cndmask_b32 v40, v36, v40, vcc
	v_cmp_gt_u32 vcc, v231, v40
	v_addc_co_u32 v38, vcc, 0, v38, vcc
	v_add_u32 v40, 0x1480, v2
	v_cmp_eq_u32 vcc, v230, v119
	v_cndmask_b32 v40, v36, v40, vcc
	v_cmp_gt_u32 vcc, v231, v40
	v_addc_co_u32 v38, vcc, 0, v38, vcc
	v_add_u32 v40, 0x14c0, v2
	v_cmp_eq_u32 vcc, v230, v117
	v_cndmask_b32 v40, v36, v40, vcc
	v_cmp_gt_u32 vcc, v231, v40
	v_addc_co_u32 v38, vcc, 0, v38, vcc
	v_add_u32 v40, 0x1500, v2
	v_cmp_eq_u32 vcc, v230, v123
	v_cndmask_b32 v40, v36, v40, vcc
	v_cmp_gt_u32 vcc, v231, v40
	v_addc_co_u32 v38, vcc, 0, v38, vcc
	v_add_u32 v40, 0x1540, v2
	v_cmp_eq_u32 vcc, v230, v121
	v_cndmask_b32 v40, v36, v40, vcc
	v_cmp_gt_u32 vcc, v231, v40
	v_addc_co_u32 v38, vcc, 0, v38, vcc
	v_add_u32 v40, 0x1580, v2
	v_cmp_eq_u32 vcc, v230, v127
	v_cndmask_b32 v40, v36, v40, vcc
	v_cmp_gt_u32 vcc, v231, v40
	v_addc_co_u32 v38, vcc, 0, v38, vcc
	v_add_u32 v40, 0x15c0, v2
	v_cmp_eq_u32 vcc, v230, v125
	v_cndmask_b32 v40, v36, v40, vcc
	v_cmp_gt_u32 vcc, v231, v40
	v_addc_co_u32 v38, vcc, 0, v38, vcc
	v_add_u32 v40, 0x1600, v2
	v_cmp_eq_u32 vcc, v230, v131
	v_cndmask_b32 v40, v36, v40, vcc
	v_cmp_gt_u32 vcc, v231, v40
	v_addc_co_u32 v38, vcc, 0, v38, vcc
	v_add_u32 v40, 0x1640, v2
	v_cmp_eq_u32 vcc, v230, v129
	v_cndmask_b32 v40, v36, v40, vcc
	v_cmp_gt_u32 vcc, v231, v40
	v_addc_co_u32 v38, vcc, 0, v38, vcc
	v_add_u32 v40, 0x1680, v2
	v_cmp_eq_u32 vcc, v230, v135
	v_cndmask_b32 v40, v36, v40, vcc
	v_cmp_gt_u32 vcc, v231, v40
	v_addc_co_u32 v38, vcc, 0, v38, vcc
	v_add_u32 v40, 0x16c0, v2
	v_cmp_eq_u32 vcc, v230, v133
	v_cndmask_b32 v40, v36, v40, vcc
	v_cmp_gt_u32 vcc, v231, v40
	v_addc_co_u32 v38, vcc, 0, v38, vcc
	v_add_u32 v40, 0x1700, v2
	v_cmp_eq_u32 vcc, v230, v139
	v_cndmask_b32 v40, v36, v40, vcc
	v_cmp_gt_u32 vcc, v231, v40
	v_addc_co_u32 v38, vcc, 0, v38, vcc
	v_add_u32 v40, 0x1740, v2
	v_cmp_eq_u32 vcc, v230, v137
	v_cndmask_b32 v40, v36, v40, vcc
	v_cmp_gt_u32 vcc, v231, v40
	v_addc_co_u32 v38, vcc, 0, v38, vcc
	v_add_u32 v40, 0x1780, v2
	v_cmp_eq_u32 vcc, v230, v143
	v_cndmask_b32 v40, v36, v40, vcc
	v_cmp_gt_u32 vcc, v231, v40
	v_addc_co_u32 v38, vcc, 0, v38, vcc
	v_add_u32 v40, 0x17c0, v2
	v_cmp_eq_u32 vcc, v230, v141
	v_cndmask_b32 v40, v36, v40, vcc
	v_cmp_gt_u32 vcc, v231, v40
	v_addc_co_u32 v38, vcc, 0, v38, vcc
	v_add_u32 v40, 0x1800, v2
	v_cmp_eq_u32 vcc, v230, v147
	v_cndmask_b32 v40, v36, v40, vcc
	v_cmp_gt_u32 vcc, v231, v40
	v_addc_co_u32 v38, vcc, 0, v38, vcc
	v_add_u32 v40, 0x1840, v2
	v_cmp_eq_u32 vcc, v230, v145
	v_cndmask_b32 v40, v36, v40, vcc
	v_cmp_gt_u32 vcc, v231, v40
	v_addc_co_u32 v38, vcc, 0, v38, vcc
	v_add_u32 v40, 0x1880, v2
	v_cmp_eq_u32 vcc, v230, v151
	v_cndmask_b32 v40, v36, v40, vcc
	v_cmp_gt_u32 vcc, v231, v40
	v_addc_co_u32 v38, vcc, 0, v38, vcc
	v_add_u32 v40, 0x18c0, v2
	v_cmp_eq_u32 vcc, v230, v149
	v_cndmask_b32 v40, v36, v40, vcc
	v_cmp_gt_u32 vcc, v231, v40
	v_addc_co_u32 v38, vcc, 0, v38, vcc
	v_add_u32 v40, 0x1900, v2
	v_cmp_eq_u32 vcc, v230, v155
	v_cndmask_b32 v40, v36, v40, vcc
	v_cmp_gt_u32 vcc, v231, v40
	v_addc_co_u32 v38, vcc, 0, v38, vcc
	v_add_u32 v40, 0x1940, v2
	v_cmp_eq_u32 vcc, v230, v153
	v_cndmask_b32 v40, v36, v40, vcc
	v_cmp_gt_u32 vcc, v231, v40
	v_addc_co_u32 v38, vcc, 0, v38, vcc
	v_add_u32 v40, 0x1980, v2
; DI int shflxi(int v, int m, int lane) { return __builtin_amdgcn_ds_bpermute((lane ^ m) << 2, v); }
; DI int wave_sum_i(int v, int lane) {
; #pragma unroll
;   for (int o = 32; o > 0; o >>= 1) v += shflxi(v, o, lane);
;   return v;
; }
; template <int NJ>
; DI void select_row(const float* row, int n, u64* bmrow, int lane) {
;     ...
;         const unsigned cand = X | (1u << bit);
;         int c = 0;
; #pragma unroll
;         for (int jj = 0; jj < NJ; ++jj) {
;           unsigned tmp;
;           asm volatile("v_add_u32 %1, %7, %5\n\tv_cmp_eq_u32 vcc, %2, %3\n\tv_cndmask_b32 %1, %4, %1, vcc\n\tv_cmp_gt_u32 vcc, %6, %1\n\tv_addc_co_u32 %0, vcc, 0, %0, vcc"
;                        : "+v"(c), "=&v"(tmp) : "s"(T), "v"(key[jj]), "v"(bigv), "v"(lane), "s"(cand), "n"(jj * 64) : "vcc");
;         }
;         c = wave_sum_i(c, lane);
;         if (c <= need) X = cand;
;       }
	v_cmp_eq_u32 vcc, v230, v159
	v_cndmask_b32 v40, v36, v40, vcc
	v_cmp_gt_u32 vcc, v231, v40
	v_addc_co_u32 v38, vcc, 0, v38, vcc
	v_add_u32 v40, 0x19c0, v2
	v_cmp_eq_u32 vcc, v230, v157
	v_cndmask_b32 v40, v36, v40, vcc
	v_cmp_gt_u32 vcc, v231, v40
	v_addc_co_u32 v38, vcc, 0, v38, vcc
	v_add_u32 v40, 0x1a00, v2
	v_cmp_eq_u32 vcc, v230, v163
	v_cndmask_b32 v40, v36, v40, vcc
	v_cmp_gt_u32 vcc, v231, v40
	v_addc_co_u32 v38, vcc, 0, v38, vcc
	v_add_u32 v40, 0x1a40, v2
	v_cmp_eq_u32 vcc, v230, v161
	v_cndmask_b32 v40, v36, v40, vcc
	v_cmp_gt_u32 vcc, v231, v40
	v_addc_co_u32 v38, vcc, 0, v38, vcc
	v_add_u32 v40, 0x1a80, v2
	v_cmp_eq_u32 vcc, v230, v167
	v_cndmask_b32 v40, v36, v40, vcc
	v_cmp_gt_u32 vcc, v231, v40
	v_addc_co_u32 v38, vcc, 0, v38, vcc
	v_add_u32 v40, 0x1ac0, v2
	v_cmp_eq_u32 vcc, v230, v165
	v_cndmask_b32 v40, v36, v40, vcc
	v_cmp_gt_u32 vcc, v231, v40
	v_addc_co_u32 v38, vcc, 0, v38, vcc
	v_add_u32 v40, 0x1b00, v2
	v_cmp_eq_u32 vcc, v230, v171
	v_cndmask_b32 v40, v36, v40, vcc
	v_cmp_gt_u32 vcc, v231, v40
	v_addc_co_u32 v38, vcc, 0, v38, vcc
	v_add_u32 v40, 0x1b40, v2
	v_cmp_eq_u32 vcc, v230, v169
	v_cndmask_b32 v40, v36, v40, vcc
	v_cmp_gt_u32 vcc, v231, v40
	v_addc_co_u32 v38, vcc, 0, v38, vcc
	v_add_u32 v40, 0x1b80, v2
	v_cmp_eq_u32 vcc, v230, v175
	v_cndmask_b32 v40, v36, v40, vcc
	v_cmp_gt_u32 vcc, v231, v40
	v_addc_co_u32 v38, vcc, 0, v38, vcc
	v_add_u32 v40, 0x1bc0, v2
	v_cmp_eq_u32 vcc, v230, v173
	v_cndmask_b32 v40, v36, v40, vcc
	v_cmp_gt_u32 vcc, v231, v40
	v_addc_co_u32 v38, vcc, 0, v38, vcc
	v_add_u32 v40, 0x1c00, v2
	v_cmp_eq_u32 vcc, v230, v179
	v_cndmask_b32 v40, v36, v40, vcc
	v_cmp_gt_u32 vcc, v231, v40
	v_addc_co_u32 v38, vcc, 0, v38, vcc
	v_add_u32 v40, 0x1c40, v2
	v_cmp_eq_u32 vcc, v230, v177
	v_cndmask_b32 v40, v36, v40, vcc
	v_cmp_gt_u32 vcc, v231, v40
	v_addc_co_u32 v38, vcc, 0, v38, vcc
	v_add_u32 v40, 0x1c80, v2
	v_cmp_eq_u32 vcc, v230, v183
	v_cndmask_b32 v40, v36, v40, vcc
	v_cmp_gt_u32 vcc, v231, v40
	v_addc_co_u32 v38, vcc, 0, v38, vcc
	v_add_u32 v40, 0x1cc0, v2
	v_cmp_eq_u32 vcc, v230, v181
	v_cndmask_b32 v40, v36, v40, vcc
	v_cmp_gt_u32 vcc, v231, v40
	v_addc_co_u32 v38, vcc, 0, v38, vcc
	v_add_u32 v40, 0x1d00, v2
	v_cmp_eq_u32 vcc, v230, v187
	v_cndmask_b32 v40, v36, v40, vcc
	v_cmp_gt_u32 vcc, v231, v40
	v_addc_co_u32 v38, vcc, 0, v38, vcc
	v_add_u32 v40, 0x1d40, v2
	v_cmp_eq_u32 vcc, v230, v185
	v_cndmask_b32 v40, v36, v40, vcc
	v_cmp_gt_u32 vcc, v231, v40
	v_addc_co_u32 v38, vcc, 0, v38, vcc
	v_add_u32 v40, 0x1d80, v2
	v_cmp_eq_u32 vcc, v230, v191
	v_cndmask_b32 v40, v36, v40, vcc
	v_cmp_gt_u32 vcc, v231, v40
	v_addc_co_u32 v38, vcc, 0, v38, vcc
	v_add_u32 v40, 0x1dc0, v2
	v_cmp_eq_u32 vcc, v230, v189
	v_cndmask_b32 v40, v36, v40, vcc
	v_cmp_gt_u32 vcc, v231, v40
	v_addc_co_u32 v38, vcc, 0, v38, vcc
	v_add_u32 v40, 0x1e00, v2
	v_cmp_eq_u32 vcc, v230, v195
	v_cndmask_b32 v40, v36, v40, vcc
	v_cmp_gt_u32 vcc, v231, v40
	v_addc_co_u32 v38, vcc, 0, v38, vcc
	v_add_u32 v40, 0x1e40, v2
	v_cmp_eq_u32 vcc, v230, v193
	v_cndmask_b32 v40, v36, v40, vcc
	v_cmp_gt_u32 vcc, v231, v40
	v_addc_co_u32 v38, vcc, 0, v38, vcc
	v_add_u32 v40, 0x1e80, v2
	v_cmp_eq_u32 vcc, v230, v199
	v_cndmask_b32 v40, v36, v40, vcc
	v_cmp_gt_u32 vcc, v231, v40
	v_addc_co_u32 v38, vcc, 0, v38, vcc
	v_add_u32 v40, 0x1ec0, v2
	v_cmp_eq_u32 vcc, v230, v197
	v_cndmask_b32 v40, v36, v40, vcc
	v_cmp_gt_u32 vcc, v231, v40
	v_addc_co_u32 v38, vcc, 0, v38, vcc
	v_add_u32 v40, 0x1f00, v2
	v_cmp_eq_u32 vcc, v230, v235
	v_cndmask_b32 v40, v36, v40, vcc
	v_cmp_gt_u32 vcc, v231, v40
	v_addc_co_u32 v38, vcc, 0, v38, vcc
	v_add_u32 v40, 0x1f40, v2
	v_cmp_eq_u32 vcc, v230, v234
	v_cndmask_b32 v40, v36, v40, vcc
	v_cmp_gt_u32 vcc, v231, v40
	v_addc_co_u32 v38, vcc, 0, v38, vcc
	v_add_u32 v40, 0x1f80, v2
	v_cmp_eq_u32 vcc, v230, v243
	v_cndmask_b32 v40, v36, v40, vcc
	v_cmp_gt_u32 vcc, v231, v40
	v_addc_co_u32 v38, vcc, 0, v38, vcc
	v_add_u32 v40, 0x1fc0, v2
	v_cmp_eq_u32 vcc, v230, v242
	v_cndmask_b32 v40, v36, v40, vcc
	v_cmp_gt_u32 vcc, v231, v40
	v_addc_co_u32 v38, vcc, 0, v38, vcc
	s_nop 1
	v_add_u32_dpp v38, v38, v38 row_shr:1 row_mask:0xf bank_mask:0xf bound_ctrl:0
	s_nop 1
	v_add_u32_dpp v38, v38, v38 row_shr:2 row_mask:0xf bank_mask:0xf bound_ctrl:0
	s_nop 1
	v_add_u32_dpp v38, v38, v38 row_shr:4 row_mask:0xf bank_mask:0xf bound_ctrl:0
	s_nop 1
	v_add_u32_dpp v38, v38, v38 row_shr:8 row_mask:0xf bank_mask:0xf bound_ctrl:0
	s_nop 1
	v_add_u32_dpp v38, v38, v38 row_bcast:15 row_mask:0xa bank_mask:0xf
	s_nop 1
	v_add_u32_dpp v38, v38, v38 row_bcast:31 row_mask:0xc bank_mask:0xf
	s_nop 1
	v_readlane_b32 s98, v38, 63
	s_nop 1
	v_mov_b32_e32 v38, s98
	v_cmp_gt_i32_e32 vcc, v38, v32
	s_nop 1
	v_cndmask_b32_e32 v34, v231, v34, vcc
	s_cbranch_scc1 .LBB0_649

; template <int NJ>
; DI void select_row(const float* row, int n, u64* bmrow, int lane) {
;     ...
;   unsigned kl0 = 0, kh0 = 0, kl1 = 0, kh1 = 0;
;   unsigned T1v = T + 1, Tv = T;
;   asm volatile("" : "+v"(Tv), "+v"(T1v));
; #pragma unroll
;   for (int jj = 0; jj < NJ; ++jj) {
;     unsigned tmp;
;     if (jj < 64)
;       asm volatile("v_add_u32 %2, %9, %4\n\tv_cmp_gt_u32 vcc, %3, %2\n\tv_cndmask_b32 %2, %5, %6, vcc\n\tv_cmp_ge_u32 vcc, %7, %2\n\ts_nop 3\n\tv_writelane_b32 %0, vcc_lo, %8\n\tv_writelane_b32 %1, vcc_hi, %8"
;                    : "+v"(kl0), "+v"(kh0), "=&v"(tmp) : "s"(X), "v"(lane), "v"(T1v), "v"(Tv), "v"(key[jj]), "n"(jj & 63), "n"(jj * 64) : "vcc");
;     else
;       asm volatile("v_add_u32 %2, %9, %4\n\tv_cmp_gt_u32 vcc, %3, %2\n\tv_cndmask_b32 %2, %5, %6, vcc\n\tv_cmp_ge_u32 vcc, %7, %2\n\ts_nop 3\n\tv_writelane_b32 %0, vcc_lo, %8\n\tv_writelane_b32 %1, vcc_hi, %8"
;                    : "+v"(kl1), "+v"(kh1), "=&v"(tmp) : "s"(X), "v"(lane), "v"(T1v), "v"(Tv), "v"(key[jj]), "n"(jj & 63), "n"(jj * 64) : "vcc");
;   }
;   bmrow[lane] = ((u64)kh0 << 32) | kl0; bmrow[64 + lane] = ((u64)kh1 << 32) | kl1;
.LBB0_651:
	s_or_b64 exec, exec, s[6:7]
	v_add_u32_e32 v36, 1, v32
	v_mov_b32_e32 v230, v1
	v_mov_b32_e32 v231, v1
	s_nop 0
	v_add_u32 v38, 0, v2
	v_cmp_gt_u32 vcc, v34, v38
	v_cndmask_b32 v38, v36, v32, vcc
	v_cmp_ge_u32 vcc, v79, v38
	s_nop 3
	v_writelane_b32 v230, vcc_lo, 0
	v_writelane_b32 v231, vcc_hi, 0
	s_nop 0
	v_add_u32 v38, 64, v2
	v_cmp_gt_u32 vcc, v34, v38
	v_cndmask_b32 v38, v36, v32, vcc
	v_cmp_ge_u32 vcc, v77, v38
	s_nop 3
	v_writelane_b32 v230, vcc_lo, 1
	v_writelane_b32 v231, vcc_hi, 1
	s_nop 0
	v_add_u32 v38, 0x80, v2
	v_cmp_gt_u32 vcc, v34, v38
	v_cndmask_b32 v38, v36, v32, vcc
	v_cmp_ge_u32 vcc, v75, v38
	s_nop 3
	v_writelane_b32 v230, vcc_lo, 2
	v_writelane_b32 v231, vcc_hi, 2
	s_nop 0
	v_add_u32 v38, 0xc0, v2
	v_cmp_gt_u32 vcc, v34, v38
	v_cndmask_b32 v38, v36, v32, vcc
	v_cmp_ge_u32 vcc, v73, v38
	s_nop 3
	v_writelane_b32 v230, vcc_lo, 3
	v_writelane_b32 v231, vcc_hi, 3
	s_nop 0
	v_add_u32 v38, 0x100, v2
	v_cmp_gt_u32 vcc, v34, v38
	v_cndmask_b32 v38, v36, v32, vcc
	v_cmp_ge_u32 vcc, v71, v38
	s_nop 3
	v_writelane_b32 v230, vcc_lo, 4
	v_writelane_b32 v231, vcc_hi, 4
	s_nop 0
	v_add_u32 v38, 0x140, v2
	v_cmp_gt_u32 vcc, v34, v38
	v_cndmask_b32 v38, v36, v32, vcc
	v_cmp_ge_u32 vcc, v69, v38
	s_nop 3
	v_writelane_b32 v230, vcc_lo, 5
	v_writelane_b32 v231, vcc_hi, 5
	s_nop 0
	v_add_u32 v38, 0x180, v2
	v_cmp_gt_u32 vcc, v34, v38
	v_cndmask_b32 v38, v36, v32, vcc
	v_cmp_ge_u32 vcc, v67, v38
	s_nop 3
	v_writelane_b32 v230, vcc_lo, 6
	v_writelane_b32 v231, vcc_hi, 6
	s_nop 0
	v_add_u32 v38, 0x1c0, v2
	v_cmp_gt_u32 vcc, v34, v38
	v_cndmask_b32 v38, v36, v32, vcc
	v_cmp_ge_u32 vcc, v65, v38
	s_nop 3
	v_writelane_b32 v230, vcc_lo, 7
	v_writelane_b32 v231, vcc_hi, 7
	s_nop 0
	v_add_u32 v38, 0x200, v2
	v_cmp_gt_u32 vcc, v34, v38
	v_cndmask_b32 v38, v36, v32, vcc
	v_cmp_ge_u32 vcc, v63, v38
	s_nop 3
	v_writelane_b32 v230, vcc_lo, 8
	v_writelane_b32 v231, vcc_hi, 8
	s_nop 0
	v_add_u32 v38, 0x240, v2
	v_cmp_gt_u32 vcc, v34, v38
	v_cndmask_b32 v38, v36, v32, vcc
	v_cmp_ge_u32 vcc, v61, v38
	s_nop 3
	v_writelane_b32 v230, vcc_lo, 9
	v_writelane_b32 v231, vcc_hi, 9
	s_nop 0
	v_add_u32 v38, 0x280, v2
	v_cmp_gt_u32 vcc, v34, v38
	v_cndmask_b32 v38, v36, v32, vcc
	v_cmp_ge_u32 vcc, v59, v38
	s_nop 3
	v_writelane_b32 v230, vcc_lo, 10
	v_writelane_b32 v231, vcc_hi, 10
	s_nop 0
	v_add_u32 v38, 0x2c0, v2
	v_cmp_gt_u32 vcc, v34, v38
	v_cndmask_b32 v38, v36, v32, vcc
	v_cmp_ge_u32 vcc, v57, v38
	s_nop 3
	v_writelane_b32 v230, vcc_lo, 11
	v_writelane_b32 v231, vcc_hi, 11
	s_nop 0
	v_add_u32 v38, 0x300, v2
	v_cmp_gt_u32 vcc, v34, v38
	v_cndmask_b32 v38, v36, v32, vcc
	v_cmp_ge_u32 vcc, v55, v38
	s_nop 3
	v_writelane_b32 v230, vcc_lo, 12
	v_writelane_b32 v231, vcc_hi, 12
	s_nop 0
	v_add_u32 v38, 0x340, v2
	v_cmp_gt_u32 vcc, v34, v38
	v_cndmask_b32 v38, v36, v32, vcc
	v_cmp_ge_u32 vcc, v51, v38
	s_nop 3
	v_writelane_b32 v230, vcc_lo, 13
	v_writelane_b32 v231, vcc_hi, 13
	s_nop 0
	v_add_u32 v38, 0x380, v2
	v_cmp_gt_u32 vcc, v34, v38
	v_cndmask_b32 v38, v36, v32, vcc
	v_cmp_ge_u32 vcc, v53, v38
	s_nop 3
	v_writelane_b32 v230, vcc_lo, 14
	v_writelane_b32 v231, vcc_hi, 14
	s_nop 0
	v_add_u32 v38, 0x3c0, v2
	v_cmp_gt_u32 vcc, v34, v38
	v_cndmask_b32 v38, v36, v32, vcc
	v_cmp_ge_u32 vcc, v49, v38
	s_nop 3
	v_writelane_b32 v230, vcc_lo, 15
	v_writelane_b32 v231, vcc_hi, 15
	s_nop 0
	v_add_u32 v38, 0x400, v2
	v_cmp_gt_u32 vcc, v34, v38
	v_cndmask_b32 v38, v36, v32, vcc
	v_cmp_ge_u32 vcc, v47, v38
	s_nop 3
	v_writelane_b32 v230, vcc_lo, 16
	v_writelane_b32 v231, vcc_hi, 16
	s_nop 0
	v_add_u32 v38, 0x440, v2
	v_cmp_gt_u32 vcc, v34, v38
	v_cndmask_b32 v38, v36, v32, vcc
	v_cmp_ge_u32 vcc, v45, v38
	s_nop 3
	v_writelane_b32 v230, vcc_lo, 17
	v_writelane_b32 v231, vcc_hi, 17
	s_nop 0
	v_add_u32 v38, 0x480, v2
	v_cmp_gt_u32 vcc, v34, v38
	v_cndmask_b32 v38, v36, v32, vcc
	v_cmp_ge_u32 vcc, v43, v38
	s_nop 3
	v_writelane_b32 v230, vcc_lo, 18
	v_writelane_b32 v231, vcc_hi, 18
	s_nop 0
	v_add_u32 v38, 0x4c0, v2
	v_cmp_gt_u32 vcc, v34, v38
	v_cndmask_b32 v38, v36, v32, vcc
	v_cmp_ge_u32 vcc, v41, v38
	s_nop 3
	v_writelane_b32 v230, vcc_lo, 19
	v_writelane_b32 v231, vcc_hi, 19
	s_nop 0
	v_add_u32 v38, 0x500, v2
	v_cmp_gt_u32 vcc, v34, v38
	v_cndmask_b32 v38, v36, v32, vcc
	v_cmp_ge_u32 vcc, v39, v38
	s_nop 3
	v_writelane_b32 v230, vcc_lo, 20
	v_writelane_b32 v231, vcc_hi, 20
	s_nop 0
	v_add_u32 v38, 0x540, v2
	v_cmp_gt_u32 vcc, v34, v38
	v_cndmask_b32 v38, v36, v32, vcc
	v_cmp_ge_u32 vcc, v37, v38
	s_nop 3
	v_writelane_b32 v230, vcc_lo, 21
	v_writelane_b32 v231, vcc_hi, 21
	v_add_u32 v37, 0x580, v2
	v_cmp_gt_u32 vcc, v34, v37
	v_cndmask_b32 v37, v36, v32, vcc
	v_cmp_ge_u32 vcc, v35, v37
	s_nop 3
	v_writelane_b32 v230, vcc_lo, 22
	v_writelane_b32 v231, vcc_hi, 22
	s_nop 0
	v_add_u32 v35, 0x5c0, v2
	v_cmp_gt_u32 vcc, v34, v35
	v_cndmask_b32 v35, v36, v32, vcc
	v_cmp_ge_u32 vcc, v33, v35
	s_nop 3
	v_writelane_b32 v230, vcc_lo, 23
	v_writelane_b32 v231, vcc_hi, 23
	s_nop 0
	v_add_u32 v33, 0x600, v2
	v_cmp_gt_u32 vcc, v34, v33
	v_cndmask_b32 v33, v36, v32, vcc
	v_cmp_ge_u32 vcc, v31, v33
	s_nop 3
	v_writelane_b32 v230, vcc_lo, 24
	v_writelane_b32 v231, vcc_hi, 24
	s_nop 0
	v_add_u32 v31, 0x640, v2
	v_cmp_gt_u32 vcc, v34, v31
	v_cndmask_b32 v31, v36, v32, vcc
	v_cmp_ge_u32 vcc, v29, v31
	s_nop 3
	v_writelane_b32 v230, vcc_lo, 25
	v_writelane_b32 v231, vcc_hi, 25
	s_nop 0
	v_add_u32 v29, 0x680, v2
	v_cmp_gt_u32 vcc, v34, v29
	v_cndmask_b32 v29, v36, v32, vcc
	v_cmp_ge_u32 vcc, v27, v29
	s_nop 3
	v_writelane_b32 v230, vcc_lo, 26
	v_writelane_b32 v231, vcc_hi, 26
	s_nop 0
	v_add_u32 v27, 0x6c0, v2
	v_cmp_gt_u32 vcc, v34, v27
	v_cndmask_b32 v27, v36, v32, vcc
; template <int NJ>
; DI void select_row(const float* row, int n, u64* bmrow, int lane) {
;     ...
;   unsigned kl0 = 0, kh0 = 0, kl1 = 0, kh1 = 0;
;   unsigned T1v = T + 1, Tv = T;
;   asm volatile("" : "+v"(Tv), "+v"(T1v));
; #pragma unroll
;   for (int jj = 0; jj < NJ; ++jj) {
;     unsigned tmp;
;     if (jj < 64)
;       asm volatile("v_add_u32 %2, %9, %4\n\tv_cmp_gt_u32 vcc, %3, %2\n\tv_cndmask_b32 %2, %5, %6, vcc\n\tv_cmp_ge_u32 vcc, %7, %2\n\ts_nop 3\n\tv_writelane_b32 %0, vcc_lo, %8\n\tv_writelane_b32 %1, vcc_hi, %8"
;                    : "+v"(kl0), "+v"(kh0), "=&v"(tmp) : "s"(X), "v"(lane), "v"(T1v), "v"(Tv), "v"(key[jj]), "n"(jj & 63), "n"(jj * 64) : "vcc");
;     else
;       asm volatile("v_add_u32 %2, %9, %4\n\tv_cmp_gt_u32 vcc, %3, %2\n\tv_cndmask_b32 %2, %5, %6, vcc\n\tv_cmp_ge_u32 vcc, %7, %2\n\ts_nop 3\n\tv_writelane_b32 %0, vcc_lo, %8\n\tv_writelane_b32 %1, vcc_hi, %8"
;                    : "+v"(kl1), "+v"(kh1), "=&v"(tmp) : "s"(X), "v"(lane), "v"(T1v), "v"(Tv), "v"(key[jj]), "n"(jj & 63), "n"(jj * 64) : "vcc");
;   }
;   bmrow[lane] = ((u64)kh0 << 32) | kl0; bmrow[64 + lane] = ((u64)kh1 << 32) | kl1;
	v_cmp_ge_u32 vcc, v25, v27
	s_nop 3
	v_writelane_b32 v230, vcc_lo, 27
	v_writelane_b32 v231, vcc_hi, 27
	s_nop 0
	v_add_u32 v25, 0x700, v2
	v_cmp_gt_u32 vcc, v34, v25
	v_cndmask_b32 v25, v36, v32, vcc
	v_cmp_ge_u32 vcc, v23, v25
	s_nop 3
	v_writelane_b32 v230, vcc_lo, 28
	v_writelane_b32 v231, vcc_hi, 28
	s_nop 0
	v_add_u32 v23, 0x740, v2
	v_cmp_gt_u32 vcc, v34, v23
	v_cndmask_b32 v23, v36, v32, vcc
	v_cmp_ge_u32 vcc, v21, v23
	s_nop 3
	v_writelane_b32 v230, vcc_lo, 29
	v_writelane_b32 v231, vcc_hi, 29
	s_nop 0
	v_add_u32 v21, 0x780, v2
	v_cmp_gt_u32 vcc, v34, v21
	v_cndmask_b32 v21, v36, v32, vcc
	v_cmp_ge_u32 vcc, v19, v21
	s_nop 3
	v_writelane_b32 v230, vcc_lo, 30
	v_writelane_b32 v231, vcc_hi, 30
	s_nop 0
	v_add_u32 v19, 0x7c0, v2
	v_cmp_gt_u32 vcc, v34, v19
	v_cndmask_b32 v19, v36, v32, vcc
	v_cmp_ge_u32 vcc, v17, v19
	s_nop 3
	v_writelane_b32 v230, vcc_lo, 31
	v_writelane_b32 v231, vcc_hi, 31
	s_nop 0
	v_add_u32 v17, 0x800, v2
	v_cmp_gt_u32 vcc, v34, v17
	v_cndmask_b32 v17, v36, v32, vcc
	v_cmp_ge_u32 vcc, v30, v17
	s_nop 3
	v_writelane_b32 v230, vcc_lo, 32
	v_writelane_b32 v231, vcc_hi, 32
	v_add_u32 v17, 0x840, v2
	v_cmp_gt_u32 vcc, v34, v17
	v_cndmask_b32 v17, v36, v32, vcc
	v_cmp_ge_u32 vcc, v28, v17
	s_nop 3
	v_writelane_b32 v230, vcc_lo, 33
	v_writelane_b32 v231, vcc_hi, 33
	v_add_u32 v17, 0x880, v2
	v_cmp_gt_u32 vcc, v34, v17
	v_cndmask_b32 v17, v36, v32, vcc
	v_cmp_ge_u32 vcc, v26, v17
	s_nop 3
	v_writelane_b32 v230, vcc_lo, 34
	v_writelane_b32 v231, vcc_hi, 34
	v_add_u32 v17, 0x8c0, v2
	v_cmp_gt_u32 vcc, v34, v17
	v_cndmask_b32 v17, v36, v32, vcc
	v_cmp_ge_u32 vcc, v24, v17
	s_nop 3
	v_writelane_b32 v230, vcc_lo, 35
	v_writelane_b32 v231, vcc_hi, 35
	v_add_u32 v17, 0x900, v2
	v_cmp_gt_u32 vcc, v34, v17
	v_cndmask_b32 v17, v36, v32, vcc
	v_cmp_ge_u32 vcc, v22, v17
	s_nop 3
	v_writelane_b32 v230, vcc_lo, 36
	v_writelane_b32 v231, vcc_hi, 36
	v_add_u32 v17, 0x940, v2
	v_cmp_gt_u32 vcc, v34, v17
	v_cndmask_b32 v17, v36, v32, vcc
	v_cmp_ge_u32 vcc, v20, v17
	s_nop 3
	v_writelane_b32 v230, vcc_lo, 37
	v_writelane_b32 v231, vcc_hi, 37
	v_add_u32 v17, 0x980, v2
	v_cmp_gt_u32 vcc, v34, v17
	v_cndmask_b32 v17, v36, v32, vcc
	v_cmp_ge_u32 vcc, v18, v17
	s_nop 3
	v_writelane_b32 v230, vcc_lo, 38
	v_writelane_b32 v231, vcc_hi, 38
	v_add_u32 v17, 0x9c0, v2
	v_cmp_gt_u32 vcc, v34, v17
	v_cndmask_b32 v17, v36, v32, vcc
	v_cmp_ge_u32 vcc, v16, v17
	s_nop 3
	v_writelane_b32 v230, vcc_lo, 39
	v_writelane_b32 v231, vcc_hi, 39
	v_add_u32 v16, 0xa00, v2
	v_cmp_gt_u32 vcc, v34, v16
	v_cndmask_b32 v16, v36, v32, vcc
	v_cmp_ge_u32 vcc, v14, v16
	s_nop 3
	v_writelane_b32 v230, vcc_lo, 40
	v_writelane_b32 v231, vcc_hi, 40
	v_add_u32 v14, 0xa40, v2
	v_cmp_gt_u32 vcc, v34, v14
	v_cndmask_b32 v14, v36, v32, vcc
	v_cmp_ge_u32 vcc, v12, v14
	s_nop 3
	v_writelane_b32 v230, vcc_lo, 41
	v_writelane_b32 v231, vcc_hi, 41
	v_add_u32 v12, 0xa80, v2
	v_cmp_gt_u32 vcc, v34, v12
	v_cndmask_b32 v12, v36, v32, vcc
	v_cmp_ge_u32 vcc, v10, v12
	s_nop 3
	v_writelane_b32 v230, vcc_lo, 42
	v_writelane_b32 v231, vcc_hi, 42
	v_add_u32 v10, 0xac0, v2
	v_cmp_gt_u32 vcc, v34, v10
	v_cndmask_b32 v10, v36, v32, vcc
	v_cmp_ge_u32 vcc, v8, v10
	s_nop 3
	v_writelane_b32 v230, vcc_lo, 43
	v_writelane_b32 v231, vcc_hi, 43
	v_add_u32 v8, 0xb00, v2
	v_cmp_gt_u32 vcc, v34, v8
	v_cndmask_b32 v8, v36, v32, vcc
	v_cmp_ge_u32 vcc, v6, v8
	s_nop 3
	v_writelane_b32 v230, vcc_lo, 44
	v_writelane_b32 v231, vcc_hi, 44
	v_add_u32 v6, 0xb40, v2
	v_cmp_gt_u32 vcc, v34, v6
	v_cndmask_b32 v6, v36, v32, vcc
	v_cmp_ge_u32 vcc, v4, v6
	s_nop 3
	v_writelane_b32 v230, vcc_lo, 45
	v_writelane_b32 v231, vcc_hi, 45
	v_add_u32 v4, 0xb80, v2
	v_cmp_gt_u32 vcc, v34, v4
	v_cndmask_b32 v4, v36, v32, vcc
	v_cmp_ge_u32 vcc, v240, v4
	s_nop 3
	v_writelane_b32 v230, vcc_lo, 46
	v_writelane_b32 v231, vcc_hi, 46
	v_add_u32 v4, 0xbc0, v2
	v_cmp_gt_u32 vcc, v34, v4
	v_cndmask_b32 v4, v36, v32, vcc
	v_cmp_ge_u32 vcc, v236, v4
	s_nop 3
	v_writelane_b32 v230, vcc_lo, 47
	v_writelane_b32 v231, vcc_hi, 47
	v_add_u32 v4, 0xc00, v2
	v_cmp_gt_u32 vcc, v34, v4
	v_cndmask_b32 v4, v36, v32, vcc
	v_cmp_ge_u32 vcc, v211, v4
	s_nop 3
	v_writelane_b32 v230, vcc_lo, 48
	v_writelane_b32 v231, vcc_hi, 48
	v_add_u32 v4, 0xc40, v2
	v_cmp_gt_u32 vcc, v34, v4
	v_cndmask_b32 v4, v36, v32, vcc
	v_cmp_ge_u32 vcc, v239, v4
	s_nop 3
	v_writelane_b32 v230, vcc_lo, 49
	v_writelane_b32 v231, vcc_hi, 49
	v_add_u32 v4, 0xc80, v2
	v_cmp_gt_u32 vcc, v34, v4
	v_cndmask_b32 v4, v36, v32, vcc
	v_cmp_ge_u32 vcc, v227, v4
	s_nop 3
	v_writelane_b32 v230, vcc_lo, 50
	v_writelane_b32 v231, vcc_hi, 50
	v_add_u32 v4, 0xcc0, v2
	v_cmp_gt_u32 vcc, v34, v4
	v_cndmask_b32 v4, v36, v32, vcc
	v_cmp_ge_u32 vcc, v253, v4
	s_nop 3
	v_writelane_b32 v230, vcc_lo, 51
	v_writelane_b32 v231, vcc_hi, 51
	v_add_u32 v4, 0xd00, v2
	v_cmp_gt_u32 vcc, v34, v4
	v_cndmask_b32 v4, v36, v32, vcc
	v_cmp_ge_u32 vcc, v252, v4
	s_nop 3
	v_writelane_b32 v230, vcc_lo, 52
	v_writelane_b32 v231, vcc_hi, 52
	v_add_u32 v4, 0xd40, v2
	v_cmp_gt_u32 vcc, v34, v4
	v_cndmask_b32 v4, v36, v32, vcc
	v_cmp_ge_u32 vcc, v251, v4
	s_nop 3
	v_writelane_b32 v230, vcc_lo, 53
	v_writelane_b32 v231, vcc_hi, 53
	v_add_u32 v4, 0xd80, v2
	v_cmp_gt_u32 vcc, v34, v4
	v_cndmask_b32 v4, v36, v32, vcc
	v_cmp_ge_u32 vcc, v250, v4
	s_nop 3
	v_writelane_b32 v230, vcc_lo, 54
	v_writelane_b32 v231, vcc_hi, 54
	v_add_u32 v4, 0xdc0, v2
	v_cmp_gt_u32 vcc, v34, v4
	v_cndmask_b32 v4, v36, v32, vcc
	v_cmp_ge_u32 vcc, v249, v4
	s_nop 3
	v_writelane_b32 v230, vcc_lo, 55
	v_writelane_b32 v231, vcc_hi, 55
	v_add_u32 v4, 0xe00, v2
	v_cmp_gt_u32 vcc, v34, v4
	v_cndmask_b32 v4, v36, v32, vcc
	v_cmp_ge_u32 vcc, v248, v4
	s_nop 3
; template <int NJ>
; DI void select_row(const float* row, int n, u64* bmrow, int lane) {
;     ...
;   unsigned kl0 = 0, kh0 = 0, kl1 = 0, kh1 = 0;
;   unsigned T1v = T + 1, Tv = T;
;   asm volatile("" : "+v"(Tv), "+v"(T1v));
; #pragma unroll
;   for (int jj = 0; jj < NJ; ++jj) {
;     unsigned tmp;
;     if (jj < 64)
;       asm volatile("v_add_u32 %2, %9, %4\n\tv_cmp_gt_u32 vcc, %3, %2\n\tv_cndmask_b32 %2, %5, %6, vcc\n\tv_cmp_ge_u32 vcc, %7, %2\n\ts_nop 3\n\tv_writelane_b32 %0, vcc_lo, %8\n\tv_writelane_b32 %1, vcc_hi, %8"
;                    : "+v"(kl0), "+v"(kh0), "=&v"(tmp) : "s"(X), "v"(lane), "v"(T1v), "v"(Tv), "v"(key[jj]), "n"(jj & 63), "n"(jj * 64) : "vcc");
;     else
;       asm volatile("v_add_u32 %2, %9, %4\n\tv_cmp_gt_u32 vcc, %3, %2\n\tv_cndmask_b32 %2, %5, %6, vcc\n\tv_cmp_ge_u32 vcc, %7, %2\n\ts_nop 3\n\tv_writelane_b32 %0, vcc_lo, %8\n\tv_writelane_b32 %1, vcc_hi, %8"
;                    : "+v"(kl1), "+v"(kh1), "=&v"(tmp) : "s"(X), "v"(lane), "v"(T1v), "v"(Tv), "v"(key[jj]), "n"(jj & 63), "n"(jj * 64) : "vcc");
;   }
;   bmrow[lane] = ((u64)kh0 << 32) | kl0; bmrow[64 + lane] = ((u64)kh1 << 32) | kl1;
	v_writelane_b32 v230, vcc_lo, 56
	v_writelane_b32 v231, vcc_hi, 56
	v_add_u32 v4, 0xe40, v2
	v_cmp_gt_u32 vcc, v34, v4
	v_cndmask_b32 v4, v36, v32, vcc
	v_cmp_ge_u32 vcc, v247, v4
	s_nop 3
	v_writelane_b32 v230, vcc_lo, 57
	v_writelane_b32 v231, vcc_hi, 57
	v_add_u32 v4, 0xe80, v2
	v_cmp_gt_u32 vcc, v34, v4
	v_cndmask_b32 v4, v36, v32, vcc
	v_cmp_ge_u32 vcc, v246, v4
	s_nop 3
	v_writelane_b32 v230, vcc_lo, 58
	v_writelane_b32 v231, vcc_hi, 58
	v_add_u32 v4, 0xec0, v2
	v_cmp_gt_u32 vcc, v34, v4
	v_cndmask_b32 v4, v36, v32, vcc
	v_cmp_ge_u32 vcc, v245, v4
	s_nop 3
	v_writelane_b32 v230, vcc_lo, 59
	v_writelane_b32 v231, vcc_hi, 59
	v_add_u32 v4, 0xf00, v2
	v_cmp_gt_u32 vcc, v34, v4
	v_cndmask_b32 v4, v36, v32, vcc
	v_cmp_ge_u32 vcc, v244, v4
	s_nop 3
	v_writelane_b32 v230, vcc_lo, 60
	v_writelane_b32 v231, vcc_hi, 60
	s_nop 0
	v_add_u32 v4, 0xf40, v2
	v_cmp_gt_u32 vcc, v34, v4
	v_cndmask_b32 v4, v36, v32, vcc
	v_cmp_ge_u32 vcc, v233, v4
	s_nop 3
	v_writelane_b32 v230, vcc_lo, 61
	v_writelane_b32 v231, vcc_hi, 61
	v_mov_b32_e32 v233, v1
	v_add_u32 v4, 0xf80, v2
	v_cmp_gt_u32 vcc, v34, v4
	v_cndmask_b32 v4, v36, v32, vcc
	v_cmp_ge_u32 vcc, v232, v4
	s_nop 3
	v_writelane_b32 v230, vcc_lo, 62
	v_writelane_b32 v231, vcc_hi, 62
	v_mov_b32_e32 v232, v1
	v_add_u32 v4, 0xfc0, v2
	v_cmp_gt_u32 vcc, v34, v4
	v_cndmask_b32 v4, v36, v32, vcc
	v_cmp_ge_u32 vcc, v0, v4
	s_nop 3
	v_writelane_b32 v230, vcc_lo, 63
	v_writelane_b32 v231, vcc_hi, 63
	v_add_u32 v0, 0x1000, v2
	v_cmp_gt_u32 vcc, v34, v0
	v_cndmask_b32 v0, v36, v32, vcc
	v_cmp_ge_u32 vcc, v83, v0
	s_nop 3
	v_writelane_b32 v232, vcc_lo, 0
	v_writelane_b32 v233, vcc_hi, 0
	v_add_u32 v0, 0x1040, v2
	v_cmp_gt_u32 vcc, v34, v0
	v_cndmask_b32 v0, v36, v32, vcc
	v_cmp_ge_u32 vcc, v81, v0
	s_nop 3
	v_writelane_b32 v232, vcc_lo, 1
	v_writelane_b32 v233, vcc_hi, 1
	v_add_u32 v0, 0x1080, v2
	v_cmp_gt_u32 vcc, v34, v0
	v_cndmask_b32 v0, v36, v32, vcc
	v_cmp_ge_u32 vcc, v87, v0
	s_nop 3
	v_writelane_b32 v232, vcc_lo, 2
	v_writelane_b32 v233, vcc_hi, 2
	v_add_u32 v0, 0x10c0, v2
	v_cmp_gt_u32 vcc, v34, v0
	v_cndmask_b32 v0, v36, v32, vcc
	v_cmp_ge_u32 vcc, v85, v0
	s_nop 3
	v_writelane_b32 v232, vcc_lo, 3
	v_writelane_b32 v233, vcc_hi, 3
	v_add_u32 v0, 0x1100, v2
	v_cmp_gt_u32 vcc, v34, v0
	v_cndmask_b32 v0, v36, v32, vcc
	v_cmp_ge_u32 vcc, v91, v0
	s_nop 3
	v_writelane_b32 v232, vcc_lo, 4
	v_writelane_b32 v233, vcc_hi, 4
	v_add_u32 v0, 0x1140, v2
	v_cmp_gt_u32 vcc, v34, v0
	v_cndmask_b32 v0, v36, v32, vcc
	v_cmp_ge_u32 vcc, v89, v0
	s_nop 3
	v_writelane_b32 v232, vcc_lo, 5
	v_writelane_b32 v233, vcc_hi, 5
	v_add_u32 v0, 0x1180, v2
	v_cmp_gt_u32 vcc, v34, v0
	v_cndmask_b32 v0, v36, v32, vcc
	v_cmp_ge_u32 vcc, v95, v0
	s_nop 3
	v_writelane_b32 v232, vcc_lo, 6
	v_writelane_b32 v233, vcc_hi, 6
	v_add_u32 v0, 0x11c0, v2
	v_cmp_gt_u32 vcc, v34, v0
	v_cndmask_b32 v0, v36, v32, vcc
	v_cmp_ge_u32 vcc, v93, v0
	s_nop 3
	v_writelane_b32 v232, vcc_lo, 7
	v_writelane_b32 v233, vcc_hi, 7
	v_add_u32 v0, 0x1200, v2
	v_cmp_gt_u32 vcc, v34, v0
	v_cndmask_b32 v0, v36, v32, vcc
	v_cmp_ge_u32 vcc, v99, v0
	s_nop 3
	v_writelane_b32 v232, vcc_lo, 8
	v_writelane_b32 v233, vcc_hi, 8
	v_add_u32 v0, 0x1240, v2
	v_cmp_gt_u32 vcc, v34, v0
	v_cndmask_b32 v0, v36, v32, vcc
	v_cmp_ge_u32 vcc, v97, v0
	s_nop 3
	v_writelane_b32 v232, vcc_lo, 9
	v_writelane_b32 v233, vcc_hi, 9
	v_add_u32 v0, 0x1280, v2
	v_cmp_gt_u32 vcc, v34, v0
	v_cndmask_b32 v0, v36, v32, vcc
	v_cmp_ge_u32 vcc, v103, v0
	s_nop 3
	v_writelane_b32 v232, vcc_lo, 10
	v_writelane_b32 v233, vcc_hi, 10
	v_add_u32 v0, 0x12c0, v2
	v_cmp_gt_u32 vcc, v34, v0
	v_cndmask_b32 v0, v36, v32, vcc
	v_cmp_ge_u32 vcc, v101, v0
	s_nop 3
	v_writelane_b32 v232, vcc_lo, 11
	v_writelane_b32 v233, vcc_hi, 11
	v_add_u32 v0, 0x1300, v2
	v_cmp_gt_u32 vcc, v34, v0
	v_cndmask_b32 v0, v36, v32, vcc
	v_cmp_ge_u32 vcc, v107, v0
	s_nop 3
	v_writelane_b32 v232, vcc_lo, 12
	v_writelane_b32 v233, vcc_hi, 12
	v_add_u32 v0, 0x1340, v2
	v_cmp_gt_u32 vcc, v34, v0
	v_cndmask_b32 v0, v36, v32, vcc
	v_cmp_ge_u32 vcc, v105, v0
	s_nop 3
	v_writelane_b32 v232, vcc_lo, 13
	v_writelane_b32 v233, vcc_hi, 13
	v_add_u32 v0, 0x1380, v2
	v_cmp_gt_u32 vcc, v34, v0
	v_cndmask_b32 v0, v36, v32, vcc
	v_cmp_ge_u32 vcc, v111, v0
	s_nop 3
	v_writelane_b32 v232, vcc_lo, 14
	v_writelane_b32 v233, vcc_hi, 14
	v_add_u32 v0, 0x13c0, v2
	v_cmp_gt_u32 vcc, v34, v0
	v_cndmask_b32 v0, v36, v32, vcc
	v_cmp_ge_u32 vcc, v109, v0
	s_nop 3
	v_writelane_b32 v232, vcc_lo, 15
	v_writelane_b32 v233, vcc_hi, 15
	v_add_u32 v0, 0x1400, v2
	v_cmp_gt_u32 vcc, v34, v0
	v_cndmask_b32 v0, v36, v32, vcc
	v_cmp_ge_u32 vcc, v115, v0
	s_nop 3
	v_writelane_b32 v232, vcc_lo, 16
	v_writelane_b32 v233, vcc_hi, 16
	v_add_u32 v0, 0x1440, v2
	v_cmp_gt_u32 vcc, v34, v0
	v_cndmask_b32 v0, v36, v32, vcc
	v_cmp_ge_u32 vcc, v113, v0
	s_nop 3
	v_writelane_b32 v232, vcc_lo, 17
	v_writelane_b32 v233, vcc_hi, 17
	v_add_u32 v0, 0x1480, v2
	v_cmp_gt_u32 vcc, v34, v0
	v_cndmask_b32 v0, v36, v32, vcc
	v_cmp_ge_u32 vcc, v119, v0
	s_nop 3
	v_writelane_b32 v232, vcc_lo, 18
	v_writelane_b32 v233, vcc_hi, 18
	v_add_u32 v0, 0x14c0, v2
	v_cmp_gt_u32 vcc, v34, v0
	v_cndmask_b32 v0, v36, v32, vcc
	v_cmp_ge_u32 vcc, v117, v0
	s_nop 3
	v_writelane_b32 v232, vcc_lo, 19
	v_writelane_b32 v233, vcc_hi, 19
	v_add_u32 v0, 0x1500, v2
	v_cmp_gt_u32 vcc, v34, v0
	v_cndmask_b32 v0, v36, v32, vcc
	v_cmp_ge_u32 vcc, v123, v0
	s_nop 3
	v_writelane_b32 v232, vcc_lo, 20
	v_writelane_b32 v233, vcc_hi, 20
	v_add_u32 v0, 0x1540, v2
	v_cmp_gt_u32 vcc, v34, v0
	v_cndmask_b32 v0, v36, v32, vcc
	v_cmp_ge_u32 vcc, v121, v0
	s_nop 3
	v_writelane_b32 v232, vcc_lo, 21
	v_writelane_b32 v233, vcc_hi, 21
	v_add_u32 v0, 0x1580, v2
; template <int NJ>
; DI void select_row(const float* row, int n, u64* bmrow, int lane) {
;     ...
;   unsigned kl0 = 0, kh0 = 0, kl1 = 0, kh1 = 0;
;   unsigned T1v = T + 1, Tv = T;
;   asm volatile("" : "+v"(Tv), "+v"(T1v));
; #pragma unroll
;   for (int jj = 0; jj < NJ; ++jj) {
;     unsigned tmp;
;     if (jj < 64)
;       asm volatile("v_add_u32 %2, %9, %4\n\tv_cmp_gt_u32 vcc, %3, %2\n\tv_cndmask_b32 %2, %5, %6, vcc\n\tv_cmp_ge_u32 vcc, %7, %2\n\ts_nop 3\n\tv_writelane_b32 %0, vcc_lo, %8\n\tv_writelane_b32 %1, vcc_hi, %8"
;                    : "+v"(kl0), "+v"(kh0), "=&v"(tmp) : "s"(X), "v"(lane), "v"(T1v), "v"(Tv), "v"(key[jj]), "n"(jj & 63), "n"(jj * 64) : "vcc");
;     else
;       asm volatile("v_add_u32 %2, %9, %4\n\tv_cmp_gt_u32 vcc, %3, %2\n\tv_cndmask_b32 %2, %5, %6, vcc\n\tv_cmp_ge_u32 vcc, %7, %2\n\ts_nop 3\n\tv_writelane_b32 %0, vcc_lo, %8\n\tv_writelane_b32 %1, vcc_hi, %8"
;                    : "+v"(kl1), "+v"(kh1), "=&v"(tmp) : "s"(X), "v"(lane), "v"(T1v), "v"(Tv), "v"(key[jj]), "n"(jj & 63), "n"(jj * 64) : "vcc");
;   }
;   bmrow[lane] = ((u64)kh0 << 32) | kl0; bmrow[64 + lane] = ((u64)kh1 << 32) | kl1;
	v_cmp_gt_u32 vcc, v34, v0
	v_cndmask_b32 v0, v36, v32, vcc
	v_cmp_ge_u32 vcc, v127, v0
	s_nop 3
	v_writelane_b32 v232, vcc_lo, 22
	v_writelane_b32 v233, vcc_hi, 22
	v_add_u32 v0, 0x15c0, v2
	v_cmp_gt_u32 vcc, v34, v0
	v_cndmask_b32 v0, v36, v32, vcc
	v_cmp_ge_u32 vcc, v125, v0
	s_nop 3
	v_writelane_b32 v232, vcc_lo, 23
	v_writelane_b32 v233, vcc_hi, 23
	v_add_u32 v0, 0x1600, v2
	v_cmp_gt_u32 vcc, v34, v0
	v_cndmask_b32 v0, v36, v32, vcc
	v_cmp_ge_u32 vcc, v131, v0
	s_nop 3
	v_writelane_b32 v232, vcc_lo, 24
	v_writelane_b32 v233, vcc_hi, 24
	v_add_u32 v0, 0x1640, v2
	v_cmp_gt_u32 vcc, v34, v0
	v_cndmask_b32 v0, v36, v32, vcc
	v_cmp_ge_u32 vcc, v129, v0
	s_nop 3
	v_writelane_b32 v232, vcc_lo, 25
	v_writelane_b32 v233, vcc_hi, 25
	v_add_u32 v0, 0x1680, v2
	v_cmp_gt_u32 vcc, v34, v0
	v_cndmask_b32 v0, v36, v32, vcc
	v_cmp_ge_u32 vcc, v135, v0
	s_nop 3
	v_writelane_b32 v232, vcc_lo, 26
	v_writelane_b32 v233, vcc_hi, 26
	v_add_u32 v0, 0x16c0, v2
	v_cmp_gt_u32 vcc, v34, v0
	v_cndmask_b32 v0, v36, v32, vcc
	v_cmp_ge_u32 vcc, v133, v0
	s_nop 3
	v_writelane_b32 v232, vcc_lo, 27
	v_writelane_b32 v233, vcc_hi, 27
	v_add_u32 v0, 0x1700, v2
	v_cmp_gt_u32 vcc, v34, v0
	v_cndmask_b32 v0, v36, v32, vcc
	v_cmp_ge_u32 vcc, v139, v0
	s_nop 3
	v_writelane_b32 v232, vcc_lo, 28
	v_writelane_b32 v233, vcc_hi, 28
	v_add_u32 v0, 0x1740, v2
	v_cmp_gt_u32 vcc, v34, v0
	v_cndmask_b32 v0, v36, v32, vcc
	v_cmp_ge_u32 vcc, v137, v0
	s_nop 3
	v_writelane_b32 v232, vcc_lo, 29
	v_writelane_b32 v233, vcc_hi, 29
	v_add_u32 v0, 0x1780, v2
	v_cmp_gt_u32 vcc, v34, v0
	v_cndmask_b32 v0, v36, v32, vcc
	v_cmp_ge_u32 vcc, v143, v0
	s_nop 3
	v_writelane_b32 v232, vcc_lo, 30
	v_writelane_b32 v233, vcc_hi, 30
	v_add_u32 v0, 0x17c0, v2
	v_cmp_gt_u32 vcc, v34, v0
	v_cndmask_b32 v0, v36, v32, vcc
	v_cmp_ge_u32 vcc, v141, v0
	s_nop 3
	v_writelane_b32 v232, vcc_lo, 31
	v_writelane_b32 v233, vcc_hi, 31
	v_add_u32 v0, 0x1800, v2
	v_cmp_gt_u32 vcc, v34, v0
	v_cndmask_b32 v0, v36, v32, vcc
	v_cmp_ge_u32 vcc, v147, v0
	s_nop 3
	v_writelane_b32 v232, vcc_lo, 32
	v_writelane_b32 v233, vcc_hi, 32
	v_add_u32 v0, 0x1840, v2
	v_cmp_gt_u32 vcc, v34, v0
	v_cndmask_b32 v0, v36, v32, vcc
	v_cmp_ge_u32 vcc, v145, v0
	s_nop 3
	v_writelane_b32 v232, vcc_lo, 33
	v_writelane_b32 v233, vcc_hi, 33
	v_add_u32 v0, 0x1880, v2
	v_cmp_gt_u32 vcc, v34, v0
	v_cndmask_b32 v0, v36, v32, vcc
	v_cmp_ge_u32 vcc, v151, v0
	s_nop 3
	v_writelane_b32 v232, vcc_lo, 34
	v_writelane_b32 v233, vcc_hi, 34
	v_add_u32 v0, 0x18c0, v2
	v_cmp_gt_u32 vcc, v34, v0
	v_cndmask_b32 v0, v36, v32, vcc
	v_cmp_ge_u32 vcc, v149, v0
	s_nop 3
	v_writelane_b32 v232, vcc_lo, 35
	v_writelane_b32 v233, vcc_hi, 35
	v_add_u32 v0, 0x1900, v2
	v_cmp_gt_u32 vcc, v34, v0
	v_cndmask_b32 v0, v36, v32, vcc
	v_cmp_ge_u32 vcc, v155, v0
	s_nop 3
	v_writelane_b32 v232, vcc_lo, 36
	v_writelane_b32 v233, vcc_hi, 36
	v_add_u32 v0, 0x1940, v2
	v_cmp_gt_u32 vcc, v34, v0
	v_cndmask_b32 v0, v36, v32, vcc
	v_cmp_ge_u32 vcc, v153, v0
	s_nop 3
	v_writelane_b32 v232, vcc_lo, 37
	v_writelane_b32 v233, vcc_hi, 37
	v_add_u32 v0, 0x1980, v2
	v_cmp_gt_u32 vcc, v34, v0
	v_cndmask_b32 v0, v36, v32, vcc
	v_cmp_ge_u32 vcc, v159, v0
	s_nop 3
	v_writelane_b32 v232, vcc_lo, 38
	v_writelane_b32 v233, vcc_hi, 38
	v_add_u32 v0, 0x19c0, v2
	v_cmp_gt_u32 vcc, v34, v0
	v_cndmask_b32 v0, v36, v32, vcc
	v_cmp_ge_u32 vcc, v157, v0
	s_nop 3
	v_writelane_b32 v232, vcc_lo, 39
	v_writelane_b32 v233, vcc_hi, 39
	v_add_u32 v0, 0x1a00, v2
	v_cmp_gt_u32 vcc, v34, v0
	v_cndmask_b32 v0, v36, v32, vcc
	v_cmp_ge_u32 vcc, v163, v0
	s_nop 3
	v_writelane_b32 v232, vcc_lo, 40
	v_writelane_b32 v233, vcc_hi, 40
	v_add_u32 v0, 0x1a40, v2
	v_cmp_gt_u32 vcc, v34, v0
	v_cndmask_b32 v0, v36, v32, vcc
	v_cmp_ge_u32 vcc, v161, v0
	s_nop 3
	v_writelane_b32 v232, vcc_lo, 41
	v_writelane_b32 v233, vcc_hi, 41
	v_add_u32 v0, 0x1a80, v2
	v_cmp_gt_u32 vcc, v34, v0
	v_cndmask_b32 v0, v36, v32, vcc
	v_cmp_ge_u32 vcc, v167, v0
	s_nop 3
	v_writelane_b32 v232, vcc_lo, 42
	v_writelane_b32 v233, vcc_hi, 42
	v_add_u32 v0, 0x1ac0, v2
	v_cmp_gt_u32 vcc, v34, v0
	v_cndmask_b32 v0, v36, v32, vcc
; template <int NJ>
; DI void select_row(const float* row, int n, u64* bmrow, int lane) {
;     ...
;   unsigned kl0 = 0, kh0 = 0, kl1 = 0, kh1 = 0;
;   unsigned T1v = T + 1, Tv = T;
;   asm volatile("" : "+v"(Tv), "+v"(T1v));
; #pragma unroll
;   for (int jj = 0; jj < NJ; ++jj) {
;     unsigned tmp;
;     if (jj < 64)
;       asm volatile("v_add_u32 %2, %9, %4\n\tv_cmp_gt_u32 vcc, %3, %2\n\tv_cndmask_b32 %2, %5, %6, vcc\n\tv_cmp_ge_u32 vcc, %7, %2\n\ts_nop 3\n\tv_writelane_b32 %0, vcc_lo, %8\n\tv_writelane_b32 %1, vcc_hi, %8"
;                    : "+v"(kl0), "+v"(kh0), "=&v"(tmp) : "s"(X), "v"(lane), "v"(T1v), "v"(Tv), "v"(key[jj]), "n"(jj & 63), "n"(jj * 64) : "vcc");
;     else
;       asm volatile("v_add_u32 %2, %9, %4\n\tv_cmp_gt_u32 vcc, %3, %2\n\tv_cndmask_b32 %2, %5, %6, vcc\n\tv_cmp_ge_u32 vcc, %7, %2\n\ts_nop 3\n\tv_writelane_b32 %0, vcc_lo, %8\n\tv_writelane_b32 %1, vcc_hi, %8"
;                    : "+v"(kl1), "+v"(kh1), "=&v"(tmp) : "s"(X), "v"(lane), "v"(T1v), "v"(Tv), "v"(key[jj]), "n"(jj & 63), "n"(jj * 64) : "vcc");
;   }
;   bmrow[lane] = ((u64)kh0 << 32) | kl0; bmrow[64 + lane] = ((u64)kh1 << 32) | kl1;
	v_cmp_ge_u32 vcc, v165, v0
	s_nop 3
	v_writelane_b32 v232, vcc_lo, 43
	v_writelane_b32 v233, vcc_hi, 43
	v_add_u32 v0, 0x1b00, v2
	v_cmp_gt_u32 vcc, v34, v0
	v_cndmask_b32 v0, v36, v32, vcc
	v_cmp_ge_u32 vcc, v171, v0
	s_nop 3
	v_writelane_b32 v232, vcc_lo, 44
	v_writelane_b32 v233, vcc_hi, 44
	v_add_u32 v0, 0x1b40, v2
	v_cmp_gt_u32 vcc, v34, v0
	v_cndmask_b32 v0, v36, v32, vcc
	v_cmp_ge_u32 vcc, v169, v0
	s_nop 3
	v_writelane_b32 v232, vcc_lo, 45
	v_writelane_b32 v233, vcc_hi, 45
	v_add_u32 v0, 0x1b80, v2
	v_cmp_gt_u32 vcc, v34, v0
	v_cndmask_b32 v0, v36, v32, vcc
	v_cmp_ge_u32 vcc, v175, v0
	s_nop 3
	v_writelane_b32 v232, vcc_lo, 46
	v_writelane_b32 v233, vcc_hi, 46
	v_add_u32 v0, 0x1bc0, v2
	v_cmp_gt_u32 vcc, v34, v0
	v_cndmask_b32 v0, v36, v32, vcc
	v_cmp_ge_u32 vcc, v173, v0
	s_nop 3
	v_writelane_b32 v232, vcc_lo, 47
	v_writelane_b32 v233, vcc_hi, 47
	v_add_u32 v0, 0x1c00, v2
	v_cmp_gt_u32 vcc, v34, v0
	v_cndmask_b32 v0, v36, v32, vcc
	v_cmp_ge_u32 vcc, v179, v0
	s_nop 3
	v_writelane_b32 v232, vcc_lo, 48
	v_writelane_b32 v233, vcc_hi, 48
	v_add_u32 v0, 0x1c40, v2
	v_cmp_gt_u32 vcc, v34, v0
	v_cndmask_b32 v0, v36, v32, vcc
	v_cmp_ge_u32 vcc, v177, v0
	s_nop 3
	v_writelane_b32 v232, vcc_lo, 49
	v_writelane_b32 v233, vcc_hi, 49
	v_add_u32 v0, 0x1c80, v2
	v_cmp_gt_u32 vcc, v34, v0
	v_cndmask_b32 v0, v36, v32, vcc
	v_cmp_ge_u32 vcc, v183, v0
	s_nop 3
	v_writelane_b32 v232, vcc_lo, 50
	v_writelane_b32 v233, vcc_hi, 50
	v_add_u32 v0, 0x1cc0, v2
	v_cmp_gt_u32 vcc, v34, v0
	v_cndmask_b32 v0, v36, v32, vcc
	v_cmp_ge_u32 vcc, v181, v0
	s_nop 3
	v_writelane_b32 v232, vcc_lo, 51
	v_writelane_b32 v233, vcc_hi, 51
	v_add_u32 v0, 0x1d00, v2
	v_cmp_gt_u32 vcc, v34, v0
	v_cndmask_b32 v0, v36, v32, vcc
	v_cmp_ge_u32 vcc, v187, v0
	s_nop 3
	v_writelane_b32 v232, vcc_lo, 52
	v_writelane_b32 v233, vcc_hi, 52
	v_add_u32 v0, 0x1d40, v2
	v_cmp_gt_u32 vcc, v34, v0
	v_cndmask_b32 v0, v36, v32, vcc
	v_cmp_ge_u32 vcc, v185, v0
	s_nop 3
	v_writelane_b32 v232, vcc_lo, 53
	v_writelane_b32 v233, vcc_hi, 53
	v_add_u32 v0, 0x1d80, v2
	v_cmp_gt_u32 vcc, v34, v0
	v_cndmask_b32 v0, v36, v32, vcc
	v_cmp_ge_u32 vcc, v191, v0
	s_nop 3
	v_writelane_b32 v232, vcc_lo, 54
	v_writelane_b32 v233, vcc_hi, 54
	v_add_u32 v0, 0x1dc0, v2
	v_cmp_gt_u32 vcc, v34, v0
	v_cndmask_b32 v0, v36, v32, vcc
	v_cmp_ge_u32 vcc, v189, v0
	s_nop 3
	v_writelane_b32 v232, vcc_lo, 55
	v_writelane_b32 v233, vcc_hi, 55
	v_add_u32 v0, 0x1e00, v2
	v_cmp_gt_u32 vcc, v34, v0
	v_cndmask_b32 v0, v36, v32, vcc
	v_cmp_ge_u32 vcc, v195, v0
	s_nop 3
	v_writelane_b32 v232, vcc_lo, 56
	v_writelane_b32 v233, vcc_hi, 56
	v_add_u32 v0, 0x1e40, v2
	v_cmp_gt_u32 vcc, v34, v0
	v_cndmask_b32 v0, v36, v32, vcc
	v_cmp_ge_u32 vcc, v193, v0
	s_nop 3
	v_writelane_b32 v232, vcc_lo, 57
	v_writelane_b32 v233, vcc_hi, 57
	v_add_u32 v0, 0x1e80, v2
	v_cmp_gt_u32 vcc, v34, v0
	v_cndmask_b32 v0, v36, v32, vcc
	v_cmp_ge_u32 vcc, v199, v0
	s_nop 3
	v_writelane_b32 v232, vcc_lo, 58
	v_writelane_b32 v233, vcc_hi, 58
	v_add_u32 v0, 0x1ec0, v2
	v_cmp_gt_u32 vcc, v34, v0
	v_cndmask_b32 v0, v36, v32, vcc
	v_cmp_ge_u32 vcc, v197, v0
	s_nop 3
	v_writelane_b32 v232, vcc_lo, 59
	v_writelane_b32 v233, vcc_hi, 59
	v_add_u32 v0, 0x1f00, v2
	v_cmp_gt_u32 vcc, v34, v0
	v_cndmask_b32 v0, v36, v32, vcc
	v_cmp_ge_u32 vcc, v235, v0
	s_nop 3
	v_writelane_b32 v232, vcc_lo, 60
	v_writelane_b32 v233, vcc_hi, 60
	v_add_u32 v0, 0x1f40, v2
	v_cmp_gt_u32 vcc, v34, v0
	v_cndmask_b32 v0, v36, v32, vcc
	v_cmp_ge_u32 vcc, v234, v0
	s_nop 3
	v_writelane_b32 v232, vcc_lo, 61
	v_writelane_b32 v233, vcc_hi, 61
	v_add_u32 v0, 0x1f80, v2
	v_cmp_gt_u32 vcc, v34, v0
	v_cndmask_b32 v0, v36, v32, vcc
	v_cmp_ge_u32 vcc, v243, v0
	s_nop 3
	v_writelane_b32 v232, vcc_lo, 62
	v_writelane_b32 v233, vcc_hi, 62
	v_add_u32 v0, 0x1fc0, v2
	v_cmp_gt_u32 vcc, v34, v0
	v_cndmask_b32 v0, v36, v32, vcc
	v_cmp_ge_u32 vcc, v242, v0
	s_nop 3
	v_writelane_b32 v232, vcc_lo, 63
	v_writelane_b32 v233, vcc_hi, 63
	s_nop 0
	v_lshlrev_b32_e32 v0, 3, v2
	v_lshl_add_u64 v[16:17], v[228:229], 0, v[0:1]
	global_store_dwordx2 v[16:17], v[230:231], off

; DI int shflxi(int v, int m, int lane) { return __builtin_amdgcn_ds_bpermute((lane ^ m) << 2, v); }
; DI int wave_sum_i(int v, int lane) {
; #pragma unroll
;   for (int o = 32; o > 0; o >>= 1) v += shflxi(v, o, lane);
;   return v;
; }
; template <int NJ>
; DI void select_row(const float* row, int n, u64* bmrow, int lane) {
;     ...
;     unsigned cand = km & 0xff800000u;
; #pragma unroll 1
;     for (int pr = 0; pr < 4; ++pr) {
;       if (cand <= lo || cand >= hi) break;
;       int c = 0;
; #pragma unroll
;       for (int jj = 0; jj < NJ; ++jj)
;         asm volatile("v_cmp_le_u32 vcc, %1, %2\n\tv_addc_co_u32 %0, vcc, 0, %0, vcc" : "+v"(c) : "s"(cand), "v"(key[jj]) : "vcc");
;       c = wave_sum_i(c, lane);
;       if (c == 256) { T = cand; exact = true; break; }
;       if (c > 256) { lo = cand; break; }
;       hi = cand;
;       if (cand < 0x00800000u) break;
;       cand -= 0x00800000u;
;     }
;   }
.LBB0_721:
	v_cmp_gt_u32_e32 vcc, v115, v0
	v_cmp_lt_u32_e64 s[6:7], v115, v36
	s_and_b64 s[40:41], vcc, s[6:7]
	s_andn2_b64 s[6:7], s[26:27], exec
	s_and_b64 s[26:27], s[38:39], exec
	s_or_b64 s[26:27], s[6:7], s[26:27]
	s_or_b64 s[24:25], s[24:25], exec
	s_and_saveexec_b64 s[6:7], s[40:41]
	s_cbranch_execz .LBB0_720
	v_mov_b32_e32 v40, v1
	v_cmp_le_u32 vcc, v115, v79
	v_addc_co_u32 v40, vcc, 0, v40, vcc
	s_movk_i32 s40, 0x100
	v_cmp_le_u32 vcc, v115, v77
	v_addc_co_u32 v40, vcc, 0, v40, vcc
	s_mov_b64 s[44:45], -1
	v_cmp_le_u32 vcc, v115, v75
	v_addc_co_u32 v40, vcc, 0, v40, vcc
	s_mov_b64 s[42:43], -1
	v_cmp_le_u32 vcc, v115, v73
	v_addc_co_u32 v40, vcc, 0, v40, vcc
	v_cmp_le_u32 vcc, v115, v71
	v_addc_co_u32 v40, vcc, 0, v40, vcc
	v_cmp_le_u32 vcc, v115, v69
	v_addc_co_u32 v40, vcc, 0, v40, vcc
	v_cmp_le_u32 vcc, v115, v67
	v_addc_co_u32 v40, vcc, 0, v40, vcc
	v_cmp_le_u32 vcc, v115, v65
	v_addc_co_u32 v40, vcc, 0, v40, vcc
	v_cmp_le_u32 vcc, v115, v63
	v_addc_co_u32 v40, vcc, 0, v40, vcc
	v_cmp_le_u32 vcc, v115, v61
	v_addc_co_u32 v40, vcc, 0, v40, vcc
	v_cmp_le_u32 vcc, v115, v59
	v_addc_co_u32 v40, vcc, 0, v40, vcc
	v_cmp_le_u32 vcc, v115, v57
	v_addc_co_u32 v40, vcc, 0, v40, vcc
	v_cmp_le_u32 vcc, v115, v55
	v_addc_co_u32 v40, vcc, 0, v40, vcc
	v_cmp_le_u32 vcc, v115, v51
	v_addc_co_u32 v40, vcc, 0, v40, vcc
	v_cmp_le_u32 vcc, v115, v53
	v_addc_co_u32 v40, vcc, 0, v40, vcc
	v_cmp_le_u32 vcc, v115, v49
	v_addc_co_u32 v40, vcc, 0, v40, vcc
	v_cmp_le_u32 vcc, v115, v47
	v_addc_co_u32 v40, vcc, 0, v40, vcc
	v_cmp_le_u32 vcc, v115, v45
	v_addc_co_u32 v40, vcc, 0, v40, vcc
	v_cmp_le_u32 vcc, v115, v43
	v_addc_co_u32 v40, vcc, 0, v40, vcc
	v_cmp_le_u32 vcc, v115, v41
	v_addc_co_u32 v40, vcc, 0, v40, vcc
	v_cmp_le_u32 vcc, v115, v39
	v_addc_co_u32 v40, vcc, 0, v40, vcc
	v_cmp_le_u32 vcc, v115, v37
	v_addc_co_u32 v40, vcc, 0, v40, vcc
	v_cmp_le_u32 vcc, v115, v35
	v_addc_co_u32 v40, vcc, 0, v40, vcc
	v_cmp_le_u32 vcc, v115, v33
	v_addc_co_u32 v40, vcc, 0, v40, vcc
	v_cmp_le_u32 vcc, v115, v31
	v_addc_co_u32 v40, vcc, 0, v40, vcc
	v_cmp_le_u32 vcc, v115, v29
	v_addc_co_u32 v40, vcc, 0, v40, vcc
	v_cmp_le_u32 vcc, v115, v27
	v_addc_co_u32 v40, vcc, 0, v40, vcc
	v_cmp_le_u32 vcc, v115, v25
	v_addc_co_u32 v40, vcc, 0, v40, vcc
	v_cmp_le_u32 vcc, v115, v23
	v_addc_co_u32 v40, vcc, 0, v40, vcc
	v_cmp_le_u32 vcc, v115, v21
	v_addc_co_u32 v40, vcc, 0, v40, vcc
	v_cmp_le_u32 vcc, v115, v19
	v_addc_co_u32 v40, vcc, 0, v40, vcc
	v_cmp_le_u32 vcc, v115, v17
	v_addc_co_u32 v40, vcc, 0, v40, vcc
	v_cmp_le_u32 vcc, v115, v6
	v_addc_co_u32 v40, vcc, 0, v40, vcc
	v_cmp_le_u32 vcc, v115, v4
	v_addc_co_u32 v40, vcc, 0, v40, vcc
	v_cmp_le_u32 vcc, v115, v10
	v_addc_co_u32 v40, vcc, 0, v40, vcc
	v_cmp_le_u32 vcc, v115, v8
	v_addc_co_u32 v40, vcc, 0, v40, vcc
	v_cmp_le_u32 vcc, v115, v14
	v_addc_co_u32 v40, vcc, 0, v40, vcc
	v_cmp_le_u32 vcc, v115, v12
	v_addc_co_u32 v40, vcc, 0, v40, vcc
	v_cmp_le_u32 vcc, v115, v18
	v_addc_co_u32 v40, vcc, 0, v40, vcc
	v_cmp_le_u32 vcc, v115, v16
	v_addc_co_u32 v40, vcc, 0, v40, vcc
	v_cmp_le_u32 vcc, v115, v22
	v_addc_co_u32 v40, vcc, 0, v40, vcc
	v_cmp_le_u32 vcc, v115, v20
	v_addc_co_u32 v40, vcc, 0, v40, vcc
	v_cmp_le_u32 vcc, v115, v26
	v_addc_co_u32 v40, vcc, 0, v40, vcc
	v_cmp_le_u32 vcc, v115, v24
	v_addc_co_u32 v40, vcc, 0, v40, vcc
	v_cmp_le_u32 vcc, v115, v30
	v_addc_co_u32 v40, vcc, 0, v40, vcc
	v_cmp_le_u32 vcc, v115, v28
	v_addc_co_u32 v40, vcc, 0, v40, vcc
	v_cmp_le_u32 vcc, v115, v83
	v_addc_co_u32 v40, vcc, 0, v40, vcc
	v_cmp_le_u32 vcc, v115, v81
	v_addc_co_u32 v40, vcc, 0, v40, vcc
	v_cmp_le_u32 vcc, v115, v87
	v_addc_co_u32 v40, vcc, 0, v40, vcc
	v_cmp_le_u32 vcc, v115, v85
	v_addc_co_u32 v40, vcc, 0, v40, vcc
	v_cmp_le_u32 vcc, v115, v91
	v_addc_co_u32 v40, vcc, 0, v40, vcc
	v_cmp_le_u32 vcc, v115, v89
	v_addc_co_u32 v40, vcc, 0, v40, vcc
	v_cmp_le_u32 vcc, v115, v95
	v_addc_co_u32 v40, vcc, 0, v40, vcc
	v_cmp_le_u32 vcc, v115, v93
	v_addc_co_u32 v40, vcc, 0, v40, vcc
	v_cmp_le_u32 vcc, v115, v99
	v_addc_co_u32 v40, vcc, 0, v40, vcc
	v_cmp_le_u32 vcc, v115, v97
	v_addc_co_u32 v40, vcc, 0, v40, vcc
	v_cmp_le_u32 vcc, v115, v32
	v_addc_co_u32 v40, vcc, 0, v40, vcc
	v_cmp_le_u32 vcc, v115, v101
	v_addc_co_u32 v40, vcc, 0, v40, vcc
	v_cmp_le_u32 vcc, v115, v105
	v_addc_co_u32 v40, vcc, 0, v40, vcc
	v_cmp_le_u32 vcc, v115, v103
	v_addc_co_u32 v40, vcc, 0, v40, vcc
	v_cmp_le_u32 vcc, v115, v109
	v_addc_co_u32 v40, vcc, 0, v40, vcc
	v_cmp_le_u32 vcc, v115, v107
	v_addc_co_u32 v40, vcc, 0, v40, vcc
	v_cmp_le_u32 vcc, v115, v113
	v_addc_co_u32 v40, vcc, 0, v40, vcc
	v_cmp_le_u32 vcc, v115, v111
	v_addc_co_u32 v40, vcc, 0, v40, vcc
	s_nop 1
	v_add_u32_dpp v40, v40, v40 row_shr:1 row_mask:0xf bank_mask:0xf bound_ctrl:0
	s_nop 1
	v_add_u32_dpp v40, v40, v40 row_shr:2 row_mask:0xf bank_mask:0xf bound_ctrl:0
	s_nop 1
	v_add_u32_dpp v40, v40, v40 row_shr:4 row_mask:0xf bank_mask:0xf bound_ctrl:0
	s_nop 1
	v_add_u32_dpp v40, v40, v40 row_shr:8 row_mask:0xf bank_mask:0xf bound_ctrl:0
	s_nop 1
	v_add_u32_dpp v40, v40, v40 row_bcast:15 row_mask:0xa bank_mask:0xf
	s_nop 1
	v_add_u32_dpp v40, v40, v40 row_bcast:31 row_mask:0xc bank_mask:0xf
	s_nop 1
	v_readlane_b32 s98, v40, 63
	s_nop 1
	v_mov_b32_e32 v119, s98
	v_mov_b32_e32 v40, s98
	v_cmp_ne_u32_e32 vcc, s40, v119
	v_mov_b32_e32 v117, v115
	s_and_saveexec_b64 s[40:41], vcc
	s_cbranch_execz .LBB0_719
	s_movk_i32 s42, 0x101
	v_cmp_gt_i32_e32 vcc, s42, v119
	v_mov_b32_e32 v117, v115
	s_and_saveexec_b64 s[42:43], vcc
	s_cbranch_execz .LBB0_718
	v_subrev_co_u32_e32 v36, vcc, 0x800000, v115
	s_orn2_b64 s[44:45], vcc, exec
	s_nop 0
	v_cndmask_b32_e32 v117, v36, v115, vcc
	v_mov_b32_e32 v36, v115
	v_mov_b32_e32 v115, v0
	s_branch .LBB0_718

; template <int NJ>
; DI void select_row(const float* row, int n, u64* bmrow, int lane) {
;     ...
;     unsigned cand = km & 0xff800000u;
; #pragma unroll 1
;     for (int pr = 0; pr < 4; ++pr) {
;       if (cand <= lo || cand >= hi) break;
;       int c = 0;
; #pragma unroll
;       for (int jj = 0; jj < NJ; ++jj)
;         asm volatile("v_cmp_le_u32 vcc, %1, %2\n\tv_addc_co_u32 %0, vcc, 0, %0, vcc" : "+v"(c) : "s"(cand), "v"(key[jj]) : "vcc");
;       c = wave_sum_i(c, lane);
;       if (c == 256) { T = cand; exact = true; break; }
;       if (c > 256) { lo = cand; break; }
;       hi = cand;
;       if (cand < 0x00800000u) break;
;       cand -= 0x00800000u;
;     }
;   }
.LBB0_787:
	v_cmp_gt_u32_e32 vcc, v51, v45
	v_cmp_lt_u32_e64 s[6:7], v51, v38
	s_and_b64 s[38:39], vcc, s[6:7]
	s_andn2_b64 s[6:7], s[24:25], exec
	s_and_b64 s[24:25], s[26:27], exec
	s_or_b64 s[24:25], s[6:7], s[24:25]
	s_or_b64 s[22:23], s[22:23], exec
	s_and_saveexec_b64 s[6:7], s[38:39]
	s_cbranch_execz .LBB0_786
	v_mov_b32_e32 v40, v1
	v_cmp_le_u32 vcc, v51, v43
	v_addc_co_u32 v40, vcc, 0, v40, vcc
	s_movk_i32 s38, 0x100
	v_cmp_le_u32 vcc, v51, v41
	v_addc_co_u32 v40, vcc, 0, v40, vcc
	s_mov_b64 s[42:43], -1
	v_cmp_le_u32 vcc, v51, v39
	v_addc_co_u32 v40, vcc, 0, v40, vcc
	s_mov_b64 s[40:41], -1
	v_cmp_le_u32 vcc, v51, v0
	v_addc_co_u32 v40, vcc, 0, v40, vcc
	v_cmp_le_u32 vcc, v51, v6
	v_addc_co_u32 v40, vcc, 0, v40, vcc
	v_cmp_le_u32 vcc, v51, v4
	v_addc_co_u32 v40, vcc, 0, v40, vcc
	v_cmp_le_u32 vcc, v51, v10
	v_addc_co_u32 v40, vcc, 0, v40, vcc
	v_cmp_le_u32 vcc, v51, v8
	v_addc_co_u32 v40, vcc, 0, v40, vcc
	v_cmp_le_u32 vcc, v51, v14
	v_addc_co_u32 v40, vcc, 0, v40, vcc
	v_cmp_le_u32 vcc, v51, v12
	v_addc_co_u32 v40, vcc, 0, v40, vcc
	v_cmp_le_u32 vcc, v51, v17
	v_addc_co_u32 v40, vcc, 0, v40, vcc
	v_cmp_le_u32 vcc, v51, v16
	v_addc_co_u32 v40, vcc, 0, v40, vcc
	v_cmp_le_u32 vcc, v51, v19
	v_addc_co_u32 v40, vcc, 0, v40, vcc
	v_cmp_le_u32 vcc, v51, v18
	v_addc_co_u32 v40, vcc, 0, v40, vcc
	v_cmp_le_u32 vcc, v51, v21
	v_addc_co_u32 v40, vcc, 0, v40, vcc
	v_cmp_le_u32 vcc, v51, v20
	v_addc_co_u32 v40, vcc, 0, v40, vcc
	v_cmp_le_u32 vcc, v51, v23
	v_addc_co_u32 v40, vcc, 0, v40, vcc
	v_cmp_le_u32 vcc, v51, v22
	v_addc_co_u32 v40, vcc, 0, v40, vcc
	v_cmp_le_u32 vcc, v51, v25
	v_addc_co_u32 v40, vcc, 0, v40, vcc
	v_cmp_le_u32 vcc, v51, v24
	v_addc_co_u32 v40, vcc, 0, v40, vcc
	v_cmp_le_u32 vcc, v51, v27
	v_addc_co_u32 v40, vcc, 0, v40, vcc
	v_cmp_le_u32 vcc, v51, v26
	v_addc_co_u32 v40, vcc, 0, v40, vcc
	v_cmp_le_u32 vcc, v51, v29
	v_addc_co_u32 v40, vcc, 0, v40, vcc
	v_cmp_le_u32 vcc, v51, v28
	v_addc_co_u32 v40, vcc, 0, v40, vcc
	v_cmp_le_u32 vcc, v51, v31
	v_addc_co_u32 v40, vcc, 0, v40, vcc
	v_cmp_le_u32 vcc, v51, v30
	v_addc_co_u32 v40, vcc, 0, v40, vcc
	v_cmp_le_u32 vcc, v51, v33
	v_addc_co_u32 v40, vcc, 0, v40, vcc
	v_cmp_le_u32 vcc, v51, v32
	v_addc_co_u32 v40, vcc, 0, v40, vcc
	v_cmp_le_u32 vcc, v51, v35
	v_addc_co_u32 v40, vcc, 0, v40, vcc
	v_cmp_le_u32 vcc, v51, v34
	v_addc_co_u32 v40, vcc, 0, v40, vcc
	v_cmp_le_u32 vcc, v51, v37
	v_addc_co_u32 v40, vcc, 0, v40, vcc
	v_cmp_le_u32 vcc, v51, v36
	v_addc_co_u32 v40, vcc, 0, v40, vcc
	s_nop 1
	v_add_u32_dpp v40, v40, v40 row_shr:1 row_mask:0xf bank_mask:0xf bound_ctrl:0
	s_nop 1
	v_add_u32_dpp v40, v40, v40 row_shr:2 row_mask:0xf bank_mask:0xf bound_ctrl:0
	s_nop 1
	v_add_u32_dpp v40, v40, v40 row_shr:4 row_mask:0xf bank_mask:0xf bound_ctrl:0
	s_nop 1
	v_add_u32_dpp v40, v40, v40 row_shr:8 row_mask:0xf bank_mask:0xf bound_ctrl:0
	s_nop 1
	v_add_u32_dpp v40, v40, v40 row_bcast:15 row_mask:0xa bank_mask:0xf
	s_nop 1
	v_add_u32_dpp v40, v40, v40 row_bcast:31 row_mask:0xc bank_mask:0xf
	s_nop 1
	v_readlane_b32 s98, v40, 63
	s_nop 1
	v_mov_b32_e32 v55, s98
	v_mov_b32_e32 v40, s98
	v_cmp_ne_u32_e32 vcc, s38, v55
	v_mov_b32_e32 v53, v51
	s_and_saveexec_b64 s[38:39], vcc
	s_cbranch_execz .LBB0_785
	s_movk_i32 s40, 0x101
	v_cmp_gt_i32_e32 vcc, s40, v55
	v_mov_b32_e32 v53, v51
	s_and_saveexec_b64 s[40:41], vcc
	s_cbranch_execz .LBB0_784
	v_subrev_co_u32_e32 v38, vcc, 0x800000, v51
	s_orn2_b64 s[42:43], vcc, exec
	s_nop 0
	v_cndmask_b32_e32 v53, v38, v51, vcc
	v_mov_b32_e32 v38, v51
	v_mov_b32_e32 v51, v45
	s_branch .LBB0_784

; template <int NJ>
; DI void select_row(const float* row, int n, u64* bmrow, int lane) {
;     ...
; #pragma unroll 1
;   while (!exact && hi - lo > 1u) {
;     const unsigned cand = lo + ((hi - lo) >> 1);
;     int c = 0;
; #pragma unroll
;     for (int jj = 0; jj < NJ; ++jj)
;       asm volatile("v_cmp_le_u32 vcc, %1, %2\n\tv_addc_co_u32 %0, vcc, 0, %0, vcc" : "+v"(c) : "s"(cand), "v"(key[jj]) : "vcc");
;     c = wave_sum_i(c, lane);
;     if (c == 256) { T = cand; exact = true; }
;     else if (c > 256) lo = cand; else hi = cand;
;   }
;   if (!exact) T = lo;
;   unsigned X = 0xffffffffu;
;   if (!exact) {
;     int cgt = 0, ceq = 0;
; #pragma unroll
;     for (int jj = 0; jj < NJ; ++jj) {
;       asm volatile("v_cmp_lt_u32 vcc, %1, %2\n\tv_addc_co_u32 %0, vcc, 0, %0, vcc" : "+v"(cgt) : "s"(T), "v"(key[jj]) : "vcc");
;       asm volatile("v_cmp_eq_u32 vcc, %1, %2\n\tv_addc_co_u32 %0, vcc, 0, %0, vcc" : "+v"(ceq) : "s"(T), "v"(key[jj]) : "vcc");
;     }
.LBB0_793:
	v_lshrrev_b32_e32 v40, 1, v49
	v_mov_b32_e32 v49, v1
	v_add_u32_e32 v40, v45, v40
	v_cmp_le_u32 vcc, v40, v43
	v_addc_co_u32 v49, vcc, 0, v49, vcc
	v_cmp_le_u32 vcc, v40, v41
	v_addc_co_u32 v49, vcc, 0, v49, vcc
	v_cmp_le_u32 vcc, v40, v39
	v_addc_co_u32 v49, vcc, 0, v49, vcc
	v_cmp_le_u32 vcc, v40, v0
	v_addc_co_u32 v49, vcc, 0, v49, vcc
	v_cmp_le_u32 vcc, v40, v6
	v_addc_co_u32 v49, vcc, 0, v49, vcc
	v_cmp_le_u32 vcc, v40, v4
	v_addc_co_u32 v49, vcc, 0, v49, vcc
	v_cmp_le_u32 vcc, v40, v10
	v_addc_co_u32 v49, vcc, 0, v49, vcc
	v_cmp_le_u32 vcc, v40, v8
	v_addc_co_u32 v49, vcc, 0, v49, vcc
	v_cmp_le_u32 vcc, v40, v14
	v_addc_co_u32 v49, vcc, 0, v49, vcc
	v_cmp_le_u32 vcc, v40, v12
	v_addc_co_u32 v49, vcc, 0, v49, vcc
	v_cmp_le_u32 vcc, v40, v17
	v_addc_co_u32 v49, vcc, 0, v49, vcc
	v_cmp_le_u32 vcc, v40, v16
	v_addc_co_u32 v49, vcc, 0, v49, vcc
	v_cmp_le_u32 vcc, v40, v19
	v_addc_co_u32 v49, vcc, 0, v49, vcc
	v_cmp_le_u32 vcc, v40, v18
	v_addc_co_u32 v49, vcc, 0, v49, vcc
	v_cmp_le_u32 vcc, v40, v21
	v_addc_co_u32 v49, vcc, 0, v49, vcc
	v_cmp_le_u32 vcc, v40, v20
	v_addc_co_u32 v49, vcc, 0, v49, vcc
	v_cmp_le_u32 vcc, v40, v23
	v_addc_co_u32 v49, vcc, 0, v49, vcc
	v_cmp_le_u32 vcc, v40, v22
	v_addc_co_u32 v49, vcc, 0, v49, vcc
	v_cmp_le_u32 vcc, v40, v25
	v_addc_co_u32 v49, vcc, 0, v49, vcc
	v_cmp_le_u32 vcc, v40, v24
	v_addc_co_u32 v49, vcc, 0, v49, vcc
	v_cmp_le_u32 vcc, v40, v27
	v_addc_co_u32 v49, vcc, 0, v49, vcc
	v_cmp_le_u32 vcc, v40, v26
	v_addc_co_u32 v49, vcc, 0, v49, vcc
	v_cmp_le_u32 vcc, v40, v29
	v_addc_co_u32 v49, vcc, 0, v49, vcc
	v_cmp_le_u32 vcc, v40, v28
	v_addc_co_u32 v49, vcc, 0, v49, vcc
	v_cmp_le_u32 vcc, v40, v31
	v_addc_co_u32 v49, vcc, 0, v49, vcc
	v_cmp_le_u32 vcc, v40, v30
	v_addc_co_u32 v49, vcc, 0, v49, vcc
	v_cmp_le_u32 vcc, v40, v33
	v_addc_co_u32 v49, vcc, 0, v49, vcc
	v_cmp_le_u32 vcc, v40, v32
	v_addc_co_u32 v49, vcc, 0, v49, vcc
	v_cmp_le_u32 vcc, v40, v35
	v_addc_co_u32 v49, vcc, 0, v49, vcc
	v_cmp_le_u32 vcc, v40, v34
	v_addc_co_u32 v49, vcc, 0, v49, vcc
	v_cmp_le_u32 vcc, v40, v37
	v_addc_co_u32 v49, vcc, 0, v49, vcc
	v_cmp_le_u32 vcc, v40, v36
	v_addc_co_u32 v49, vcc, 0, v49, vcc
	s_nop 1
	v_add_u32_dpp v49, v49, v49 row_shr:1 row_mask:0xf bank_mask:0xf bound_ctrl:0
	s_nop 1
	v_add_u32_dpp v49, v49, v49 row_shr:2 row_mask:0xf bank_mask:0xf bound_ctrl:0
	s_nop 1
	v_add_u32_dpp v49, v49, v49 row_shr:4 row_mask:0xf bank_mask:0xf bound_ctrl:0
	s_nop 1
	v_add_u32_dpp v49, v49, v49 row_shr:8 row_mask:0xf bank_mask:0xf bound_ctrl:0
	s_nop 1
	v_add_u32_dpp v49, v49, v49 row_bcast:15 row_mask:0xa bank_mask:0xf
	s_nop 1
	v_add_u32_dpp v49, v49, v49 row_bcast:31 row_mask:0xc bank_mask:0xf
	s_nop 1
	v_readlane_b32 s98, v49, 63
	s_nop 1
	v_mov_b32_e32 v49, s98
	v_cmp_lt_i32_e32 vcc, s26, v49
	s_nop 1
	v_cndmask_b32_e32 v51, v45, v40, vcc
	v_cmp_lt_i32_e32 vcc, s27, v49
	s_nop 1
	v_cndmask_b32_e32 v38, v40, v38, vcc
	v_cmp_eq_u32_e32 vcc, s26, v49
	s_nop 1
	v_cndmask_b32_e32 v45, v51, v45, vcc
	v_sub_u32_e32 v49, v38, v45
	v_cmp_gt_u32_e64 s[6:7], 2, v49
	s_or_b64 s[6:7], vcc, s[6:7]
	s_and_b64 s[6:7], exec, s[6:7]
	s_or_b64 s[22:23], s[6:7], s[22:23]
	s_andn2_b64 s[6:7], s[24:25], exec
	s_and_b64 s[24:25], vcc, exec
	v_cndmask_b32_e32 v47, v47, v40, vcc
	s_or_b64 s[24:25], s[6:7], s[24:25]
	s_andn2_b64 exec, exec, s[22:23]
	s_cbranch_execnz .LBB0_793
	s_or_b64 exec, exec, s[22:23]
	s_andn2_b64 s[6:7], s[18:19], exec
	s_and_b64 s[18:19], s[24:25], exec
	s_or_b64 s[18:19], s[6:7], s[18:19]
.LBB0_795:
	s_or_b64 exec, exec, s[20:21]
	s_xor_b64 s[18:19], s[18:19], -1
	v_mov_b32_e32 v38, -1
	s_and_saveexec_b64 s[6:7], s[18:19]
	s_cbranch_execz .LBB0_800
	v_mov_b32_e32 v38, v1
	v_cmp_lt_u32 vcc, v45, v43
	v_addc_co_u32 v38, vcc, 0, v38, vcc
	v_mov_b32_e32 v40, v1
	v_cmp_eq_u32 vcc, v45, v43
	v_addc_co_u32 v40, vcc, 0, v40, vcc
	v_cmp_lt_u32 vcc, v45, v41
	v_addc_co_u32 v38, vcc, 0, v38, vcc
	v_cmp_eq_u32 vcc, v45, v41
	v_addc_co_u32 v40, vcc, 0, v40, vcc
	v_cmp_lt_u32 vcc, v45, v39
	v_addc_co_u32 v38, vcc, 0, v38, vcc
	v_cmp_eq_u32 vcc, v45, v39
	v_addc_co_u32 v40, vcc, 0, v40, vcc
	v_cmp_lt_u32 vcc, v45, v0
	v_addc_co_u32 v38, vcc, 0, v38, vcc
	v_cmp_eq_u32 vcc, v45, v0
	v_addc_co_u32 v40, vcc, 0, v40, vcc
	v_cmp_lt_u32 vcc, v45, v6
	v_addc_co_u32 v38, vcc, 0, v38, vcc
	v_cmp_eq_u32 vcc, v45, v6
	v_addc_co_u32 v40, vcc, 0, v40, vcc
	v_cmp_lt_u32 vcc, v45, v4
	v_addc_co_u32 v38, vcc, 0, v38, vcc
	v_cmp_eq_u32 vcc, v45, v4
	v_addc_co_u32 v40, vcc, 0, v40, vcc
	v_cmp_lt_u32 vcc, v45, v10
	v_addc_co_u32 v38, vcc, 0, v38, vcc
	v_cmp_eq_u32 vcc, v45, v10
	v_addc_co_u32 v40, vcc, 0, v40, vcc
	v_cmp_lt_u32 vcc, v45, v8
	v_addc_co_u32 v38, vcc, 0, v38, vcc
	v_cmp_eq_u32 vcc, v45, v8
	v_addc_co_u32 v40, vcc, 0, v40, vcc
	v_cmp_lt_u32 vcc, v45, v14
	v_addc_co_u32 v38, vcc, 0, v38, vcc
	v_cmp_eq_u32 vcc, v45, v14
	v_addc_co_u32 v40, vcc, 0, v40, vcc
	v_cmp_lt_u32 vcc, v45, v12
	v_addc_co_u32 v38, vcc, 0, v38, vcc
	v_cmp_eq_u32 vcc, v45, v12
	v_addc_co_u32 v40, vcc, 0, v40, vcc
	v_cmp_lt_u32 vcc, v45, v17
	v_addc_co_u32 v38, vcc, 0, v38, vcc
	v_cmp_eq_u32 vcc, v45, v17
	v_addc_co_u32 v40, vcc, 0, v40, vcc
	v_cmp_lt_u32 vcc, v45, v16
	v_addc_co_u32 v38, vcc, 0, v38, vcc
	v_cmp_eq_u32 vcc, v45, v16
	v_addc_co_u32 v40, vcc, 0, v40, vcc
	v_cmp_lt_u32 vcc, v45, v19
	v_addc_co_u32 v38, vcc, 0, v38, vcc
	v_cmp_eq_u32 vcc, v45, v19
	v_addc_co_u32 v40, vcc, 0, v40, vcc
	v_cmp_lt_u32 vcc, v45, v18
	v_addc_co_u32 v38, vcc, 0, v38, vcc
	v_cmp_eq_u32 vcc, v45, v18
	v_addc_co_u32 v40, vcc, 0, v40, vcc
	v_cmp_lt_u32 vcc, v45, v21
	v_addc_co_u32 v38, vcc, 0, v38, vcc
	v_cmp_eq_u32 vcc, v45, v21
	v_addc_co_u32 v40, vcc, 0, v40, vcc
; template <int NJ>
; DI void select_row(const float* row, int n, u64* bmrow, int lane) {
;     ...
;   unsigned X = 0xffffffffu;
;   if (!exact) {
;     int cgt = 0, ceq = 0;
; #pragma unroll
;     for (int jj = 0; jj < NJ; ++jj) {
;       asm volatile("v_cmp_lt_u32 vcc, %1, %2\n\tv_addc_co_u32 %0, vcc, 0, %0, vcc" : "+v"(cgt) : "s"(T), "v"(key[jj]) : "vcc");
;       asm volatile("v_cmp_eq_u32 vcc, %1, %2\n\tv_addc_co_u32 %0, vcc, 0, %0, vcc" : "+v"(ceq) : "s"(T), "v"(key[jj]) : "vcc");
;     }
;     cgt = wave_sum_i(cgt, lane); ceq = wave_sum_i(ceq, lane);
;     const int need = 256 - cgt;
;     unsigned bigv = 0x7fffffffu;
;     asm volatile("" : "+v"(bigv));
;     if (ceq != need) {
;       X = 0;
; #pragma unroll 1
;     ...
;         const unsigned cand = X | (1u << bit);
	v_cmp_lt_u32 vcc, v45, v20
	v_addc_co_u32 v38, vcc, 0, v38, vcc
	v_cmp_eq_u32 vcc, v45, v20
	v_addc_co_u32 v40, vcc, 0, v40, vcc
	v_cmp_lt_u32 vcc, v45, v23
	v_addc_co_u32 v38, vcc, 0, v38, vcc
	v_cmp_eq_u32 vcc, v45, v23
	v_addc_co_u32 v40, vcc, 0, v40, vcc
	v_cmp_lt_u32 vcc, v45, v22
	v_addc_co_u32 v38, vcc, 0, v38, vcc
	v_cmp_eq_u32 vcc, v45, v22
	v_addc_co_u32 v40, vcc, 0, v40, vcc
	v_cmp_lt_u32 vcc, v45, v25
	v_addc_co_u32 v38, vcc, 0, v38, vcc
	v_cmp_eq_u32 vcc, v45, v25
	v_addc_co_u32 v40, vcc, 0, v40, vcc
	v_cmp_lt_u32 vcc, v45, v24
	v_addc_co_u32 v38, vcc, 0, v38, vcc
	v_cmp_eq_u32 vcc, v45, v24
	v_addc_co_u32 v40, vcc, 0, v40, vcc
	v_cmp_lt_u32 vcc, v45, v27
	v_addc_co_u32 v38, vcc, 0, v38, vcc
	v_cmp_eq_u32 vcc, v45, v27
	v_addc_co_u32 v40, vcc, 0, v40, vcc
	v_cmp_lt_u32 vcc, v45, v26
	v_addc_co_u32 v38, vcc, 0, v38, vcc
	v_cmp_eq_u32 vcc, v45, v26
	v_addc_co_u32 v40, vcc, 0, v40, vcc
	v_cmp_lt_u32 vcc, v45, v29
	v_addc_co_u32 v38, vcc, 0, v38, vcc
	v_cmp_eq_u32 vcc, v45, v29
	v_addc_co_u32 v40, vcc, 0, v40, vcc
	v_cmp_lt_u32 vcc, v45, v28
	v_addc_co_u32 v38, vcc, 0, v38, vcc
	v_cmp_eq_u32 vcc, v45, v28
	v_addc_co_u32 v40, vcc, 0, v40, vcc
	v_cmp_lt_u32 vcc, v45, v31
	v_addc_co_u32 v38, vcc, 0, v38, vcc
	v_cmp_eq_u32 vcc, v45, v31
	v_addc_co_u32 v40, vcc, 0, v40, vcc
	v_cmp_lt_u32 vcc, v45, v30
	v_addc_co_u32 v38, vcc, 0, v38, vcc
	v_cmp_eq_u32 vcc, v45, v30
	v_addc_co_u32 v40, vcc, 0, v40, vcc
	v_cmp_lt_u32 vcc, v45, v33
	v_addc_co_u32 v38, vcc, 0, v38, vcc
	v_cmp_eq_u32 vcc, v45, v33
	v_addc_co_u32 v40, vcc, 0, v40, vcc
	v_cmp_lt_u32 vcc, v45, v32
	v_addc_co_u32 v38, vcc, 0, v38, vcc
	v_cmp_eq_u32 vcc, v45, v32
	v_addc_co_u32 v40, vcc, 0, v40, vcc
	v_cmp_lt_u32 vcc, v45, v35
	v_addc_co_u32 v38, vcc, 0, v38, vcc
	v_cmp_eq_u32 vcc, v45, v35
	v_addc_co_u32 v40, vcc, 0, v40, vcc
	v_cmp_lt_u32 vcc, v45, v34
	v_addc_co_u32 v38, vcc, 0, v38, vcc
	v_cmp_eq_u32 vcc, v45, v34
	v_addc_co_u32 v40, vcc, 0, v40, vcc
	v_cmp_lt_u32 vcc, v45, v37
	v_addc_co_u32 v38, vcc, 0, v38, vcc
	v_cmp_eq_u32 vcc, v45, v37
	v_addc_co_u32 v40, vcc, 0, v40, vcc
	v_cmp_lt_u32 vcc, v45, v36
	v_addc_co_u32 v38, vcc, 0, v38, vcc
	ds_bpermute_b32 v47, v5, v38
	v_cmp_eq_u32 vcc, v45, v36
	v_addc_co_u32 v40, vcc, 0, v40, vcc
	ds_bpermute_b32 v49, v5, v40
	s_waitcnt lgkmcnt(1)
	v_add_u32_e32 v38, v47, v38
	ds_bpermute_b32 v47, v7, v38
	s_waitcnt lgkmcnt(1)
	v_add_u32_e32 v40, v49, v40
	ds_bpermute_b32 v49, v7, v40
	s_waitcnt lgkmcnt(1)
	v_add_u32_e32 v38, v47, v38
	ds_bpermute_b32 v47, v9, v38
	s_waitcnt lgkmcnt(1)
	v_add_u32_e32 v40, v49, v40
	ds_bpermute_b32 v49, v9, v40
	s_waitcnt lgkmcnt(1)
	v_add_u32_e32 v38, v47, v38
	ds_bpermute_b32 v47, v11, v38
	s_waitcnt lgkmcnt(1)
	v_add_u32_e32 v40, v49, v40
	ds_bpermute_b32 v49, v11, v40
	s_waitcnt lgkmcnt(1)
	v_add_u32_e32 v38, v47, v38
	ds_bpermute_b32 v47, v13, v38
	s_waitcnt lgkmcnt(1)
	v_add_u32_e32 v40, v49, v40
	ds_bpermute_b32 v49, v13, v40
	s_waitcnt lgkmcnt(1)
	v_add_u32_e32 v38, v47, v38
	s_waitcnt lgkmcnt(0)
	v_add_u32_e32 v40, v49, v40
	ds_bpermute_b32 v49, v15, v38
	ds_bpermute_b32 v47, v15, v40
	s_waitcnt lgkmcnt(1)
	v_add_u32_e32 v38, v49, v38
	s_waitcnt lgkmcnt(0)
	v_add_u32_e32 v40, v47, v40
	v_sub_u32_e32 v47, 0x100, v38
	v_bfrev_b32_e32 v49, -2
	v_cmp_ne_u32_e32 vcc, v40, v47
	v_mov_b32_e32 v38, -1
	s_and_saveexec_b64 s[18:19], vcc
	s_cbranch_execz .LBB0_799
	v_mov_b32_e32 v38, 0
	s_mov_b32 s20, 13
; template <int NJ>
; DI void select_row(const float* row, int n, u64* bmrow, int lane) {
;     ...
; #pragma unroll 1
;     ...
;         const unsigned cand = X | (1u << bit);
;         int c = 0;
; #pragma unroll
;         for (int jj = 0; jj < NJ; ++jj) {
;           unsigned tmp;
;           asm volatile("v_add_u32 %1, %7, %5\n\tv_cmp_eq_u32 vcc, %2, %3\n\tv_cndmask_b32 %1, %4, %1, vcc\n\tv_cmp_gt_u32 vcc, %6, %1\n\tv_addc_co_u32 %0, vcc, 0, %0, vcc"
;                        : "+v"(c), "=&v"(tmp) : "s"(T), "v"(key[jj]), "v"(bigv), "v"(lane), "s"(cand), "n"(jj * 64) : "vcc");
;         }
;         c = wave_sum_i(c, lane);
;         if (c <= need) X = cand;
;       }
;     }
.LBB0_798:
	v_mov_b32_e32 v51, v1
	v_lshl_or_b32 v40, 1, s20, v38
	v_add_u32 v53, 0, v2
	v_cmp_eq_u32 vcc, v45, v43
	v_cndmask_b32 v53, v49, v53, vcc
	v_cmp_gt_u32 vcc, v40, v53
	v_addc_co_u32 v51, vcc, 0, v51, vcc
	s_add_i32 s20, s20, -1
	v_add_u32 v53, 64, v2
	v_cmp_eq_u32 vcc, v45, v41
	v_cndmask_b32 v53, v49, v53, vcc
	v_cmp_gt_u32 vcc, v40, v53
	v_addc_co_u32 v51, vcc, 0, v51, vcc
	s_cmp_lg_u32 s20, -1
	v_add_u32 v53, 0x80, v2
	v_cmp_eq_u32 vcc, v45, v39
	v_cndmask_b32 v53, v49, v53, vcc
	v_cmp_gt_u32 vcc, v40, v53
	v_addc_co_u32 v51, vcc, 0, v51, vcc
	v_add_u32 v53, 0xc0, v2
	v_cmp_eq_u32 vcc, v45, v0
	v_cndmask_b32 v53, v49, v53, vcc
	v_cmp_gt_u32 vcc, v40, v53
	v_addc_co_u32 v51, vcc, 0, v51, vcc
	v_add_u32 v53, 0x100, v2
	v_cmp_eq_u32 vcc, v45, v6
	v_cndmask_b32 v53, v49, v53, vcc
	v_cmp_gt_u32 vcc, v40, v53
	v_addc_co_u32 v51, vcc, 0, v51, vcc
	v_add_u32 v53, 0x140, v2
	v_cmp_eq_u32 vcc, v45, v4
	v_cndmask_b32 v53, v49, v53, vcc
	v_cmp_gt_u32 vcc, v40, v53
	v_addc_co_u32 v51, vcc, 0, v51, vcc
	v_add_u32 v53, 0x180, v2
	v_cmp_eq_u32 vcc, v45, v10
	v_cndmask_b32 v53, v49, v53, vcc
	v_cmp_gt_u32 vcc, v40, v53
	v_addc_co_u32 v51, vcc, 0, v51, vcc
	v_add_u32 v53, 0x1c0, v2
	v_cmp_eq_u32 vcc, v45, v8
	v_cndmask_b32 v53, v49, v53, vcc
	v_cmp_gt_u32 vcc, v40, v53
	v_addc_co_u32 v51, vcc, 0, v51, vcc
	v_add_u32 v53, 0x200, v2
	v_cmp_eq_u32 vcc, v45, v14
	v_cndmask_b32 v53, v49, v53, vcc
	v_cmp_gt_u32 vcc, v40, v53
	v_addc_co_u32 v51, vcc, 0, v51, vcc
	v_add_u32 v53, 0x240, v2
	v_cmp_eq_u32 vcc, v45, v12
	v_cndmask_b32 v53, v49, v53, vcc
	v_cmp_gt_u32 vcc, v40, v53
	v_addc_co_u32 v51, vcc, 0, v51, vcc
	v_add_u32 v53, 0x280, v2
	v_cmp_eq_u32 vcc, v45, v17
	v_cndmask_b32 v53, v49, v53, vcc
	v_cmp_gt_u32 vcc, v40, v53
	v_addc_co_u32 v51, vcc, 0, v51, vcc
	v_add_u32 v53, 0x2c0, v2
	v_cmp_eq_u32 vcc, v45, v16
	v_cndmask_b32 v53, v49, v53, vcc
	v_cmp_gt_u32 vcc, v40, v53
	v_addc_co_u32 v51, vcc, 0, v51, vcc
	v_add_u32 v53, 0x300, v2
	v_cmp_eq_u32 vcc, v45, v19
	v_cndmask_b32 v53, v49, v53, vcc
	v_cmp_gt_u32 vcc, v40, v53
	v_addc_co_u32 v51, vcc, 0, v51, vcc
	v_add_u32 v53, 0x340, v2
	v_cmp_eq_u32 vcc, v45, v18
	v_cndmask_b32 v53, v49, v53, vcc
	v_cmp_gt_u32 vcc, v40, v53
	v_addc_co_u32 v51, vcc, 0, v51, vcc
	v_add_u32 v53, 0x380, v2
	v_cmp_eq_u32 vcc, v45, v21
	v_cndmask_b32 v53, v49, v53, vcc
	v_cmp_gt_u32 vcc, v40, v53
	v_addc_co_u32 v51, vcc, 0, v51, vcc
	v_add_u32 v53, 0x3c0, v2
	v_cmp_eq_u32 vcc, v45, v20
	v_cndmask_b32 v53, v49, v53, vcc
	v_cmp_gt_u32 vcc, v40, v53
	v_addc_co_u32 v51, vcc, 0, v51, vcc
	v_add_u32 v53, 0x400, v2
	v_cmp_eq_u32 vcc, v45, v23
	v_cndmask_b32 v53, v49, v53, vcc
	v_cmp_gt_u32 vcc, v40, v53
	v_addc_co_u32 v51, vcc, 0, v51, vcc
	v_add_u32 v53, 0x440, v2
	v_cmp_eq_u32 vcc, v45, v22
	v_cndmask_b32 v53, v49, v53, vcc
	v_cmp_gt_u32 vcc, v40, v53
	v_addc_co_u32 v51, vcc, 0, v51, vcc
	v_add_u32 v53, 0x480, v2
	v_cmp_eq_u32 vcc, v45, v25
	v_cndmask_b32 v53, v49, v53, vcc
	v_cmp_gt_u32 vcc, v40, v53
	v_addc_co_u32 v51, vcc, 0, v51, vcc
	v_add_u32 v53, 0x4c0, v2
	v_cmp_eq_u32 vcc, v45, v24
	v_cndmask_b32 v53, v49, v53, vcc
	v_cmp_gt_u32 vcc, v40, v53
	v_addc_co_u32 v51, vcc, 0, v51, vcc
	v_add_u32 v53, 0x500, v2
	v_cmp_eq_u32 vcc, v45, v27
	v_cndmask_b32 v53, v49, v53, vcc
	v_cmp_gt_u32 vcc, v40, v53
	v_addc_co_u32 v51, vcc, 0, v51, vcc
	v_add_u32 v53, 0x540, v2
	v_cmp_eq_u32 vcc, v45, v26
	v_cndmask_b32 v53, v49, v53, vcc
	v_cmp_gt_u32 vcc, v40, v53
	v_addc_co_u32 v51, vcc, 0, v51, vcc
	v_add_u32 v53, 0x580, v2
	v_cmp_eq_u32 vcc, v45, v29
	v_cndmask_b32 v53, v49, v53, vcc
	v_cmp_gt_u32 vcc, v40, v53
	v_addc_co_u32 v51, vcc, 0, v51, vcc
	v_add_u32 v53, 0x5c0, v2
	v_cmp_eq_u32 vcc, v45, v28
	v_cndmask_b32 v53, v49, v53, vcc
	v_cmp_gt_u32 vcc, v40, v53
	v_addc_co_u32 v51, vcc, 0, v51, vcc
	v_add_u32 v53, 0x600, v2
	v_cmp_eq_u32 vcc, v45, v31
	v_cndmask_b32 v53, v49, v53, vcc
	v_cmp_gt_u32 vcc, v40, v53
	v_addc_co_u32 v51, vcc, 0, v51, vcc
	v_add_u32 v53, 0x640, v2
	v_cmp_eq_u32 vcc, v45, v30
	v_cndmask_b32 v53, v49, v53, vcc
	v_cmp_gt_u32 vcc, v40, v53
	v_addc_co_u32 v51, vcc, 0, v51, vcc
	v_add_u32 v53, 0x680, v2
	v_cmp_eq_u32 vcc, v45, v33
	v_cndmask_b32 v53, v49, v53, vcc
	v_cmp_gt_u32 vcc, v40, v53
	v_addc_co_u32 v51, vcc, 0, v51, vcc
	v_add_u32 v53, 0x6c0, v2
	v_cmp_eq_u32 vcc, v45, v32
	v_cndmask_b32 v53, v49, v53, vcc
	v_cmp_gt_u32 vcc, v40, v53
	v_addc_co_u32 v51, vcc, 0, v51, vcc
	v_add_u32 v53, 0x700, v2
	v_cmp_eq_u32 vcc, v45, v35
	v_cndmask_b32 v53, v49, v53, vcc
	v_cmp_gt_u32 vcc, v40, v53
	v_addc_co_u32 v51, vcc, 0, v51, vcc
	v_add_u32 v53, 0x740, v2
	v_cmp_eq_u32 vcc, v45, v34
	v_cndmask_b32 v53, v49, v53, vcc
	v_cmp_gt_u32 vcc, v40, v53
	v_addc_co_u32 v51, vcc, 0, v51, vcc
	v_add_u32 v53, 0x780, v2
	v_cmp_eq_u32 vcc, v45, v37
	v_cndmask_b32 v53, v49, v53, vcc
	v_cmp_gt_u32 vcc, v40, v53
	v_addc_co_u32 v51, vcc, 0, v51, vcc
	v_add_u32 v53, 0x7c0, v2
	v_cmp_eq_u32 vcc, v45, v36
	v_cndmask_b32 v53, v49, v53, vcc
	v_cmp_gt_u32 vcc, v40, v53
	v_addc_co_u32 v51, vcc, 0, v51, vcc
	s_nop 1
	v_add_u32_dpp v51, v51, v51 row_shr:1 row_mask:0xf bank_mask:0xf bound_ctrl:0
	s_nop 1
	v_add_u32_dpp v51, v51, v51 row_shr:2 row_mask:0xf bank_mask:0xf bound_ctrl:0
	s_nop 1
	v_add_u32_dpp v51, v51, v51 row_shr:4 row_mask:0xf bank_mask:0xf bound_ctrl:0
	s_nop 1
	v_add_u32_dpp v51, v51, v51 row_shr:8 row_mask:0xf bank_mask:0xf bound_ctrl:0
	s_nop 1
	v_add_u32_dpp v51, v51, v51 row_bcast:15 row_mask:0xa bank_mask:0xf
	s_nop 1
	v_add_u32_dpp v51, v51, v51 row_bcast:31 row_mask:0xc bank_mask:0xf
	s_nop 1
	v_readlane_b32 s98, v51, 63
	s_nop 1
	v_mov_b32_e32 v51, s98
	v_cmp_gt_i32_e32 vcc, v51, v47
	s_nop 1
	v_cndmask_b32_e32 v38, v40, v38, vcc
	s_cbranch_scc1 .LBB0_798

; template <int NJ>
; DI void select_row(const float* row, int n, u64* bmrow, int lane) {
;     ...
;   unsigned kl0 = 0, kh0 = 0, kl1 = 0, kh1 = 0;
;   unsigned T1v = T + 1, Tv = T;
;   asm volatile("" : "+v"(Tv), "+v"(T1v));
; #pragma unroll
;   for (int jj = 0; jj < NJ; ++jj) {
;     unsigned tmp;
;     if (jj < 64)
;       asm volatile("v_add_u32 %2, %9, %4\n\tv_cmp_gt_u32 vcc, %3, %2\n\tv_cndmask_b32 %2, %5, %6, vcc\n\tv_cmp_ge_u32 vcc, %7, %2\n\ts_nop 3\n\tv_writelane_b32 %0, vcc_lo, %8\n\tv_writelane_b32 %1, vcc_hi, %8"
;                    : "+v"(kl0), "+v"(kh0), "=&v"(tmp) : "s"(X), "v"(lane), "v"(T1v), "v"(Tv), "v"(key[jj]), "n"(jj & 63), "n"(jj * 64) : "vcc");
;     else
;       asm volatile("v_add_u32 %2, %9, %4\n\tv_cmp_gt_u32 vcc, %3, %2\n\tv_cndmask_b32 %2, %5, %6, vcc\n\tv_cmp_ge_u32 vcc, %7, %2\n\ts_nop 3\n\tv_writelane_b32 %0, vcc_lo, %8\n\tv_writelane_b32 %1, vcc_hi, %8"
;                    : "+v"(kl1), "+v"(kh1), "=&v"(tmp) : "s"(X), "v"(lane), "v"(T1v), "v"(Tv), "v"(key[jj]), "n"(jj & 63), "n"(jj * 64) : "vcc");
;   }
;   bmrow[lane] = ((u64)kh0 << 32) | kl0; bmrow[64 + lane] = ((u64)kh1 << 32) | kl1;
.LBB0_800:
	s_or_b64 exec, exec, s[6:7]
	v_add_u32_e32 v40, 1, v47
	v_mov_b32_e32 v212, v1
	v_mov_b32_e32 v213, v1
	v_mov_b64_e32 v[232:233], 0
	v_add_u32 v45, 0, v2
	v_cmp_gt_u32 vcc, v38, v45
	v_cndmask_b32 v45, v40, v47, vcc
	v_cmp_ge_u32 vcc, v43, v45
	s_nop 3
	v_writelane_b32 v212, vcc_lo, 0
	v_writelane_b32 v213, vcc_hi, 0
	v_add_u32 v43, 64, v2
	v_cmp_gt_u32 vcc, v38, v43
	v_cndmask_b32 v43, v40, v47, vcc
	v_cmp_ge_u32 vcc, v41, v43
	s_nop 3
	v_writelane_b32 v212, vcc_lo, 1
	v_writelane_b32 v213, vcc_hi, 1
	v_add_u32 v41, 0x80, v2
	v_cmp_gt_u32 vcc, v38, v41
	v_cndmask_b32 v41, v40, v47, vcc
	v_cmp_ge_u32 vcc, v39, v41
	s_nop 3
	v_writelane_b32 v212, vcc_lo, 2
	v_writelane_b32 v213, vcc_hi, 2
	v_add_u32 v39, 0xc0, v2
	v_cmp_gt_u32 vcc, v38, v39
	v_cndmask_b32 v39, v40, v47, vcc
	v_cmp_ge_u32 vcc, v0, v39
	s_nop 3
	v_writelane_b32 v212, vcc_lo, 3
	v_writelane_b32 v213, vcc_hi, 3
	v_add_u32 v0, 0x100, v2
	v_cmp_gt_u32 vcc, v38, v0
	v_cndmask_b32 v0, v40, v47, vcc
	v_cmp_ge_u32 vcc, v6, v0
	s_nop 3
	v_writelane_b32 v212, vcc_lo, 4
	v_writelane_b32 v213, vcc_hi, 4
	v_add_u32 v0, 0x140, v2
	v_cmp_gt_u32 vcc, v38, v0
	v_cndmask_b32 v0, v40, v47, vcc
	v_cmp_ge_u32 vcc, v4, v0
	s_nop 3
	v_writelane_b32 v212, vcc_lo, 5
	v_writelane_b32 v213, vcc_hi, 5
	v_add_u32 v0, 0x180, v2
	v_cmp_gt_u32 vcc, v38, v0
	v_cndmask_b32 v0, v40, v47, vcc
	v_cmp_ge_u32 vcc, v10, v0
	s_nop 3
	v_writelane_b32 v212, vcc_lo, 6
	v_writelane_b32 v213, vcc_hi, 6
	v_add_u32 v0, 0x1c0, v2
	v_cmp_gt_u32 vcc, v38, v0
	v_cndmask_b32 v0, v40, v47, vcc
	v_cmp_ge_u32 vcc, v8, v0
	s_nop 3
	v_writelane_b32 v212, vcc_lo, 7
	v_writelane_b32 v213, vcc_hi, 7
	v_add_u32 v0, 0x200, v2
	v_cmp_gt_u32 vcc, v38, v0
	v_cndmask_b32 v0, v40, v47, vcc
	v_cmp_ge_u32 vcc, v14, v0
	s_nop 3
	v_writelane_b32 v212, vcc_lo, 8
	v_writelane_b32 v213, vcc_hi, 8
	v_add_u32 v0, 0x240, v2
	v_cmp_gt_u32 vcc, v38, v0
	v_cndmask_b32 v0, v40, v47, vcc
	v_cmp_ge_u32 vcc, v12, v0
	s_nop 3
	v_writelane_b32 v212, vcc_lo, 9
	v_writelane_b32 v213, vcc_hi, 9
	v_add_u32 v0, 0x280, v2
	v_cmp_gt_u32 vcc, v38, v0
	v_cndmask_b32 v0, v40, v47, vcc
	v_cmp_ge_u32 vcc, v17, v0
	s_nop 3
	v_writelane_b32 v212, vcc_lo, 10
	v_writelane_b32 v213, vcc_hi, 10
	v_add_u32 v0, 0x2c0, v2
	v_cmp_gt_u32 vcc, v38, v0
	v_cndmask_b32 v0, v40, v47, vcc
	v_cmp_ge_u32 vcc, v16, v0
	s_nop 3
	v_writelane_b32 v212, vcc_lo, 11
	v_writelane_b32 v213, vcc_hi, 11
	v_add_u32 v0, 0x300, v2
	v_cmp_gt_u32 vcc, v38, v0
	v_cndmask_b32 v0, v40, v47, vcc
	v_cmp_ge_u32 vcc, v19, v0
	s_nop 3
	v_writelane_b32 v212, vcc_lo, 12
	v_writelane_b32 v213, vcc_hi, 12
	v_add_u32 v0, 0x340, v2
	v_cmp_gt_u32 vcc, v38, v0
	v_cndmask_b32 v0, v40, v47, vcc
	v_cmp_ge_u32 vcc, v18, v0
	s_nop 3
	v_writelane_b32 v212, vcc_lo, 13
	v_writelane_b32 v213, vcc_hi, 13
	v_add_u32 v0, 0x380, v2
	v_cmp_gt_u32 vcc, v38, v0
	v_cndmask_b32 v0, v40, v47, vcc
	v_cmp_ge_u32 vcc, v21, v0
	s_nop 3
	v_writelane_b32 v212, vcc_lo, 14
	v_writelane_b32 v213, vcc_hi, 14
	v_add_u32 v0, 0x3c0, v2
	v_cmp_gt_u32 vcc, v38, v0
	v_cndmask_b32 v0, v40, v47, vcc
	v_cmp_ge_u32 vcc, v20, v0
	s_nop 3
	v_writelane_b32 v212, vcc_lo, 15
	v_writelane_b32 v213, vcc_hi, 15
	v_add_u32 v0, 0x400, v2
	v_cmp_gt_u32 vcc, v38, v0
	v_cndmask_b32 v0, v40, v47, vcc
	v_cmp_ge_u32 vcc, v23, v0
	s_nop 3
	v_writelane_b32 v212, vcc_lo, 16
	v_writelane_b32 v213, vcc_hi, 16
	v_add_u32 v0, 0x440, v2
	v_cmp_gt_u32 vcc, v38, v0
	v_cndmask_b32 v0, v40, v47, vcc
	v_cmp_ge_u32 vcc, v22, v0
	s_nop 3
	v_writelane_b32 v212, vcc_lo, 17
	v_writelane_b32 v213, vcc_hi, 17
	v_add_u32 v0, 0x480, v2
	v_cmp_gt_u32 vcc, v38, v0
	v_cndmask_b32 v0, v40, v47, vcc
	v_cmp_ge_u32 vcc, v25, v0
	s_nop 3
	v_writelane_b32 v212, vcc_lo, 18
	v_writelane_b32 v213, vcc_hi, 18
	v_add_u32 v0, 0x4c0, v2
	v_cmp_gt_u32 vcc, v38, v0
	v_cndmask_b32 v0, v40, v47, vcc
	v_cmp_ge_u32 vcc, v24, v0
	s_nop 3
	v_writelane_b32 v212, vcc_lo, 19
	v_writelane_b32 v213, vcc_hi, 19
	v_add_u32 v0, 0x500, v2
	v_cmp_gt_u32 vcc, v38, v0
	v_cndmask_b32 v0, v40, v47, vcc
	v_cmp_ge_u32 vcc, v27, v0
	s_nop 3
	v_writelane_b32 v212, vcc_lo, 20
	v_writelane_b32 v213, vcc_hi, 20
	v_add_u32 v0, 0x540, v2
	v_cmp_gt_u32 vcc, v38, v0
	v_cndmask_b32 v0, v40, v47, vcc
	v_cmp_ge_u32 vcc, v26, v0
	s_nop 3
	v_writelane_b32 v212, vcc_lo, 21
	v_writelane_b32 v213, vcc_hi, 21
	v_add_u32 v0, 0x580, v2
	v_cmp_gt_u32 vcc, v38, v0
	v_cndmask_b32 v0, v40, v47, vcc
	v_cmp_ge_u32 vcc, v29, v0
	s_nop 3
	v_writelane_b32 v212, vcc_lo, 22
	v_writelane_b32 v213, vcc_hi, 22
	v_add_u32 v0, 0x5c0, v2
	v_cmp_gt_u32 vcc, v38, v0
	v_cndmask_b32 v0, v40, v47, vcc
	v_cmp_ge_u32 vcc, v28, v0
	s_nop 3
	v_writelane_b32 v212, vcc_lo, 23
	v_writelane_b32 v213, vcc_hi, 23
	v_add_u32 v0, 0x600, v2
	v_cmp_gt_u32 vcc, v38, v0
	v_cndmask_b32 v0, v40, v47, vcc
	v_cmp_ge_u32 vcc, v31, v0
	s_nop 3
	v_writelane_b32 v212, vcc_lo, 24
	v_writelane_b32 v213, vcc_hi, 24
	v_add_u32 v0, 0x640, v2
	v_cmp_gt_u32 vcc, v38, v0
	v_cndmask_b32 v0, v40, v47, vcc
	v_cmp_ge_u32 vcc, v30, v0
	s_nop 3
	v_writelane_b32 v212, vcc_lo, 25
	v_writelane_b32 v213, vcc_hi, 25
	v_add_u32 v0, 0x680, v2
	v_cmp_gt_u32 vcc, v38, v0
	v_cndmask_b32 v0, v40, v47, vcc
	v_cmp_ge_u32 vcc, v33, v0
	s_nop 3
	v_writelane_b32 v212, vcc_lo, 26
	v_writelane_b32 v213, vcc_hi, 26
	v_add_u32 v0, 0x6c0, v2
	v_cmp_gt_u32 vcc, v38, v0
	v_cndmask_b32 v0, v40, v47, vcc
	v_cmp_ge_u32 vcc, v32, v0
	s_nop 3
	v_writelane_b32 v212, vcc_lo, 27
	v_writelane_b32 v213, vcc_hi, 27
	v_add_u32 v0, 0x700, v2
	v_cmp_gt_u32 vcc, v38, v0
	v_cndmask_b32 v0, v40, v47, vcc
	v_cmp_ge_u32 vcc, v35, v0
	s_nop 3
	v_writelane_b32 v212, vcc_lo, 28
	v_writelane_b32 v213, vcc_hi, 28
	v_add_u32 v0, 0x740, v2
	v_cmp_gt_u32 vcc, v38, v0
	v_cndmask_b32 v0, v40, v47, vcc
	v_cmp_ge_u32 vcc, v34, v0
	s_nop 3
	v_writelane_b32 v212, vcc_lo, 29
	v_writelane_b32 v213, vcc_hi, 29
	v_add_u32 v0, 0x780, v2
	v_cmp_gt_u32 vcc, v38, v0
	v_cndmask_b32 v0, v40, v47, vcc
	v_cmp_ge_u32 vcc, v37, v0
	s_nop 3
	v_writelane_b32 v212, vcc_lo, 30
	v_writelane_b32 v213, vcc_hi, 30
	v_add_u32 v0, 0x7c0, v2
	v_cmp_gt_u32 vcc, v38, v0
	v_cndmask_b32 v0, v40, v47, vcc
	v_cmp_ge_u32 vcc, v36, v0
	s_nop 3
	v_writelane_b32 v212, vcc_lo, 31
	v_writelane_b32 v213, vcc_hi, 31
	s_nop 0
	v_lshlrev_b32_e32 v0, 3, v2
	v_lshl_add_u64 v[16:17], v[228:229], 0, v[0:1]
	global_store_dwordx2 v[16:17], v[212:213], off

; template <int NJ>
; DI void select_row(const float* row, int n, u64* bmrow, int lane) {
;     ...
; #pragma unroll 1
;   while (!exact && hi - lo > 1u) {
;     const unsigned cand = lo + ((hi - lo) >> 1);
;     int c = 0;
; #pragma unroll
;     for (int jj = 0; jj < NJ; ++jj)
;       asm volatile("v_cmp_le_u32 vcc, %1, %2\n\tv_addc_co_u32 %0, vcc, 0, %0, vcc" : "+v"(c) : "s"(cand), "v"(key[jj]) : "vcc");
;     c = wave_sum_i(c, lane);
;     if (c == 256) { T = cand; exact = true; }
;     else if (c > 256) lo = cand; else hi = cand;
;   }
.LBB0_806:
	v_lshrrev_b32_e32 v38, 1, v38
	v_mov_b32_e32 v40, v1
	v_add_u32_e32 v38, v0, v38
	v_cmp_le_u32 vcc, v38, v79
	v_addc_co_u32 v40, vcc, 0, v40, vcc
	v_cmp_le_u32 vcc, v38, v77
	v_addc_co_u32 v40, vcc, 0, v40, vcc
	v_cmp_le_u32 vcc, v38, v75
	v_addc_co_u32 v40, vcc, 0, v40, vcc
	v_cmp_le_u32 vcc, v38, v73
	v_addc_co_u32 v40, vcc, 0, v40, vcc
	v_cmp_le_u32 vcc, v38, v71
	v_addc_co_u32 v40, vcc, 0, v40, vcc
	v_cmp_le_u32 vcc, v38, v69
	v_addc_co_u32 v40, vcc, 0, v40, vcc
	v_cmp_le_u32 vcc, v38, v67
	v_addc_co_u32 v40, vcc, 0, v40, vcc
	v_cmp_le_u32 vcc, v38, v65
	v_addc_co_u32 v40, vcc, 0, v40, vcc
	v_cmp_le_u32 vcc, v38, v63
	v_addc_co_u32 v40, vcc, 0, v40, vcc
	v_cmp_le_u32 vcc, v38, v61
	v_addc_co_u32 v40, vcc, 0, v40, vcc
	v_cmp_le_u32 vcc, v38, v59
	v_addc_co_u32 v40, vcc, 0, v40, vcc
	v_cmp_le_u32 vcc, v38, v57
	v_addc_co_u32 v40, vcc, 0, v40, vcc
	v_cmp_le_u32 vcc, v38, v55
	v_addc_co_u32 v40, vcc, 0, v40, vcc
	v_cmp_le_u32 vcc, v38, v51
	v_addc_co_u32 v40, vcc, 0, v40, vcc
	v_cmp_le_u32 vcc, v38, v53
	v_addc_co_u32 v40, vcc, 0, v40, vcc
	v_cmp_le_u32 vcc, v38, v49
	v_addc_co_u32 v40, vcc, 0, v40, vcc
	v_cmp_le_u32 vcc, v38, v47
	v_addc_co_u32 v40, vcc, 0, v40, vcc
	v_cmp_le_u32 vcc, v38, v45
	v_addc_co_u32 v40, vcc, 0, v40, vcc
	v_cmp_le_u32 vcc, v38, v43
	v_addc_co_u32 v40, vcc, 0, v40, vcc
	v_cmp_le_u32 vcc, v38, v41
	v_addc_co_u32 v40, vcc, 0, v40, vcc
	v_cmp_le_u32 vcc, v38, v39
	v_addc_co_u32 v40, vcc, 0, v40, vcc
	v_cmp_le_u32 vcc, v38, v37
	v_addc_co_u32 v40, vcc, 0, v40, vcc
	v_cmp_le_u32 vcc, v38, v35
	v_addc_co_u32 v40, vcc, 0, v40, vcc
	v_cmp_le_u32 vcc, v38, v33
	v_addc_co_u32 v40, vcc, 0, v40, vcc
	v_cmp_le_u32 vcc, v38, v31
	v_addc_co_u32 v40, vcc, 0, v40, vcc
	v_cmp_le_u32 vcc, v38, v29
	v_addc_co_u32 v40, vcc, 0, v40, vcc
	v_cmp_le_u32 vcc, v38, v27
	v_addc_co_u32 v40, vcc, 0, v40, vcc
	v_cmp_le_u32 vcc, v38, v25
	v_addc_co_u32 v40, vcc, 0, v40, vcc
	v_cmp_le_u32 vcc, v38, v23
	v_addc_co_u32 v40, vcc, 0, v40, vcc
	v_cmp_le_u32 vcc, v38, v21
	v_addc_co_u32 v40, vcc, 0, v40, vcc
	v_cmp_le_u32 vcc, v38, v19
	v_addc_co_u32 v40, vcc, 0, v40, vcc
	v_cmp_le_u32 vcc, v38, v17
	v_addc_co_u32 v40, vcc, 0, v40, vcc
	v_cmp_le_u32 vcc, v38, v6
	v_addc_co_u32 v40, vcc, 0, v40, vcc
	v_cmp_le_u32 vcc, v38, v4
	v_addc_co_u32 v40, vcc, 0, v40, vcc
	v_cmp_le_u32 vcc, v38, v10
	v_addc_co_u32 v40, vcc, 0, v40, vcc
	v_cmp_le_u32 vcc, v38, v8
	v_addc_co_u32 v40, vcc, 0, v40, vcc
	v_cmp_le_u32 vcc, v38, v14
	v_addc_co_u32 v40, vcc, 0, v40, vcc
	v_cmp_le_u32 vcc, v38, v12
	v_addc_co_u32 v40, vcc, 0, v40, vcc
	v_cmp_le_u32 vcc, v38, v18
	v_addc_co_u32 v40, vcc, 0, v40, vcc
	v_cmp_le_u32 vcc, v38, v16
	v_addc_co_u32 v40, vcc, 0, v40, vcc
	v_cmp_le_u32 vcc, v38, v22
	v_addc_co_u32 v40, vcc, 0, v40, vcc
	v_cmp_le_u32 vcc, v38, v20
	v_addc_co_u32 v40, vcc, 0, v40, vcc
	v_cmp_le_u32 vcc, v38, v26
	v_addc_co_u32 v40, vcc, 0, v40, vcc
	v_cmp_le_u32 vcc, v38, v24
	v_addc_co_u32 v40, vcc, 0, v40, vcc
	v_cmp_le_u32 vcc, v38, v30
	v_addc_co_u32 v40, vcc, 0, v40, vcc
	v_cmp_le_u32 vcc, v38, v28
	v_addc_co_u32 v40, vcc, 0, v40, vcc
	v_cmp_le_u32 vcc, v38, v83
	v_addc_co_u32 v40, vcc, 0, v40, vcc
	v_cmp_le_u32 vcc, v38, v81
	v_addc_co_u32 v40, vcc, 0, v40, vcc
	v_cmp_le_u32 vcc, v38, v87
	v_addc_co_u32 v40, vcc, 0, v40, vcc
	v_cmp_le_u32 vcc, v38, v85
	v_addc_co_u32 v40, vcc, 0, v40, vcc
	v_cmp_le_u32 vcc, v38, v91
	v_addc_co_u32 v40, vcc, 0, v40, vcc
	v_cmp_le_u32 vcc, v38, v89
	v_addc_co_u32 v40, vcc, 0, v40, vcc
	v_cmp_le_u32 vcc, v38, v95
	v_addc_co_u32 v40, vcc, 0, v40, vcc
	v_cmp_le_u32 vcc, v38, v93
	v_addc_co_u32 v40, vcc, 0, v40, vcc
	v_cmp_le_u32 vcc, v38, v99
	v_addc_co_u32 v40, vcc, 0, v40, vcc
	v_cmp_le_u32 vcc, v38, v97
	v_addc_co_u32 v40, vcc, 0, v40, vcc
	v_cmp_le_u32 vcc, v38, v32
	v_addc_co_u32 v40, vcc, 0, v40, vcc
	v_cmp_le_u32 vcc, v38, v101
	v_addc_co_u32 v40, vcc, 0, v40, vcc
	v_cmp_le_u32 vcc, v38, v105
	v_addc_co_u32 v40, vcc, 0, v40, vcc
	v_cmp_le_u32 vcc, v38, v103
	v_addc_co_u32 v40, vcc, 0, v40, vcc
	v_cmp_le_u32 vcc, v38, v109
	v_addc_co_u32 v40, vcc, 0, v40, vcc
	v_cmp_le_u32 vcc, v38, v107
	v_addc_co_u32 v40, vcc, 0, v40, vcc
	v_cmp_le_u32 vcc, v38, v113
	v_addc_co_u32 v40, vcc, 0, v40, vcc
	v_cmp_le_u32 vcc, v38, v111
	v_addc_co_u32 v40, vcc, 0, v40, vcc
	s_nop 1
	v_add_u32_dpp v40, v40, v40 row_shr:1 row_mask:0xf bank_mask:0xf bound_ctrl:0
	s_nop 1
	v_add_u32_dpp v40, v40, v40 row_shr:2 row_mask:0xf bank_mask:0xf bound_ctrl:0
	s_nop 1
	v_add_u32_dpp v40, v40, v40 row_shr:4 row_mask:0xf bank_mask:0xf bound_ctrl:0
	s_nop 1
	v_add_u32_dpp v40, v40, v40 row_shr:8 row_mask:0xf bank_mask:0xf bound_ctrl:0
	s_nop 1
	v_add_u32_dpp v40, v40, v40 row_bcast:15 row_mask:0xa bank_mask:0xf
	s_nop 1
	v_add_u32_dpp v40, v40, v40 row_bcast:31 row_mask:0xc bank_mask:0xf
	s_nop 1
	v_readlane_b32 s98, v40, 63
	s_nop 1
	v_mov_b32_e32 v40, s98
	v_cmp_lt_i32_e32 vcc, s38, v40
	s_nop 1
	v_cndmask_b32_e32 v115, v0, v38, vcc
	v_cmp_lt_i32_e32 vcc, s39, v40
	s_nop 1
	v_cndmask_b32_e32 v36, v38, v36, vcc
	v_cmp_eq_u32_e32 vcc, s38, v40
	s_nop 1
	v_cndmask_b32_e32 v0, v115, v0, vcc
	v_cndmask_b32_e32 v34, v34, v38, vcc
	v_sub_u32_e32 v38, v36, v0
	v_cmp_gt_u32_e64 s[6:7], 2, v38
	s_or_b64 s[6:7], vcc, s[6:7]
	s_and_b64 s[6:7], exec, s[6:7]
	s_or_b64 s[24:25], s[6:7], s[24:25]
	s_andn2_b64 s[6:7], s[26:27], exec
	s_and_b64 s[26:27], vcc, exec
	s_or_b64 s[26:27], s[6:7], s[26:27]
	s_andn2_b64 exec, exec, s[24:25]
	s_cbranch_execnz .LBB0_806
	s_or_b64 exec, exec, s[24:25]
	s_andn2_b64 s[6:7], s[20:21], exec
	s_and_b64 s[20:21], s[26:27], exec
	s_or_b64 s[20:21], s[6:7], s[20:21]
; template <int NJ>
; DI void select_row(const float* row, int n, u64* bmrow, int lane) {
;     ...
;   unsigned X = 0xffffffffu;
;   if (!exact) {
;     int cgt = 0, ceq = 0;
; #pragma unroll
;     for (int jj = 0; jj < NJ; ++jj) {
;       asm volatile("v_cmp_lt_u32 vcc, %1, %2\n\tv_addc_co_u32 %0, vcc, 0, %0, vcc" : "+v"(cgt) : "s"(T), "v"(key[jj]) : "vcc");
;       asm volatile("v_cmp_eq_u32 vcc, %1, %2\n\tv_addc_co_u32 %0, vcc, 0, %0, vcc" : "+v"(ceq) : "s"(T), "v"(key[jj]) : "vcc");
;     }
.LBB0_808:
	s_or_b64 exec, exec, s[22:23]
	s_xor_b64 s[20:21], s[20:21], -1
	v_mov_b32_e32 v36, -1
	s_and_saveexec_b64 s[6:7], s[20:21]
	s_cbranch_execz .LBB0_813
	v_mov_b32_e32 v34, v1
	v_cmp_lt_u32 vcc, v0, v79
	v_addc_co_u32 v34, vcc, 0, v34, vcc
	v_mov_b32_e32 v36, v1
	v_cmp_eq_u32 vcc, v0, v79
	v_addc_co_u32 v36, vcc, 0, v36, vcc
	v_cmp_lt_u32 vcc, v0, v77
	v_addc_co_u32 v34, vcc, 0, v34, vcc
	v_cmp_eq_u32 vcc, v0, v77
	v_addc_co_u32 v36, vcc, 0, v36, vcc
	v_cmp_lt_u32 vcc, v0, v75
	v_addc_co_u32 v34, vcc, 0, v34, vcc
	v_cmp_eq_u32 vcc, v0, v75
	v_addc_co_u32 v36, vcc, 0, v36, vcc
	v_cmp_lt_u32 vcc, v0, v73
	v_addc_co_u32 v34, vcc, 0, v34, vcc
	v_cmp_eq_u32 vcc, v0, v73
	v_addc_co_u32 v36, vcc, 0, v36, vcc
	v_cmp_lt_u32 vcc, v0, v71
	v_addc_co_u32 v34, vcc, 0, v34, vcc
	v_cmp_eq_u32 vcc, v0, v71
	v_addc_co_u32 v36, vcc, 0, v36, vcc
	v_cmp_lt_u32 vcc, v0, v69
	v_addc_co_u32 v34, vcc, 0, v34, vcc
	v_cmp_eq_u32 vcc, v0, v69
	v_addc_co_u32 v36, vcc, 0, v36, vcc
	v_cmp_lt_u32 vcc, v0, v67
	v_addc_co_u32 v34, vcc, 0, v34, vcc
	v_cmp_eq_u32 vcc, v0, v67
	v_addc_co_u32 v36, vcc, 0, v36, vcc
	v_cmp_lt_u32 vcc, v0, v65
	v_addc_co_u32 v34, vcc, 0, v34, vcc
	v_cmp_eq_u32 vcc, v0, v65
	v_addc_co_u32 v36, vcc, 0, v36, vcc
	v_cmp_lt_u32 vcc, v0, v63
	v_addc_co_u32 v34, vcc, 0, v34, vcc
	v_cmp_eq_u32 vcc, v0, v63
	v_addc_co_u32 v36, vcc, 0, v36, vcc
	v_cmp_lt_u32 vcc, v0, v61
	v_addc_co_u32 v34, vcc, 0, v34, vcc
	v_cmp_eq_u32 vcc, v0, v61
	v_addc_co_u32 v36, vcc, 0, v36, vcc
	v_cmp_lt_u32 vcc, v0, v59
	v_addc_co_u32 v34, vcc, 0, v34, vcc
	v_cmp_eq_u32 vcc, v0, v59
	v_addc_co_u32 v36, vcc, 0, v36, vcc
	v_cmp_lt_u32 vcc, v0, v57
	v_addc_co_u32 v34, vcc, 0, v34, vcc
	v_cmp_eq_u32 vcc, v0, v57
	v_addc_co_u32 v36, vcc, 0, v36, vcc
	v_cmp_lt_u32 vcc, v0, v55
	v_addc_co_u32 v34, vcc, 0, v34, vcc
	v_cmp_eq_u32 vcc, v0, v55
	v_addc_co_u32 v36, vcc, 0, v36, vcc
	v_cmp_lt_u32 vcc, v0, v51
	v_addc_co_u32 v34, vcc, 0, v34, vcc
	v_cmp_eq_u32 vcc, v0, v51
	v_addc_co_u32 v36, vcc, 0, v36, vcc
	v_cmp_lt_u32 vcc, v0, v53
	v_addc_co_u32 v34, vcc, 0, v34, vcc
	v_cmp_eq_u32 vcc, v0, v53
	v_addc_co_u32 v36, vcc, 0, v36, vcc
	v_cmp_lt_u32 vcc, v0, v49
	v_addc_co_u32 v34, vcc, 0, v34, vcc
	v_cmp_eq_u32 vcc, v0, v49
	v_addc_co_u32 v36, vcc, 0, v36, vcc
	v_cmp_lt_u32 vcc, v0, v47
	v_addc_co_u32 v34, vcc, 0, v34, vcc
	v_cmp_eq_u32 vcc, v0, v47
	v_addc_co_u32 v36, vcc, 0, v36, vcc
	v_cmp_lt_u32 vcc, v0, v45
	v_addc_co_u32 v34, vcc, 0, v34, vcc
	v_cmp_eq_u32 vcc, v0, v45
	v_addc_co_u32 v36, vcc, 0, v36, vcc
	v_cmp_lt_u32 vcc, v0, v43
	v_addc_co_u32 v34, vcc, 0, v34, vcc
	v_cmp_eq_u32 vcc, v0, v43
	v_addc_co_u32 v36, vcc, 0, v36, vcc
	v_cmp_lt_u32 vcc, v0, v41
	v_addc_co_u32 v34, vcc, 0, v34, vcc
	v_cmp_eq_u32 vcc, v0, v41
	v_addc_co_u32 v36, vcc, 0, v36, vcc
	v_cmp_lt_u32 vcc, v0, v39
	v_addc_co_u32 v34, vcc, 0, v34, vcc
	v_cmp_eq_u32 vcc, v0, v39
	v_addc_co_u32 v36, vcc, 0, v36, vcc
	v_cmp_lt_u32 vcc, v0, v37
	v_addc_co_u32 v34, vcc, 0, v34, vcc
	v_cmp_eq_u32 vcc, v0, v37
	v_addc_co_u32 v36, vcc, 0, v36, vcc
	v_cmp_lt_u32 vcc, v0, v35
	v_addc_co_u32 v34, vcc, 0, v34, vcc
	v_cmp_eq_u32 vcc, v0, v35
	v_addc_co_u32 v36, vcc, 0, v36, vcc
	v_cmp_lt_u32 vcc, v0, v33
	v_addc_co_u32 v34, vcc, 0, v34, vcc
	v_cmp_eq_u32 vcc, v0, v33
	v_addc_co_u32 v36, vcc, 0, v36, vcc
	v_cmp_lt_u32 vcc, v0, v31
	v_addc_co_u32 v34, vcc, 0, v34, vcc
	v_cmp_eq_u32 vcc, v0, v31
	v_addc_co_u32 v36, vcc, 0, v36, vcc
	v_cmp_lt_u32 vcc, v0, v29
	v_addc_co_u32 v34, vcc, 0, v34, vcc
	v_cmp_eq_u32 vcc, v0, v29
	v_addc_co_u32 v36, vcc, 0, v36, vcc
	v_cmp_lt_u32 vcc, v0, v27
	v_addc_co_u32 v34, vcc, 0, v34, vcc
	v_cmp_eq_u32 vcc, v0, v27
	v_addc_co_u32 v36, vcc, 0, v36, vcc
	v_cmp_lt_u32 vcc, v0, v25
	v_addc_co_u32 v34, vcc, 0, v34, vcc
	v_cmp_eq_u32 vcc, v0, v25
	v_addc_co_u32 v36, vcc, 0, v36, vcc
	v_cmp_lt_u32 vcc, v0, v23
	v_addc_co_u32 v34, vcc, 0, v34, vcc
	v_cmp_eq_u32 vcc, v0, v23
	v_addc_co_u32 v36, vcc, 0, v36, vcc
	v_cmp_lt_u32 vcc, v0, v21
	v_addc_co_u32 v34, vcc, 0, v34, vcc
	v_cmp_eq_u32 vcc, v0, v21
	v_addc_co_u32 v36, vcc, 0, v36, vcc
	v_cmp_lt_u32 vcc, v0, v19
	v_addc_co_u32 v34, vcc, 0, v34, vcc
	v_cmp_eq_u32 vcc, v0, v19
	v_addc_co_u32 v36, vcc, 0, v36, vcc
	v_cmp_lt_u32 vcc, v0, v17
	v_addc_co_u32 v34, vcc, 0, v34, vcc
	v_cmp_eq_u32 vcc, v0, v17
	v_addc_co_u32 v36, vcc, 0, v36, vcc
	v_cmp_lt_u32 vcc, v0, v6
	v_addc_co_u32 v34, vcc, 0, v34, vcc
	v_cmp_eq_u32 vcc, v0, v6
	v_addc_co_u32 v36, vcc, 0, v36, vcc
	v_cmp_lt_u32 vcc, v0, v4
	v_addc_co_u32 v34, vcc, 0, v34, vcc
	v_cmp_eq_u32 vcc, v0, v4
	v_addc_co_u32 v36, vcc, 0, v36, vcc
	v_cmp_lt_u32 vcc, v0, v10
	v_addc_co_u32 v34, vcc, 0, v34, vcc
	v_cmp_eq_u32 vcc, v0, v10
	v_addc_co_u32 v36, vcc, 0, v36, vcc
	v_cmp_lt_u32 vcc, v0, v8
	v_addc_co_u32 v34, vcc, 0, v34, vcc
	v_cmp_eq_u32 vcc, v0, v8
	v_addc_co_u32 v36, vcc, 0, v36, vcc
	v_cmp_lt_u32 vcc, v0, v14
	v_addc_co_u32 v34, vcc, 0, v34, vcc
	v_cmp_eq_u32 vcc, v0, v14
	v_addc_co_u32 v36, vcc, 0, v36, vcc
	v_cmp_lt_u32 vcc, v0, v12
	v_addc_co_u32 v34, vcc, 0, v34, vcc
	v_cmp_eq_u32 vcc, v0, v12
	v_addc_co_u32 v36, vcc, 0, v36, vcc
	v_cmp_lt_u32 vcc, v0, v18
	v_addc_co_u32 v34, vcc, 0, v34, vcc
	v_cmp_eq_u32 vcc, v0, v18
	v_addc_co_u32 v36, vcc, 0, v36, vcc
	v_cmp_lt_u32 vcc, v0, v16
	v_addc_co_u32 v34, vcc, 0, v34, vcc
	v_cmp_eq_u32 vcc, v0, v16
	v_addc_co_u32 v36, vcc, 0, v36, vcc
	v_cmp_lt_u32 vcc, v0, v22
	v_addc_co_u32 v34, vcc, 0, v34, vcc
	v_cmp_eq_u32 vcc, v0, v22
	v_addc_co_u32 v36, vcc, 0, v36, vcc
	v_cmp_lt_u32 vcc, v0, v20
	v_addc_co_u32 v34, vcc, 0, v34, vcc
	v_cmp_eq_u32 vcc, v0, v20
	v_addc_co_u32 v36, vcc, 0, v36, vcc
	v_cmp_lt_u32 vcc, v0, v26
	v_addc_co_u32 v34, vcc, 0, v34, vcc
; template <int NJ>
; DI void select_row(const float* row, int n, u64* bmrow, int lane) {
;     ...
;     int cgt = 0, ceq = 0;
; #pragma unroll
;     for (int jj = 0; jj < NJ; ++jj) {
;       asm volatile("v_cmp_lt_u32 vcc, %1, %2\n\tv_addc_co_u32 %0, vcc, 0, %0, vcc" : "+v"(cgt) : "s"(T), "v"(key[jj]) : "vcc");
;       asm volatile("v_cmp_eq_u32 vcc, %1, %2\n\tv_addc_co_u32 %0, vcc, 0, %0, vcc" : "+v"(ceq) : "s"(T), "v"(key[jj]) : "vcc");
;     }
;     cgt = wave_sum_i(cgt, lane); ceq = wave_sum_i(ceq, lane);
;     const int need = 256 - cgt;
;     unsigned bigv = 0x7fffffffu;
;     asm volatile("" : "+v"(bigv));
;     if (ceq != need) {
;       X = 0;
; #pragma unroll 1
;     ...
;         const unsigned cand = X | (1u << bit);
;         int c = 0;
; #pragma unroll
;         for (int jj = 0; jj < NJ; ++jj) {
;           unsigned tmp;
;           asm volatile("v_add_u32 %1, %7, %5\n\tv_cmp_eq_u32 vcc, %2, %3\n\tv_cndmask_b32 %1, %4, %1, vcc\n\tv_cmp_gt_u32 vcc, %6, %1\n\tv_addc_co_u32 %0, vcc, 0, %0, vcc"
;                        : "+v"(c), "=&v"(tmp) : "s"(T), "v"(key[jj]), "v"(bigv), "v"(lane), "s"(cand), "n"(jj * 64) : "vcc");
;         }
;         c = wave_sum_i(c, lane);
	v_cmp_eq_u32 vcc, v0, v26
	v_addc_co_u32 v36, vcc, 0, v36, vcc
	v_cmp_lt_u32 vcc, v0, v24
	v_addc_co_u32 v34, vcc, 0, v34, vcc
	v_cmp_eq_u32 vcc, v0, v24
	v_addc_co_u32 v36, vcc, 0, v36, vcc
	v_cmp_lt_u32 vcc, v0, v30
	v_addc_co_u32 v34, vcc, 0, v34, vcc
	v_cmp_eq_u32 vcc, v0, v30
	v_addc_co_u32 v36, vcc, 0, v36, vcc
	v_cmp_lt_u32 vcc, v0, v28
	v_addc_co_u32 v34, vcc, 0, v34, vcc
	v_cmp_eq_u32 vcc, v0, v28
	v_addc_co_u32 v36, vcc, 0, v36, vcc
	v_cmp_lt_u32 vcc, v0, v83
	v_addc_co_u32 v34, vcc, 0, v34, vcc
	v_cmp_eq_u32 vcc, v0, v83
	v_addc_co_u32 v36, vcc, 0, v36, vcc
	v_cmp_lt_u32 vcc, v0, v81
	v_addc_co_u32 v34, vcc, 0, v34, vcc
	v_cmp_eq_u32 vcc, v0, v81
	v_addc_co_u32 v36, vcc, 0, v36, vcc
	v_cmp_lt_u32 vcc, v0, v87
	v_addc_co_u32 v34, vcc, 0, v34, vcc
	v_cmp_eq_u32 vcc, v0, v87
	v_addc_co_u32 v36, vcc, 0, v36, vcc
	v_cmp_lt_u32 vcc, v0, v85
	v_addc_co_u32 v34, vcc, 0, v34, vcc
	v_cmp_eq_u32 vcc, v0, v85
	v_addc_co_u32 v36, vcc, 0, v36, vcc
	v_cmp_lt_u32 vcc, v0, v91
	v_addc_co_u32 v34, vcc, 0, v34, vcc
	v_cmp_eq_u32 vcc, v0, v91
	v_addc_co_u32 v36, vcc, 0, v36, vcc
	v_cmp_lt_u32 vcc, v0, v89
	v_addc_co_u32 v34, vcc, 0, v34, vcc
	v_cmp_eq_u32 vcc, v0, v89
	v_addc_co_u32 v36, vcc, 0, v36, vcc
	v_cmp_lt_u32 vcc, v0, v95
	v_addc_co_u32 v34, vcc, 0, v34, vcc
	v_cmp_eq_u32 vcc, v0, v95
	v_addc_co_u32 v36, vcc, 0, v36, vcc
	v_cmp_lt_u32 vcc, v0, v93
	v_addc_co_u32 v34, vcc, 0, v34, vcc
	v_cmp_eq_u32 vcc, v0, v93
	v_addc_co_u32 v36, vcc, 0, v36, vcc
	v_cmp_lt_u32 vcc, v0, v99
	v_addc_co_u32 v34, vcc, 0, v34, vcc
	v_cmp_eq_u32 vcc, v0, v99
	v_addc_co_u32 v36, vcc, 0, v36, vcc
	v_cmp_lt_u32 vcc, v0, v97
	v_addc_co_u32 v34, vcc, 0, v34, vcc
	v_cmp_eq_u32 vcc, v0, v97
	v_addc_co_u32 v36, vcc, 0, v36, vcc
	v_cmp_lt_u32 vcc, v0, v32
	v_addc_co_u32 v34, vcc, 0, v34, vcc
	v_cmp_eq_u32 vcc, v0, v32
	v_addc_co_u32 v36, vcc, 0, v36, vcc
	v_cmp_lt_u32 vcc, v0, v101
	v_addc_co_u32 v34, vcc, 0, v34, vcc
	v_cmp_eq_u32 vcc, v0, v101
	v_addc_co_u32 v36, vcc, 0, v36, vcc
	v_cmp_lt_u32 vcc, v0, v105
	v_addc_co_u32 v34, vcc, 0, v34, vcc
	v_cmp_eq_u32 vcc, v0, v105
	v_addc_co_u32 v36, vcc, 0, v36, vcc
	v_cmp_lt_u32 vcc, v0, v103
	v_addc_co_u32 v34, vcc, 0, v34, vcc
	v_cmp_eq_u32 vcc, v0, v103
	v_addc_co_u32 v36, vcc, 0, v36, vcc
	v_cmp_lt_u32 vcc, v0, v109
	v_addc_co_u32 v34, vcc, 0, v34, vcc
	v_cmp_eq_u32 vcc, v0, v109
	v_addc_co_u32 v36, vcc, 0, v36, vcc
	v_cmp_lt_u32 vcc, v0, v107
	v_addc_co_u32 v34, vcc, 0, v34, vcc
	v_cmp_eq_u32 vcc, v0, v107
	v_addc_co_u32 v36, vcc, 0, v36, vcc
	v_cmp_lt_u32 vcc, v0, v113
	v_addc_co_u32 v34, vcc, 0, v34, vcc
	v_cmp_eq_u32 vcc, v0, v113
	v_addc_co_u32 v36, vcc, 0, v36, vcc
	v_cmp_lt_u32 vcc, v0, v111
	v_addc_co_u32 v34, vcc, 0, v34, vcc
	ds_bpermute_b32 v38, v5, v34
	v_cmp_eq_u32 vcc, v0, v111
	v_addc_co_u32 v36, vcc, 0, v36, vcc
	ds_bpermute_b32 v40, v5, v36
	s_waitcnt lgkmcnt(1)
	v_add_u32_e32 v34, v38, v34
	ds_bpermute_b32 v38, v7, v34
	s_waitcnt lgkmcnt(1)
	v_add_u32_e32 v36, v40, v36
	ds_bpermute_b32 v40, v7, v36
	s_waitcnt lgkmcnt(1)
	v_add_u32_e32 v34, v38, v34
	ds_bpermute_b32 v38, v9, v34
	s_waitcnt lgkmcnt(1)
	v_add_u32_e32 v36, v40, v36
	ds_bpermute_b32 v40, v9, v36
	s_waitcnt lgkmcnt(1)
	v_add_u32_e32 v34, v38, v34
	ds_bpermute_b32 v38, v11, v34
	s_waitcnt lgkmcnt(1)
	v_add_u32_e32 v36, v40, v36
	ds_bpermute_b32 v40, v11, v36
	s_waitcnt lgkmcnt(1)
	v_add_u32_e32 v34, v38, v34
	ds_bpermute_b32 v38, v13, v34
	s_waitcnt lgkmcnt(1)
	v_add_u32_e32 v36, v40, v36
	ds_bpermute_b32 v40, v13, v36
	s_waitcnt lgkmcnt(1)
	v_add_u32_e32 v34, v38, v34
	s_waitcnt lgkmcnt(0)
	v_add_u32_e32 v36, v40, v36
	ds_bpermute_b32 v40, v15, v34
	ds_bpermute_b32 v38, v15, v36
	s_waitcnt lgkmcnt(1)
	v_add_u32_e32 v34, v40, v34
	s_waitcnt lgkmcnt(0)
	v_add_u32_e32 v36, v38, v36
	v_sub_u32_e32 v34, 0x100, v34
	v_bfrev_b32_e32 v38, -2
	v_cmp_ne_u32_e32 vcc, v36, v34
	v_mov_b32_e32 v36, -1
	s_and_saveexec_b64 s[20:21], vcc
	s_cbranch_execz .LBB0_812
	v_mov_b32_e32 v36, 0
	s_mov_b32 s22, 13
.LBB0_811:
	v_mov_b32_e32 v115, v1
	v_lshl_or_b32 v40, 1, s22, v36
	v_add_u32 v117, 0, v2
	v_cmp_eq_u32 vcc, v0, v79
	v_cndmask_b32 v117, v38, v117, vcc
	v_cmp_gt_u32 vcc, v40, v117
	v_addc_co_u32 v115, vcc, 0, v115, vcc
	s_add_i32 s22, s22, -1
	v_add_u32 v117, 64, v2
	v_cmp_eq_u32 vcc, v0, v77
	v_cndmask_b32 v117, v38, v117, vcc
	v_cmp_gt_u32 vcc, v40, v117
	v_addc_co_u32 v115, vcc, 0, v115, vcc
	s_cmp_lg_u32 s22, -1
	v_add_u32 v117, 0x80, v2
	v_cmp_eq_u32 vcc, v0, v75
	v_cndmask_b32 v117, v38, v117, vcc
	v_cmp_gt_u32 vcc, v40, v117
	v_addc_co_u32 v115, vcc, 0, v115, vcc
	v_add_u32 v117, 0xc0, v2
	v_cmp_eq_u32 vcc, v0, v73
	v_cndmask_b32 v117, v38, v117, vcc
	v_cmp_gt_u32 vcc, v40, v117
	v_addc_co_u32 v115, vcc, 0, v115, vcc
	v_add_u32 v117, 0x100, v2
	v_cmp_eq_u32 vcc, v0, v71
	v_cndmask_b32 v117, v38, v117, vcc
	v_cmp_gt_u32 vcc, v40, v117
	v_addc_co_u32 v115, vcc, 0, v115, vcc
	v_add_u32 v117, 0x140, v2
	v_cmp_eq_u32 vcc, v0, v69
	v_cndmask_b32 v117, v38, v117, vcc
	v_cmp_gt_u32 vcc, v40, v117
	v_addc_co_u32 v115, vcc, 0, v115, vcc
	v_add_u32 v117, 0x180, v2
	v_cmp_eq_u32 vcc, v0, v67
	v_cndmask_b32 v117, v38, v117, vcc
	v_cmp_gt_u32 vcc, v40, v117
	v_addc_co_u32 v115, vcc, 0, v115, vcc
	v_add_u32 v117, 0x1c0, v2
	v_cmp_eq_u32 vcc, v0, v65
	v_cndmask_b32 v117, v38, v117, vcc
	v_cmp_gt_u32 vcc, v40, v117
	v_addc_co_u32 v115, vcc, 0, v115, vcc
	v_add_u32 v117, 0x200, v2
	v_cmp_eq_u32 vcc, v0, v63
	v_cndmask_b32 v117, v38, v117, vcc
	v_cmp_gt_u32 vcc, v40, v117
	v_addc_co_u32 v115, vcc, 0, v115, vcc
	v_add_u32 v117, 0x240, v2
	v_cmp_eq_u32 vcc, v0, v61
	v_cndmask_b32 v117, v38, v117, vcc
	v_cmp_gt_u32 vcc, v40, v117
	v_addc_co_u32 v115, vcc, 0, v115, vcc
; template <int NJ>
; DI void select_row(const float* row, int n, u64* bmrow, int lane) {
;     ...
;         const unsigned cand = X | (1u << bit);
;         int c = 0;
; #pragma unroll
;         for (int jj = 0; jj < NJ; ++jj) {
;           unsigned tmp;
;           asm volatile("v_add_u32 %1, %7, %5\n\tv_cmp_eq_u32 vcc, %2, %3\n\tv_cndmask_b32 %1, %4, %1, vcc\n\tv_cmp_gt_u32 vcc, %6, %1\n\tv_addc_co_u32 %0, vcc, 0, %0, vcc"
;                        : "+v"(c), "=&v"(tmp) : "s"(T), "v"(key[jj]), "v"(bigv), "v"(lane), "s"(cand), "n"(jj * 64) : "vcc");
;         }
;         c = wave_sum_i(c, lane);
	v_add_u32 v117, 0x280, v2
	v_cmp_eq_u32 vcc, v0, v59
	v_cndmask_b32 v117, v38, v117, vcc
	v_cmp_gt_u32 vcc, v40, v117
	v_addc_co_u32 v115, vcc, 0, v115, vcc
	v_add_u32 v117, 0x2c0, v2
	v_cmp_eq_u32 vcc, v0, v57
	v_cndmask_b32 v117, v38, v117, vcc
	v_cmp_gt_u32 vcc, v40, v117
	v_addc_co_u32 v115, vcc, 0, v115, vcc
	v_add_u32 v117, 0x300, v2
	v_cmp_eq_u32 vcc, v0, v55
	v_cndmask_b32 v117, v38, v117, vcc
	v_cmp_gt_u32 vcc, v40, v117
	v_addc_co_u32 v115, vcc, 0, v115, vcc
	v_add_u32 v117, 0x340, v2
	v_cmp_eq_u32 vcc, v0, v51
	v_cndmask_b32 v117, v38, v117, vcc
	v_cmp_gt_u32 vcc, v40, v117
	v_addc_co_u32 v115, vcc, 0, v115, vcc
	v_add_u32 v117, 0x380, v2
	v_cmp_eq_u32 vcc, v0, v53
	v_cndmask_b32 v117, v38, v117, vcc
	v_cmp_gt_u32 vcc, v40, v117
	v_addc_co_u32 v115, vcc, 0, v115, vcc
	v_add_u32 v117, 0x3c0, v2
	v_cmp_eq_u32 vcc, v0, v49
	v_cndmask_b32 v117, v38, v117, vcc
	v_cmp_gt_u32 vcc, v40, v117
	v_addc_co_u32 v115, vcc, 0, v115, vcc
	v_add_u32 v117, 0x400, v2
	v_cmp_eq_u32 vcc, v0, v47
	v_cndmask_b32 v117, v38, v117, vcc
	v_cmp_gt_u32 vcc, v40, v117
	v_addc_co_u32 v115, vcc, 0, v115, vcc
	v_add_u32 v117, 0x440, v2
	v_cmp_eq_u32 vcc, v0, v45
	v_cndmask_b32 v117, v38, v117, vcc
	v_cmp_gt_u32 vcc, v40, v117
	v_addc_co_u32 v115, vcc, 0, v115, vcc
	v_add_u32 v117, 0x480, v2
	v_cmp_eq_u32 vcc, v0, v43
	v_cndmask_b32 v117, v38, v117, vcc
	v_cmp_gt_u32 vcc, v40, v117
	v_addc_co_u32 v115, vcc, 0, v115, vcc
	v_add_u32 v117, 0x4c0, v2
	v_cmp_eq_u32 vcc, v0, v41
	v_cndmask_b32 v117, v38, v117, vcc
	v_cmp_gt_u32 vcc, v40, v117
	v_addc_co_u32 v115, vcc, 0, v115, vcc
	v_add_u32 v117, 0x500, v2
	v_cmp_eq_u32 vcc, v0, v39
	v_cndmask_b32 v117, v38, v117, vcc
	v_cmp_gt_u32 vcc, v40, v117
	v_addc_co_u32 v115, vcc, 0, v115, vcc
	v_add_u32 v117, 0x540, v2
	v_cmp_eq_u32 vcc, v0, v37
	v_cndmask_b32 v117, v38, v117, vcc
	v_cmp_gt_u32 vcc, v40, v117
	v_addc_co_u32 v115, vcc, 0, v115, vcc
	v_add_u32 v117, 0x580, v2
	v_cmp_eq_u32 vcc, v0, v35
	v_cndmask_b32 v117, v38, v117, vcc
	v_cmp_gt_u32 vcc, v40, v117
	v_addc_co_u32 v115, vcc, 0, v115, vcc
	v_add_u32 v117, 0x5c0, v2
	v_cmp_eq_u32 vcc, v0, v33
	v_cndmask_b32 v117, v38, v117, vcc
	v_cmp_gt_u32 vcc, v40, v117
	v_addc_co_u32 v115, vcc, 0, v115, vcc
	v_add_u32 v117, 0x600, v2
	v_cmp_eq_u32 vcc, v0, v31
	v_cndmask_b32 v117, v38, v117, vcc
	v_cmp_gt_u32 vcc, v40, v117
	v_addc_co_u32 v115, vcc, 0, v115, vcc
	v_add_u32 v117, 0x640, v2
	v_cmp_eq_u32 vcc, v0, v29
	v_cndmask_b32 v117, v38, v117, vcc
	v_cmp_gt_u32 vcc, v40, v117
	v_addc_co_u32 v115, vcc, 0, v115, vcc
	v_add_u32 v117, 0x680, v2
	v_cmp_eq_u32 vcc, v0, v27
	v_cndmask_b32 v117, v38, v117, vcc
	v_cmp_gt_u32 vcc, v40, v117
	v_addc_co_u32 v115, vcc, 0, v115, vcc
	v_add_u32 v117, 0x6c0, v2
	v_cmp_eq_u32 vcc, v0, v25
	v_cndmask_b32 v117, v38, v117, vcc
	v_cmp_gt_u32 vcc, v40, v117
	v_addc_co_u32 v115, vcc, 0, v115, vcc
	v_add_u32 v117, 0x700, v2
	v_cmp_eq_u32 vcc, v0, v23
	v_cndmask_b32 v117, v38, v117, vcc
	v_cmp_gt_u32 vcc, v40, v117
	v_addc_co_u32 v115, vcc, 0, v115, vcc
	v_add_u32 v117, 0x740, v2
	v_cmp_eq_u32 vcc, v0, v21
	v_cndmask_b32 v117, v38, v117, vcc
	v_cmp_gt_u32 vcc, v40, v117
	v_addc_co_u32 v115, vcc, 0, v115, vcc
	v_add_u32 v117, 0x780, v2
	v_cmp_eq_u32 vcc, v0, v19
	v_cndmask_b32 v117, v38, v117, vcc
	v_cmp_gt_u32 vcc, v40, v117
	v_addc_co_u32 v115, vcc, 0, v115, vcc
	v_add_u32 v117, 0x7c0, v2
	v_cmp_eq_u32 vcc, v0, v17
	v_cndmask_b32 v117, v38, v117, vcc
	v_cmp_gt_u32 vcc, v40, v117
	v_addc_co_u32 v115, vcc, 0, v115, vcc
	v_add_u32 v117, 0x800, v2
	v_cmp_eq_u32 vcc, v0, v6
	v_cndmask_b32 v117, v38, v117, vcc
	v_cmp_gt_u32 vcc, v40, v117
	v_addc_co_u32 v115, vcc, 0, v115, vcc
	v_add_u32 v117, 0x840, v2
	v_cmp_eq_u32 vcc, v0, v4
	v_cndmask_b32 v117, v38, v117, vcc
	v_cmp_gt_u32 vcc, v40, v117
	v_addc_co_u32 v115, vcc, 0, v115, vcc
	v_add_u32 v117, 0x880, v2
	v_cmp_eq_u32 vcc, v0, v10
	v_cndmask_b32 v117, v38, v117, vcc
	v_cmp_gt_u32 vcc, v40, v117
	v_addc_co_u32 v115, vcc, 0, v115, vcc
	v_add_u32 v117, 0x8c0, v2
	v_cmp_eq_u32 vcc, v0, v8
	v_cndmask_b32 v117, v38, v117, vcc
	v_cmp_gt_u32 vcc, v40, v117
	v_addc_co_u32 v115, vcc, 0, v115, vcc
	v_add_u32 v117, 0x900, v2
	v_cmp_eq_u32 vcc, v0, v14
	v_cndmask_b32 v117, v38, v117, vcc
	v_cmp_gt_u32 vcc, v40, v117
	v_addc_co_u32 v115, vcc, 0, v115, vcc
	v_add_u32 v117, 0x940, v2
	v_cmp_eq_u32 vcc, v0, v12
	v_cndmask_b32 v117, v38, v117, vcc
	v_cmp_gt_u32 vcc, v40, v117
	v_addc_co_u32 v115, vcc, 0, v115, vcc
	v_add_u32 v117, 0x980, v2
	v_cmp_eq_u32 vcc, v0, v18
	v_cndmask_b32 v117, v38, v117, vcc
	v_cmp_gt_u32 vcc, v40, v117
	v_addc_co_u32 v115, vcc, 0, v115, vcc
	v_add_u32 v117, 0x9c0, v2
	v_cmp_eq_u32 vcc, v0, v16
; template <int NJ>
; DI void select_row(const float* row, int n, u64* bmrow, int lane) {
;     ...
;         const unsigned cand = X | (1u << bit);
;         int c = 0;
; #pragma unroll
;         for (int jj = 0; jj < NJ; ++jj) {
;           unsigned tmp;
;           asm volatile("v_add_u32 %1, %7, %5\n\tv_cmp_eq_u32 vcc, %2, %3\n\tv_cndmask_b32 %1, %4, %1, vcc\n\tv_cmp_gt_u32 vcc, %6, %1\n\tv_addc_co_u32 %0, vcc, 0, %0, vcc"
;                        : "+v"(c), "=&v"(tmp) : "s"(T), "v"(key[jj]), "v"(bigv), "v"(lane), "s"(cand), "n"(jj * 64) : "vcc");
;         }
;         c = wave_sum_i(c, lane);
;         if (c <= need) X = cand;
;       }
;     }
	v_cndmask_b32 v117, v38, v117, vcc
	v_cmp_gt_u32 vcc, v40, v117
	v_addc_co_u32 v115, vcc, 0, v115, vcc
	v_add_u32 v117, 0xa00, v2
	v_cmp_eq_u32 vcc, v0, v22
	v_cndmask_b32 v117, v38, v117, vcc
	v_cmp_gt_u32 vcc, v40, v117
	v_addc_co_u32 v115, vcc, 0, v115, vcc
	v_add_u32 v117, 0xa40, v2
	v_cmp_eq_u32 vcc, v0, v20
	v_cndmask_b32 v117, v38, v117, vcc
	v_cmp_gt_u32 vcc, v40, v117
	v_addc_co_u32 v115, vcc, 0, v115, vcc
	v_add_u32 v117, 0xa80, v2
	v_cmp_eq_u32 vcc, v0, v26
	v_cndmask_b32 v117, v38, v117, vcc
	v_cmp_gt_u32 vcc, v40, v117
	v_addc_co_u32 v115, vcc, 0, v115, vcc
	v_add_u32 v117, 0xac0, v2
	v_cmp_eq_u32 vcc, v0, v24
	v_cndmask_b32 v117, v38, v117, vcc
	v_cmp_gt_u32 vcc, v40, v117
	v_addc_co_u32 v115, vcc, 0, v115, vcc
	v_add_u32 v117, 0xb00, v2
	v_cmp_eq_u32 vcc, v0, v30
	v_cndmask_b32 v117, v38, v117, vcc
	v_cmp_gt_u32 vcc, v40, v117
	v_addc_co_u32 v115, vcc, 0, v115, vcc
	v_add_u32 v117, 0xb40, v2
	v_cmp_eq_u32 vcc, v0, v28
	v_cndmask_b32 v117, v38, v117, vcc
	v_cmp_gt_u32 vcc, v40, v117
	v_addc_co_u32 v115, vcc, 0, v115, vcc
	v_add_u32 v117, 0xb80, v2
	v_cmp_eq_u32 vcc, v0, v83
	v_cndmask_b32 v117, v38, v117, vcc
	v_cmp_gt_u32 vcc, v40, v117
	v_addc_co_u32 v115, vcc, 0, v115, vcc
	v_add_u32 v117, 0xbc0, v2
	v_cmp_eq_u32 vcc, v0, v81
	v_cndmask_b32 v117, v38, v117, vcc
	v_cmp_gt_u32 vcc, v40, v117
	v_addc_co_u32 v115, vcc, 0, v115, vcc
	v_add_u32 v117, 0xc00, v2
	v_cmp_eq_u32 vcc, v0, v87
	v_cndmask_b32 v117, v38, v117, vcc
	v_cmp_gt_u32 vcc, v40, v117
	v_addc_co_u32 v115, vcc, 0, v115, vcc
	v_add_u32 v117, 0xc40, v2
	v_cmp_eq_u32 vcc, v0, v85
	v_cndmask_b32 v117, v38, v117, vcc
	v_cmp_gt_u32 vcc, v40, v117
	v_addc_co_u32 v115, vcc, 0, v115, vcc
	v_add_u32 v117, 0xc80, v2
	v_cmp_eq_u32 vcc, v0, v91
	v_cndmask_b32 v117, v38, v117, vcc
	v_cmp_gt_u32 vcc, v40, v117
	v_addc_co_u32 v115, vcc, 0, v115, vcc
	v_add_u32 v117, 0xcc0, v2
	v_cmp_eq_u32 vcc, v0, v89
	v_cndmask_b32 v117, v38, v117, vcc
	v_cmp_gt_u32 vcc, v40, v117
	v_addc_co_u32 v115, vcc, 0, v115, vcc
	v_add_u32 v117, 0xd00, v2
	v_cmp_eq_u32 vcc, v0, v95
	v_cndmask_b32 v117, v38, v117, vcc
	v_cmp_gt_u32 vcc, v40, v117
	v_addc_co_u32 v115, vcc, 0, v115, vcc
	v_add_u32 v117, 0xd40, v2
	v_cmp_eq_u32 vcc, v0, v93
	v_cndmask_b32 v117, v38, v117, vcc
	v_cmp_gt_u32 vcc, v40, v117
	v_addc_co_u32 v115, vcc, 0, v115, vcc
	v_add_u32 v117, 0xd80, v2
	v_cmp_eq_u32 vcc, v0, v99
	v_cndmask_b32 v117, v38, v117, vcc
	v_cmp_gt_u32 vcc, v40, v117
	v_addc_co_u32 v115, vcc, 0, v115, vcc
	v_add_u32 v117, 0xdc0, v2
	v_cmp_eq_u32 vcc, v0, v97
	v_cndmask_b32 v117, v38, v117, vcc
	v_cmp_gt_u32 vcc, v40, v117
	v_addc_co_u32 v115, vcc, 0, v115, vcc
	v_add_u32 v117, 0xe00, v2
	v_cmp_eq_u32 vcc, v0, v32
	v_cndmask_b32 v117, v38, v117, vcc
	v_cmp_gt_u32 vcc, v40, v117
	v_addc_co_u32 v115, vcc, 0, v115, vcc
	v_add_u32 v117, 0xe40, v2
	v_cmp_eq_u32 vcc, v0, v101
	v_cndmask_b32 v117, v38, v117, vcc
	v_cmp_gt_u32 vcc, v40, v117
	v_addc_co_u32 v115, vcc, 0, v115, vcc
	v_add_u32 v117, 0xe80, v2
	v_cmp_eq_u32 vcc, v0, v105
	v_cndmask_b32 v117, v38, v117, vcc
	v_cmp_gt_u32 vcc, v40, v117
	v_addc_co_u32 v115, vcc, 0, v115, vcc
	v_add_u32 v117, 0xec0, v2
	v_cmp_eq_u32 vcc, v0, v103
	v_cndmask_b32 v117, v38, v117, vcc
	v_cmp_gt_u32 vcc, v40, v117
	v_addc_co_u32 v115, vcc, 0, v115, vcc
	v_add_u32 v117, 0xf00, v2
	v_cmp_eq_u32 vcc, v0, v109
	v_cndmask_b32 v117, v38, v117, vcc
	v_cmp_gt_u32 vcc, v40, v117
	v_addc_co_u32 v115, vcc, 0, v115, vcc
	v_add_u32 v117, 0xf40, v2
	v_cmp_eq_u32 vcc, v0, v107
	v_cndmask_b32 v117, v38, v117, vcc
	v_cmp_gt_u32 vcc, v40, v117
	v_addc_co_u32 v115, vcc, 0, v115, vcc
	v_add_u32 v117, 0xf80, v2
	v_cmp_eq_u32 vcc, v0, v113
	v_cndmask_b32 v117, v38, v117, vcc
	v_cmp_gt_u32 vcc, v40, v117
	v_addc_co_u32 v115, vcc, 0, v115, vcc
	v_add_u32 v117, 0xfc0, v2
	v_cmp_eq_u32 vcc, v0, v111
	v_cndmask_b32 v117, v38, v117, vcc
	v_cmp_gt_u32 vcc, v40, v117
	v_addc_co_u32 v115, vcc, 0, v115, vcc
	s_nop 1
	v_add_u32_dpp v115, v115, v115 row_shr:1 row_mask:0xf bank_mask:0xf bound_ctrl:0
	s_nop 1
	v_add_u32_dpp v115, v115, v115 row_shr:2 row_mask:0xf bank_mask:0xf bound_ctrl:0
	s_nop 1
	v_add_u32_dpp v115, v115, v115 row_shr:4 row_mask:0xf bank_mask:0xf bound_ctrl:0
	s_nop 1
	v_add_u32_dpp v115, v115, v115 row_shr:8 row_mask:0xf bank_mask:0xf bound_ctrl:0
	s_nop 1
	v_add_u32_dpp v115, v115, v115 row_bcast:15 row_mask:0xa bank_mask:0xf
	s_nop 1
	v_add_u32_dpp v115, v115, v115 row_bcast:31 row_mask:0xc bank_mask:0xf
	s_nop 1
	v_readlane_b32 s98, v115, 63
	s_nop 1
	v_mov_b32_e32 v115, s98
	v_cmp_gt_i32_e32 vcc, v115, v34
	s_nop 1
	v_cndmask_b32_e32 v36, v40, v36, vcc
	s_cbranch_scc1 .LBB0_811

; template <int NJ>
; DI void select_row(const float* row, int n, u64* bmrow, int lane) {
;     ...
;   unsigned kl0 = 0, kh0 = 0, kl1 = 0, kh1 = 0;
;   unsigned T1v = T + 1, Tv = T;
;   asm volatile("" : "+v"(Tv), "+v"(T1v));
; #pragma unroll
;   for (int jj = 0; jj < NJ; ++jj) {
;     unsigned tmp;
;     if (jj < 64)
;       asm volatile("v_add_u32 %2, %9, %4\n\tv_cmp_gt_u32 vcc, %3, %2\n\tv_cndmask_b32 %2, %5, %6, vcc\n\tv_cmp_ge_u32 vcc, %7, %2\n\ts_nop 3\n\tv_writelane_b32 %0, vcc_lo, %8\n\tv_writelane_b32 %1, vcc_hi, %8"
;                    : "+v"(kl0), "+v"(kh0), "=&v"(tmp) : "s"(X), "v"(lane), "v"(T1v), "v"(Tv), "v"(key[jj]), "n"(jj & 63), "n"(jj * 64) : "vcc");
;     else
;       asm volatile("v_add_u32 %2, %9, %4\n\tv_cmp_gt_u32 vcc, %3, %2\n\tv_cndmask_b32 %2, %5, %6, vcc\n\tv_cmp_ge_u32 vcc, %7, %2\n\ts_nop 3\n\tv_writelane_b32 %0, vcc_lo, %8\n\tv_writelane_b32 %1, vcc_hi, %8"
;                    : "+v"(kl1), "+v"(kh1), "=&v"(tmp) : "s"(X), "v"(lane), "v"(T1v), "v"(Tv), "v"(key[jj]), "n"(jj & 63), "n"(jj * 64) : "vcc");
;   }
;   bmrow[lane] = ((u64)kh0 << 32) | kl0; bmrow[64 + lane] = ((u64)kh1 << 32) | kl1;
.LBB0_813:
	s_or_b64 exec, exec, s[6:7]
	v_add_u32_e32 v0, 1, v34
	v_mov_b32_e32 v230, v1
	v_mov_b32_e32 v231, v1
	v_mov_b64_e32 v[232:233], 0
	v_add_u32 v38, 0, v2
	v_cmp_gt_u32 vcc, v36, v38
	v_cndmask_b32 v38, v0, v34, vcc
	v_cmp_ge_u32 vcc, v79, v38
	s_nop 3
	v_writelane_b32 v230, vcc_lo, 0
	v_writelane_b32 v231, vcc_hi, 0
	v_add_u32 v38, 64, v2
	v_cmp_gt_u32 vcc, v36, v38
	v_cndmask_b32 v38, v0, v34, vcc
	v_cmp_ge_u32 vcc, v77, v38
	s_nop 3
	v_writelane_b32 v230, vcc_lo, 1
	v_writelane_b32 v231, vcc_hi, 1
	v_add_u32 v38, 0x80, v2
	v_cmp_gt_u32 vcc, v36, v38
	v_cndmask_b32 v38, v0, v34, vcc
	v_cmp_ge_u32 vcc, v75, v38
	s_nop 3
	v_writelane_b32 v230, vcc_lo, 2
	v_writelane_b32 v231, vcc_hi, 2
	v_add_u32 v38, 0xc0, v2
	v_cmp_gt_u32 vcc, v36, v38
	v_cndmask_b32 v38, v0, v34, vcc
	v_cmp_ge_u32 vcc, v73, v38
	s_nop 3
	v_writelane_b32 v230, vcc_lo, 3
	v_writelane_b32 v231, vcc_hi, 3
	v_add_u32 v38, 0x100, v2
	v_cmp_gt_u32 vcc, v36, v38
	v_cndmask_b32 v38, v0, v34, vcc
	v_cmp_ge_u32 vcc, v71, v38
	s_nop 3
	v_writelane_b32 v230, vcc_lo, 4
	v_writelane_b32 v231, vcc_hi, 4
	v_add_u32 v38, 0x140, v2
	v_cmp_gt_u32 vcc, v36, v38
	v_cndmask_b32 v38, v0, v34, vcc
	v_cmp_ge_u32 vcc, v69, v38
	s_nop 3
	v_writelane_b32 v230, vcc_lo, 5
	v_writelane_b32 v231, vcc_hi, 5
	v_add_u32 v38, 0x180, v2
	v_cmp_gt_u32 vcc, v36, v38
	v_cndmask_b32 v38, v0, v34, vcc
	v_cmp_ge_u32 vcc, v67, v38
	s_nop 3
	v_writelane_b32 v230, vcc_lo, 6
	v_writelane_b32 v231, vcc_hi, 6
	v_add_u32 v38, 0x1c0, v2
	v_cmp_gt_u32 vcc, v36, v38
	v_cndmask_b32 v38, v0, v34, vcc
	v_cmp_ge_u32 vcc, v65, v38
	s_nop 3
	v_writelane_b32 v230, vcc_lo, 7
	v_writelane_b32 v231, vcc_hi, 7
	v_add_u32 v38, 0x200, v2
	v_cmp_gt_u32 vcc, v36, v38
	v_cndmask_b32 v38, v0, v34, vcc
	v_cmp_ge_u32 vcc, v63, v38
	s_nop 3
	v_writelane_b32 v230, vcc_lo, 8
	v_writelane_b32 v231, vcc_hi, 8
	v_add_u32 v38, 0x240, v2
	v_cmp_gt_u32 vcc, v36, v38
	v_cndmask_b32 v38, v0, v34, vcc
	v_cmp_ge_u32 vcc, v61, v38
	s_nop 3
	v_writelane_b32 v230, vcc_lo, 9
	v_writelane_b32 v231, vcc_hi, 9
	v_add_u32 v38, 0x280, v2
	v_cmp_gt_u32 vcc, v36, v38
	v_cndmask_b32 v38, v0, v34, vcc
	v_cmp_ge_u32 vcc, v59, v38
	s_nop 3
	v_writelane_b32 v230, vcc_lo, 10
	v_writelane_b32 v231, vcc_hi, 10
	v_add_u32 v38, 0x2c0, v2
	v_cmp_gt_u32 vcc, v36, v38
	v_cndmask_b32 v38, v0, v34, vcc
	v_cmp_ge_u32 vcc, v57, v38
	s_nop 3
	v_writelane_b32 v230, vcc_lo, 11
	v_writelane_b32 v231, vcc_hi, 11
	v_add_u32 v38, 0x300, v2
	v_cmp_gt_u32 vcc, v36, v38
	v_cndmask_b32 v38, v0, v34, vcc
	v_cmp_ge_u32 vcc, v55, v38
	s_nop 3
	v_writelane_b32 v230, vcc_lo, 12
	v_writelane_b32 v231, vcc_hi, 12
	v_add_u32 v38, 0x340, v2
	v_cmp_gt_u32 vcc, v36, v38
	v_cndmask_b32 v38, v0, v34, vcc
	v_cmp_ge_u32 vcc, v51, v38
	s_nop 3
	v_writelane_b32 v230, vcc_lo, 13
	v_writelane_b32 v231, vcc_hi, 13
	v_add_u32 v38, 0x380, v2
	v_cmp_gt_u32 vcc, v36, v38
	v_cndmask_b32 v38, v0, v34, vcc
	v_cmp_ge_u32 vcc, v53, v38
	s_nop 3
	v_writelane_b32 v230, vcc_lo, 14
	v_writelane_b32 v231, vcc_hi, 14
	v_add_u32 v38, 0x3c0, v2
	v_cmp_gt_u32 vcc, v36, v38
	v_cndmask_b32 v38, v0, v34, vcc
	v_cmp_ge_u32 vcc, v49, v38
	s_nop 3
	v_writelane_b32 v230, vcc_lo, 15
	v_writelane_b32 v231, vcc_hi, 15
	v_add_u32 v38, 0x400, v2
	v_cmp_gt_u32 vcc, v36, v38
	v_cndmask_b32 v38, v0, v34, vcc
	v_cmp_ge_u32 vcc, v47, v38
	s_nop 3
	v_writelane_b32 v230, vcc_lo, 16
	v_writelane_b32 v231, vcc_hi, 16
	v_add_u32 v38, 0x440, v2
	v_cmp_gt_u32 vcc, v36, v38
	v_cndmask_b32 v38, v0, v34, vcc
	v_cmp_ge_u32 vcc, v45, v38
	s_nop 3
	v_writelane_b32 v230, vcc_lo, 17
	v_writelane_b32 v231, vcc_hi, 17
	v_add_u32 v38, 0x480, v2
	v_cmp_gt_u32 vcc, v36, v38
	v_cndmask_b32 v38, v0, v34, vcc
	v_cmp_ge_u32 vcc, v43, v38
	s_nop 3
	v_writelane_b32 v230, vcc_lo, 18
	v_writelane_b32 v231, vcc_hi, 18
	v_add_u32 v38, 0x4c0, v2
	v_cmp_gt_u32 vcc, v36, v38
	v_cndmask_b32 v38, v0, v34, vcc
	v_cmp_ge_u32 vcc, v41, v38
	s_nop 3
	v_writelane_b32 v230, vcc_lo, 19
	v_writelane_b32 v231, vcc_hi, 19
	v_add_u32 v38, 0x500, v2
	v_cmp_gt_u32 vcc, v36, v38
	v_cndmask_b32 v38, v0, v34, vcc
	v_cmp_ge_u32 vcc, v39, v38
	s_nop 3
	v_writelane_b32 v230, vcc_lo, 20
	v_writelane_b32 v231, vcc_hi, 20
	v_add_u32 v38, 0x540, v2
	v_cmp_gt_u32 vcc, v36, v38
	v_cndmask_b32 v38, v0, v34, vcc
	v_cmp_ge_u32 vcc, v37, v38
	s_nop 3
	v_writelane_b32 v230, vcc_lo, 21
	v_writelane_b32 v231, vcc_hi, 21
	v_add_u32 v37, 0x580, v2
	v_cmp_gt_u32 vcc, v36, v37
	v_cndmask_b32 v37, v0, v34, vcc
	v_cmp_ge_u32 vcc, v35, v37
	s_nop 3
	v_writelane_b32 v230, vcc_lo, 22
	v_writelane_b32 v231, vcc_hi, 22
	v_add_u32 v35, 0x5c0, v2
	v_cmp_gt_u32 vcc, v36, v35
	v_cndmask_b32 v35, v0, v34, vcc
	v_cmp_ge_u32 vcc, v33, v35
	s_nop 3
	v_writelane_b32 v230, vcc_lo, 23
	v_writelane_b32 v231, vcc_hi, 23
	v_add_u32 v33, 0x600, v2
	v_cmp_gt_u32 vcc, v36, v33
	v_cndmask_b32 v33, v0, v34, vcc
	v_cmp_ge_u32 vcc, v31, v33
	s_nop 3
	v_writelane_b32 v230, vcc_lo, 24
	v_writelane_b32 v231, vcc_hi, 24
	v_add_u32 v31, 0x640, v2
	v_cmp_gt_u32 vcc, v36, v31
	v_cndmask_b32 v31, v0, v34, vcc
	v_cmp_ge_u32 vcc, v29, v31
	s_nop 3
	v_writelane_b32 v230, vcc_lo, 25
	v_writelane_b32 v231, vcc_hi, 25
	v_add_u32 v29, 0x680, v2
	v_cmp_gt_u32 vcc, v36, v29
	v_cndmask_b32 v29, v0, v34, vcc
	v_cmp_ge_u32 vcc, v27, v29
	s_nop 3
	v_writelane_b32 v230, vcc_lo, 26
	v_writelane_b32 v231, vcc_hi, 26
	v_add_u32 v27, 0x6c0, v2
	v_cmp_gt_u32 vcc, v36, v27
	v_cndmask_b32 v27, v0, v34, vcc
	v_cmp_ge_u32 vcc, v25, v27
	s_nop 3
	v_writelane_b32 v230, vcc_lo, 27
	v_writelane_b32 v231, vcc_hi, 27
	v_add_u32 v25, 0x700, v2
	v_cmp_gt_u32 vcc, v36, v25
	v_cndmask_b32 v25, v0, v34, vcc
	v_cmp_ge_u32 vcc, v23, v25
	s_nop 3
	v_writelane_b32 v230, vcc_lo, 28
; template <int NJ>
; DI void select_row(const float* row, int n, u64* bmrow, int lane) {
;     ...
;   unsigned kl0 = 0, kh0 = 0, kl1 = 0, kh1 = 0;
;   unsigned T1v = T + 1, Tv = T;
;   asm volatile("" : "+v"(Tv), "+v"(T1v));
; #pragma unroll
;   for (int jj = 0; jj < NJ; ++jj) {
;     unsigned tmp;
;     if (jj < 64)
;       asm volatile("v_add_u32 %2, %9, %4\n\tv_cmp_gt_u32 vcc, %3, %2\n\tv_cndmask_b32 %2, %5, %6, vcc\n\tv_cmp_ge_u32 vcc, %7, %2\n\ts_nop 3\n\tv_writelane_b32 %0, vcc_lo, %8\n\tv_writelane_b32 %1, vcc_hi, %8"
;                    : "+v"(kl0), "+v"(kh0), "=&v"(tmp) : "s"(X), "v"(lane), "v"(T1v), "v"(Tv), "v"(key[jj]), "n"(jj & 63), "n"(jj * 64) : "vcc");
;     else
;       asm volatile("v_add_u32 %2, %9, %4\n\tv_cmp_gt_u32 vcc, %3, %2\n\tv_cndmask_b32 %2, %5, %6, vcc\n\tv_cmp_ge_u32 vcc, %7, %2\n\ts_nop 3\n\tv_writelane_b32 %0, vcc_lo, %8\n\tv_writelane_b32 %1, vcc_hi, %8"
;                    : "+v"(kl1), "+v"(kh1), "=&v"(tmp) : "s"(X), "v"(lane), "v"(T1v), "v"(Tv), "v"(key[jj]), "n"(jj & 63), "n"(jj * 64) : "vcc");
;   }
;   bmrow[lane] = ((u64)kh0 << 32) | kl0; bmrow[64 + lane] = ((u64)kh1 << 32) | kl1;
; DI void select_phase(const Params& p) {
;     ...
;   for (int base = 0; base < NTOK; base += nw, ++it) {
;     const int rowi = base + ((it & 1) ? (nw - 1 - gw) : gw);
;     if (rowi >= NTOK) continue;
;     const int b = rowi >> 13, t = rowi & 8191, blk = t >> 6, rr = t & 63, n = (blk + 1) * 64;
;     const float* row = SC + (size_t)b * SCB + (size_t)2048 * blk * (blk + 1) + (size_t)rr * n;
;     u64* bmrow = BM + (size_t)rowi * 128;
;     if (n <= 256) {
;       const int nwd = n >> 6;
;       bmrow[lane] = (lane < nwd) ? ~0ull : 0ull; bmrow[64 + lane] = 0ull;
;     } else if (n <= 2048) select_row<32>(row, n, bmrow, lane);
;     else if (n <= 4096) select_row<64>(row, n, bmrow, lane);
;     else select_row<128>(row, n, bmrow, lane);
;   }
	v_writelane_b32 v231, vcc_hi, 28
	v_add_u32 v23, 0x740, v2
	v_cmp_gt_u32 vcc, v36, v23
	v_cndmask_b32 v23, v0, v34, vcc
	v_cmp_ge_u32 vcc, v21, v23
	s_nop 3
	v_writelane_b32 v230, vcc_lo, 29
	v_writelane_b32 v231, vcc_hi, 29
	v_add_u32 v21, 0x780, v2
	v_cmp_gt_u32 vcc, v36, v21
	v_cndmask_b32 v21, v0, v34, vcc
	v_cmp_ge_u32 vcc, v19, v21
	s_nop 3
	v_writelane_b32 v230, vcc_lo, 30
	v_writelane_b32 v231, vcc_hi, 30
	v_add_u32 v19, 0x7c0, v2
	v_cmp_gt_u32 vcc, v36, v19
	v_cndmask_b32 v19, v0, v34, vcc
	v_cmp_ge_u32 vcc, v17, v19
	s_nop 3
	v_writelane_b32 v230, vcc_lo, 31
	v_writelane_b32 v231, vcc_hi, 31
	v_add_u32 v17, 0x800, v2
	v_cmp_gt_u32 vcc, v36, v17
	v_cndmask_b32 v17, v0, v34, vcc
	v_cmp_ge_u32 vcc, v6, v17
	s_nop 3
	v_writelane_b32 v230, vcc_lo, 32
	v_writelane_b32 v231, vcc_hi, 32
	v_add_u32 v6, 0x840, v2
	v_cmp_gt_u32 vcc, v36, v6
	v_cndmask_b32 v6, v0, v34, vcc
	v_cmp_ge_u32 vcc, v4, v6
	s_nop 3
	v_writelane_b32 v230, vcc_lo, 33
	v_writelane_b32 v231, vcc_hi, 33
	v_add_u32 v4, 0x880, v2
	v_cmp_gt_u32 vcc, v36, v4
	v_cndmask_b32 v4, v0, v34, vcc
	v_cmp_ge_u32 vcc, v10, v4
	s_nop 3
	v_writelane_b32 v230, vcc_lo, 34
	v_writelane_b32 v231, vcc_hi, 34
	v_add_u32 v4, 0x8c0, v2
	v_cmp_gt_u32 vcc, v36, v4
	v_cndmask_b32 v4, v0, v34, vcc
	v_cmp_ge_u32 vcc, v8, v4
	s_nop 3
	v_writelane_b32 v230, vcc_lo, 35
	v_writelane_b32 v231, vcc_hi, 35
	v_add_u32 v4, 0x900, v2
	v_cmp_gt_u32 vcc, v36, v4
	v_cndmask_b32 v4, v0, v34, vcc
	v_cmp_ge_u32 vcc, v14, v4
	s_nop 3
	v_writelane_b32 v230, vcc_lo, 36
	v_writelane_b32 v231, vcc_hi, 36
	v_add_u32 v4, 0x940, v2
	v_cmp_gt_u32 vcc, v36, v4
	v_cndmask_b32 v4, v0, v34, vcc
	v_cmp_ge_u32 vcc, v12, v4
	s_nop 3
	v_writelane_b32 v230, vcc_lo, 37
	v_writelane_b32 v231, vcc_hi, 37
	v_add_u32 v4, 0x980, v2
	v_cmp_gt_u32 vcc, v36, v4
	v_cndmask_b32 v4, v0, v34, vcc
	v_cmp_ge_u32 vcc, v18, v4
	s_nop 3
	v_writelane_b32 v230, vcc_lo, 38
	v_writelane_b32 v231, vcc_hi, 38
	v_add_u32 v4, 0x9c0, v2
	v_cmp_gt_u32 vcc, v36, v4
	v_cndmask_b32 v4, v0, v34, vcc
	v_cmp_ge_u32 vcc, v16, v4
	s_nop 3
	v_writelane_b32 v230, vcc_lo, 39
	v_writelane_b32 v231, vcc_hi, 39
	v_add_u32 v4, 0xa00, v2
	v_cmp_gt_u32 vcc, v36, v4
	v_cndmask_b32 v4, v0, v34, vcc
	v_cmp_ge_u32 vcc, v22, v4
	s_nop 3
	v_writelane_b32 v230, vcc_lo, 40
	v_writelane_b32 v231, vcc_hi, 40
	v_add_u32 v4, 0xa40, v2
	v_cmp_gt_u32 vcc, v36, v4
	v_cndmask_b32 v4, v0, v34, vcc
	v_cmp_ge_u32 vcc, v20, v4
	s_nop 3
	v_writelane_b32 v230, vcc_lo, 41
	v_writelane_b32 v231, vcc_hi, 41
	v_add_u32 v4, 0xa80, v2
	v_cmp_gt_u32 vcc, v36, v4
	v_cndmask_b32 v4, v0, v34, vcc
	v_cmp_ge_u32 vcc, v26, v4
	s_nop 3
	v_writelane_b32 v230, vcc_lo, 42
	v_writelane_b32 v231, vcc_hi, 42
	v_add_u32 v4, 0xac0, v2
	v_cmp_gt_u32 vcc, v36, v4
	v_cndmask_b32 v4, v0, v34, vcc
	v_cmp_ge_u32 vcc, v24, v4
	s_nop 3
	v_writelane_b32 v230, vcc_lo, 43
	v_writelane_b32 v231, vcc_hi, 43
	v_add_u32 v4, 0xb00, v2
	v_cmp_gt_u32 vcc, v36, v4
	v_cndmask_b32 v4, v0, v34, vcc
	v_cmp_ge_u32 vcc, v30, v4
	s_nop 3
	v_writelane_b32 v230, vcc_lo, 44
	v_writelane_b32 v231, vcc_hi, 44
	v_add_u32 v4, 0xb40, v2
	v_cmp_gt_u32 vcc, v36, v4
	v_cndmask_b32 v4, v0, v34, vcc
	v_cmp_ge_u32 vcc, v28, v4
	s_nop 3
	v_writelane_b32 v230, vcc_lo, 45
	v_writelane_b32 v231, vcc_hi, 45
	v_add_u32 v4, 0xb80, v2
	v_cmp_gt_u32 vcc, v36, v4
	v_cndmask_b32 v4, v0, v34, vcc
	v_cmp_ge_u32 vcc, v83, v4
	s_nop 3
	v_writelane_b32 v230, vcc_lo, 46
	v_writelane_b32 v231, vcc_hi, 46
	v_add_u32 v4, 0xbc0, v2
	v_cmp_gt_u32 vcc, v36, v4
	v_cndmask_b32 v4, v0, v34, vcc
	v_cmp_ge_u32 vcc, v81, v4
	s_nop 3
	v_writelane_b32 v230, vcc_lo, 47
	v_writelane_b32 v231, vcc_hi, 47
	v_add_u32 v4, 0xc00, v2
	v_cmp_gt_u32 vcc, v36, v4
	v_cndmask_b32 v4, v0, v34, vcc
	v_cmp_ge_u32 vcc, v87, v4
	s_nop 3
	v_writelane_b32 v230, vcc_lo, 48
	v_writelane_b32 v231, vcc_hi, 48
	v_add_u32 v4, 0xc40, v2
	v_cmp_gt_u32 vcc, v36, v4
	v_cndmask_b32 v4, v0, v34, vcc
	v_cmp_ge_u32 vcc, v85, v4
	s_nop 3
	v_writelane_b32 v230, vcc_lo, 49
	v_writelane_b32 v231, vcc_hi, 49
	v_add_u32 v4, 0xc80, v2
	v_cmp_gt_u32 vcc, v36, v4
	v_cndmask_b32 v4, v0, v34, vcc
	v_cmp_ge_u32 vcc, v91, v4
	s_nop 3
	v_writelane_b32 v230, vcc_lo, 50
	v_writelane_b32 v231, vcc_hi, 50
	v_add_u32 v4, 0xcc0, v2
	v_cmp_gt_u32 vcc, v36, v4
	v_cndmask_b32 v4, v0, v34, vcc
	v_cmp_ge_u32 vcc, v89, v4
	s_nop 3
	v_writelane_b32 v230, vcc_lo, 51
	v_writelane_b32 v231, vcc_hi, 51
	v_add_u32 v4, 0xd00, v2
	v_cmp_gt_u32 vcc, v36, v4
	v_cndmask_b32 v4, v0, v34, vcc
	v_cmp_ge_u32 vcc, v95, v4
	s_nop 3
	v_writelane_b32 v230, vcc_lo, 52
	v_writelane_b32 v231, vcc_hi, 52
	v_add_u32 v4, 0xd40, v2
	v_cmp_gt_u32 vcc, v36, v4
	v_cndmask_b32 v4, v0, v34, vcc
	v_cmp_ge_u32 vcc, v93, v4
	s_nop 3
	v_writelane_b32 v230, vcc_lo, 53
	v_writelane_b32 v231, vcc_hi, 53
	v_add_u32 v4, 0xd80, v2
	v_cmp_gt_u32 vcc, v36, v4
	v_cndmask_b32 v4, v0, v34, vcc
	v_cmp_ge_u32 vcc, v99, v4
	s_nop 3
	v_writelane_b32 v230, vcc_lo, 54
	v_writelane_b32 v231, vcc_hi, 54
	v_add_u32 v4, 0xdc0, v2
	v_cmp_gt_u32 vcc, v36, v4
	v_cndmask_b32 v4, v0, v34, vcc
	v_cmp_ge_u32 vcc, v97, v4
	s_nop 3
	v_writelane_b32 v230, vcc_lo, 55
	v_writelane_b32 v231, vcc_hi, 55
	v_add_u32 v4, 0xe00, v2
	v_cmp_gt_u32 vcc, v36, v4
	v_cndmask_b32 v4, v0, v34, vcc
	v_cmp_ge_u32 vcc, v32, v4
	s_nop 3
	v_writelane_b32 v230, vcc_lo, 56
	v_writelane_b32 v231, vcc_hi, 56
	v_add_u32 v4, 0xe40, v2
	v_cmp_gt_u32 vcc, v36, v4
	v_cndmask_b32 v4, v0, v34, vcc
	v_cmp_ge_u32 vcc, v101, v4
	s_nop 3
	v_writelane_b32 v230, vcc_lo, 57
	v_writelane_b32 v231, vcc_hi, 57
	v_add_u32 v4, 0xe80, v2
	v_cmp_gt_u32 vcc, v36, v4
	v_cndmask_b32 v4, v0, v34, vcc
	v_cmp_ge_u32 vcc, v105, v4
	s_nop 3
	v_writelane_b32 v230, vcc_lo, 58
	v_writelane_b32 v231, vcc_hi, 58
	v_add_u32 v4, 0xec0, v2
	v_cmp_gt_u32 vcc, v36, v4
	v_cndmask_b32 v4, v0, v34, vcc
	v_cmp_ge_u32 vcc, v103, v4
	s_nop 3
	v_writelane_b32 v230, vcc_lo, 59
	v_writelane_b32 v231, vcc_hi, 59
	v_add_u32 v4, 0xf00, v2
	v_cmp_gt_u32 vcc, v36, v4
	v_cndmask_b32 v4, v0, v34, vcc
	v_cmp_ge_u32 vcc, v109, v4
	s_nop 3
	v_writelane_b32 v230, vcc_lo, 60
	v_writelane_b32 v231, vcc_hi, 60
	v_add_u32 v4, 0xf40, v2
	v_cmp_gt_u32 vcc, v36, v4
	v_cndmask_b32 v4, v0, v34, vcc
	v_cmp_ge_u32 vcc, v107, v4
	s_nop 3
	v_writelane_b32 v230, vcc_lo, 61
	v_writelane_b32 v231, vcc_hi, 61
	v_add_u32 v4, 0xf80, v2
	v_cmp_gt_u32 vcc, v36, v4
	v_cndmask_b32 v4, v0, v34, vcc
	v_cmp_ge_u32 vcc, v113, v4
	s_nop 3
	v_writelane_b32 v230, vcc_lo, 62
	v_writelane_b32 v231, vcc_hi, 62
	v_add_u32 v4, 0xfc0, v2
	v_cmp_gt_u32 vcc, v36, v4
	v_cndmask_b32 v4, v0, v34, vcc
	v_cmp_ge_u32 vcc, v111, v4
	s_nop 3
	v_writelane_b32 v230, vcc_lo, 63
	v_writelane_b32 v231, vcc_hi, 63
	v_lshlrev_b32_e32 v0, 3, v2
	v_lshl_add_u64 v[16:17], v[228:229], 0, v[0:1]
	global_store_dwordx2 v[16:17], v[230:231], off
	s_or_b64 exec, exec, s[18:19]
	s_andn2_saveexec_b64 s[16:17], s[16:17]
	s_cbranch_execnz .LBB0_727
	s_branch .LBB0_801

; #define BID opqs((int)blockIdx.x)
; DI void score_phase(const Params& p, char* smem) {
;     ...
;   for (int idx = BID; idx < 512; idx += gridDim.x) {
;     const int half = idx & 1, b = (idx >> 1) & 1, t = idx >> 2;
;     const int blk = (t < 64) ? (127 - t) : (t - 64);
;     const int n = (blk + 1) * 64, ntile = n >> 5;
;     const int nt_lo = half ? (ntile >> 1) : 0, nt_hi = half ? ntile : (ntile >> 1);
;     const int t0 = blk * 64 + wave * 8;
;     const u16* Hb = H + (size_t)b * S_ * HLD;
;     bf16x8 af[4][4];
; #pragma unroll
;     for (int rt = 0; rt < 4; ++rt) {
;       const int tokA = t0 + 2 * rt + ((r >> 2) & 1), head = (r >> 3) * 4 + (r & 3);
; #pragma unroll
;       for (int st = 0; st < 4; ++st) af[rt][st] = *(const bf16x8*)(Hb + (size_t)tokA * HLD + 3072 + head * 64 + st * 16 + 8 * h);
;     }
;     wl[lane] = AUX[(size_t)(b * S_ + t0) * 16 + lane] * 0.125f;
;     wl[64 + lane] = AUX[(size_t)(b * S_ + t0) * 16 + 64 + lane] * 0.125f;
;     __syncthreads();
;     float* scb = SC + (size_t)b * SCB + (size_t)2048 * blk * (blk + 1);
;     bf16x8 bfr[4], bnx[4];
; #pragma unroll
;     for (int st = 0; st < 4; ++st) bfr[st] = *(const bf16x8*)(Hb + (size_t)(nt_lo * 32 + r) * HLD + 4096 + st * 16 + 8 * h);
; #pragma unroll 1
;     for (int nt2 = nt_lo; nt2 < nt_hi; ++nt2) {
;       const int k0 = nt2 * 32;
;       const int kn = (nt2 + 1 < nt_hi) ? (k0 + 32) : k0;
; #pragma unroll
;       for (int st = 0; st < 4; ++st) bnx[st] = *(const bf16x8*)(Hb + (size_t)(kn + r) * HLD + 4096 + st * 16 + 8 * h);
.LBB0_820:
	s_ashr_i32 s7, s10, 2
	s_and_b32 s16, s10, 1
	s_bfe_i32 s6, s10, 0x10000
	s_bfe_u32 s8, s10, 0x10001
	s_sub_i32 s9, 0x7f, s7
	s_sub_i32 s15, s7, 64
	s_cmp_lt_i32 s7, 64
	s_cselect_b32 s18, s9, s15
	s_add_i32 s9, s18, 1
	s_and_b32 s15, s6, s9
	s_lshl_b32 s17, s18, 6
	s_mul_i32 s6, s8, 0x5400000
	s_add_u32 s6, s11, s6
	v_add_u32_e32 v2, s17, v198
	s_addc_u32 s7, s12, 0
	v_or_b32_e32 v3, v2, v199
	v_mov_b64_e32 v[4:5], s[6:7]
	s_movk_i32 s22, 0x2a00
	v_mad_i64_i32 v[6:7], s[20:21], v3, s22, v[4:5]
	v_mov_b32_e32 v183, v1
	v_lshl_add_u64 v[6:7], v[6:7], 0, v[182:183]
	v_lshl_add_u64 v[6:7], v[6:7], 0, v[0:1]
	s_mov_b64 s[24:25], 0x1800
	s_movk_i32 s19, 0x1000
	v_lshl_add_u64 v[8:9], v[6:7], 0, s[24:25]
	v_add_co_u32_e32 v6, vcc, s19, v6
	s_lshl_b32 s16, s9, s16
	s_nop 0
	v_addc_co_u32_e32 v7, vcc, 0, v7, vcc
	global_load_dwordx4 v[18:21], v[8:9], off offset:32
	global_load_dwordx4 v[22:25], v[8:9], off offset:64
	global_load_dwordx4 v[26:29], v[6:7], off offset:2048
	global_load_dwordx4 v[30:33], v[8:9], off offset:96
	v_or_b32_e32 v6, 2, v3
	v_mad_i64_i32 v[6:7], s[20:21], v6, s22, v[4:5]
	v_lshl_add_u64 v[6:7], v[6:7], 0, v[182:183]
	v_lshl_add_u64 v[6:7], v[6:7], 0, v[0:1]
	v_lshl_add_u64 v[8:9], v[6:7], 0, s[24:25]
	v_add_co_u32_e32 v6, vcc, s19, v6
	s_cmp_ge_i32 s15, s16
	s_nop 0
	v_addc_co_u32_e32 v7, vcc, 0, v7, vcc
	global_load_dwordx4 v[34:37], v[8:9], off offset:32
	global_load_dwordx4 v[38:41], v[8:9], off offset:64
	global_load_dwordx4 v[42:45], v[6:7], off offset:2048
	global_load_dwordx4 v[46:49], v[8:9], off offset:96
	v_or_b32_e32 v6, 4, v3
	v_mad_i64_i32 v[6:7], s[20:21], v6, s22, v[4:5]
	v_lshl_add_u64 v[6:7], v[6:7], 0, v[182:183]
	v_lshl_add_u64 v[6:7], v[6:7], 0, v[0:1]
	v_lshl_add_u64 v[8:9], v[6:7], 0, s[24:25]
	v_add_co_u32_e32 v6, vcc, s19, v6
	v_or_b32_e32 v3, 6, v3
	s_nop 0
	v_addc_co_u32_e32 v7, vcc, 0, v7, vcc
	global_load_dwordx4 v[50:53], v[8:9], off offset:32
	global_load_dwordx4 v[54:57], v[8:9], off offset:64
	global_load_dwordx4 v[58:61], v[6:7], off offset:2048
	global_load_dwordx4 v[62:65], v[8:9], off offset:96
	v_mad_i64_i32 v[4:5], s[20:21], v3, s22, v[4:5]
	v_lshl_add_u32 v8, s8, 13, v2
	v_lshl_add_u64 v[4:5], v[4:5], 0, v[182:183]
	v_ashrrev_i32_e32 v9, 31, v8
	v_lshl_add_u64 v[4:5], v[4:5], 0, v[0:1]
	v_lshlrev_b64 v[8:9], 6, v[8:9]
	v_lshl_add_u64 v[6:7], v[4:5], 0, s[24:25]
	v_lshl_add_u64 v[8:9], v[180:181], 0, v[8:9]
	v_add_co_u32_e32 v4, vcc, s19, v4
	global_load_dword v3, v[8:9], off
	s_nop 0
	global_load_dword v8, v[8:9], off offset:256
	v_addc_co_u32_e32 v5, vcc, 0, v5, vcc
	global_load_dwordx4 v[66:69], v[6:7], off offset:32
	global_load_dwordx4 v[70:73], v[6:7], off offset:64
	global_load_dwordx4 v[74:77], v[4:5], off offset:2048
	global_load_dwordx4 v[78:81], v[6:7], off offset:96
	s_movk_i32 s23, 0x2000
	s_mov_b64 s[24:25], 0x2000
	s_waitcnt vmcnt(0)
	v_mul_f32_e32 v3, 0x3e000000, v3
	v_mul_f32_e32 v4, 0x3e000000, v8
	ds_write2st64_b32 v200, v3, v4 offset1:1
	s_waitcnt lgkmcnt(0)
	s_barrier
	s_cbranch_scc1 .LBB0_819
	s_mul_i32 s8, s8, 0x8100000
	s_add_u32 s8, s13, s8
	s_mul_hi_i32 s19, s18, s9
	s_mul_i32 s18, s18, s9
	s_addc_u32 s20, s14, 0
	s_lshl_b64 s[18:19], s[18:19], 13
	s_add_u32 s18, s8, s18
	s_addc_u32 s19, s20, s19
	s_lshl_b32 s8, s15, 5
	v_or_b32_e32 v3, s8, v178
	v_mov_b64_e32 v[4:5], s[6:7]
	v_mad_i64_i32 v[4:5], s[20:21], v3, s22, v[4:5]
	v_lshl_add_u64 v[4:5], v[4:5], 0, v[0:1]
	v_lshl_add_u64 v[6:7], v[4:5], 0, s[24:25]
	v_add_co_u32_e32 v4, vcc, s23, v4
	global_load_dwordx4 v[162:165], v[6:7], off offset:96
	s_nop 0
	v_addc_co_u32_e32 v5, vcc, 0, v5, vcc
	global_load_dwordx4 v[174:177], v[4:5], off
	global_load_dwordx4 v[170:173], v[6:7], off offset:32
	global_load_dwordx4 v[166:169], v[6:7], off offset:64
	ds_read_b128 v[82:85], v202
	ds_read_b128 v[86:89], v202 offset:16
	ds_read_b128 v[90:93], v202 offset:32
	ds_read_b128 v[94:97], v202 offset:48
	ds_read_b128 v[98:101], v202 offset:128
	ds_read_b128 v[102:105], v202 offset:144
	ds_read_b128 v[106:109], v202 offset:160
	ds_read_b128 v[110:113], v202 offset:176
	ds_read_b128 v[114:117], v202 offset:256
	ds_read_b128 v[118:121], v202 offset:272
	ds_read_b128 v[122:125], v202 offset:288
	ds_read_b128 v[126:129], v202 offset:304
	ds_read_b128 v[130:133], v202 offset:384
	ds_read_b128 v[134:137], v202 offset:400
	ds_read_b128 v[138:141], v202 offset:416
	ds_read_b128 v[142:145], v202 offset:432
	v_or_b32_e32 v2, v2, v179
	v_subrev_u32_e32 v2, s17, v2
	s_lshl_b32 s9, s9, 6
	v_mov_b32_e32 v185, v1
	v_or_b32_e32 v3, 2, v2
	v_lshl_add_u64 v[186:187], s[18:19], 0, v[184:185]
	v_mad_i64_i32 v[188:189], s[18:19], v2, s9, 0
	v_mad_i64_i32 v[190:191], s[18:19], v3, s9, 0
	v_or_b32_e32 v3, 4, v2
	v_or_b32_e32 v2, 6, v2
	v_mad_i64_i32 v[192:193], s[18:19], v3, s9, 0
	v_mad_i64_i32 v[194:195], s[18:19], v2, s9, 0
	s_add_i32 s19, s8, 32
	s_add_i32 s18, s15, 1
	s_cmp_lt_i32 s18, s16
	s_cselect_b32 s18, s19, s8
	v_or_b32_e32 v244, s18, v178
	v_mov_b64_e32 v[246:247], s[6:7]
	v_mad_i64_i32 v[246:247], s[18:19], v244, s22, v[246:247]
	v_lshl_add_u64 v[246:247], v[246:247], 0, v[0:1]
	v_lshl_add_u64 v[248:249], v[246:247], 0, s[24:25]
	v_add_co_u32_e32 v246, vcc, s23, v246
	s_nop 1
	v_addc_co_u32_e32 v247, vcc, 0, v247, vcc
	global_load_dwordx4 v[154:157], v[246:247], off
	global_load_dwordx4 v[150:153], v[248:249], off offset:32
	global_load_dwordx4 v[146:149], v[248:249], off offset:64
	global_load_dwordx4 v[158:161], v[248:249], off offset:96
	s_waitcnt vmcnt(4) lgkmcnt(0)
	v_mfma_f32_32x32x16_bf16 v[2:17], v[26:29], v[174:177], 0
	v_mfma_f32_32x32x16_bf16 v[2:17], v[18:21], v[170:173], v[2:17]
	v_mfma_f32_32x32x16_bf16 v[2:17], v[22:25], v[166:169], v[2:17]
	v_mfma_f32_32x32x16_bf16 v[2:17], v[30:33], v[162:165], v[2:17]
; #define MFMA(a, b, c) __builtin_amdgcn_mfma_f32_32x32x16_bf16((a), (b), (c), 0, 0, 0)
; DI void score_phase(const Params& p, char* smem) {
;     ...
; #pragma unroll 1
;     for (int nt2 = nt_lo; nt2 < nt_hi; ++nt2) {
;       const int k0 = nt2 * 32;
;       const int kn = (nt2 + 1 < nt_hi) ? (k0 + 32) : k0;
; #pragma unroll
;       for (int st = 0; st < 4; ++st) bnx[st] = *(const bf16x8*)(Hb + (size_t)(kn + r) * HLD + 4096 + st * 16 + 8 * h);
; #pragma unroll
;       for (int rt = 0; rt < 4; ++rt) {
;         f32x16 acc;
; #pragma unroll
;         for (int e = 0; e < 16; ++e) acc[e] = 0.f;
; #pragma unroll
;         for (int st = 0; st < 4; ++st) acc = MFMA(af[rt][st], bfr[st], acc);
;         float s = 0.f;
; #pragma unroll
;         for (int e4 = 0; e4 < 4; ++e4) {
;           const f32x4 wv = *(const f32x4*)(wl + (2 * rt + h) * 16 + e4 * 4);
; #pragma unroll
;           for (int i = 0; i < 4; ++i) s += fmaxf(acc[e4 * 4 + i], 0.f) * wv[i];
;         }
;         const int row = (t0 + 2 * rt + h) - blk * 64;
;         __builtin_nontemporal_store(s, scb + (size_t)row * n + k0 + r);
;       }
; #pragma unroll
;       for (int st = 0; st < 4; ++st) bfr[st] = bnx[st];
;     }
.LBB0_822:
	s_add_i32 s15, s15, 1
	s_add_i32 s17, s8, 32
	s_add_i32 s19, s8, 64
	s_add_i32 s18, s15, 1
	s_cmp_lt_i32 s18, s16
	s_cselect_b32 s18, s19, s8
	v_or_b32_e32 v244, s18, v178
	v_mov_b64_e32 v[246:247], s[6:7]
	v_mad_i64_i32 v[246:247], s[18:19], v244, s22, v[246:247]
	v_lshl_add_u64 v[246:247], v[246:247], 0, v[0:1]
	v_lshl_add_u64 v[248:249], v[246:247], 0, s[24:25]
	v_add_co_u32_e32 v246, vcc, s23, v246
	s_nop 1
	v_addc_co_u32_e32 v247, vcc, 0, v247, vcc
	global_load_dwordx4 v[204:207], v[246:247], off
	global_load_dwordx4 v[208:211], v[248:249], off offset:32
	global_load_dwordx4 v[212:215], v[248:249], off offset:64
	global_load_dwordx4 v[250:253], v[248:249], off offset:96
	s_ashr_i32 s9, s8, 31
	v_lshl_add_u64 v[196:197], s[8:9], 2, v[186:187]
	s_cmp_ge_i32 s15, s16
	s_mov_b32 s8, s17
	v_mfma_f32_32x32x16_bf16 v[224:239], v[42:45], v[174:177], 0
	v_max_f32_e32 v240, 0, v2
	v_fma_f32 v183, v82, v240, 0
	v_max_f32_e32 v241, 0, v3
	v_fmac_f32_e32 v183, v83, v241
	v_max_f32_e32 v240, 0, v4
	v_fmac_f32_e32 v183, v84, v240
	v_max_f32_e32 v241, 0, v5
	v_fmac_f32_e32 v183, v85, v241
	v_mfma_f32_32x32x16_bf16 v[224:239], v[34:37], v[170:173], v[224:239]
	v_max_f32_e32 v240, 0, v6
	v_fmac_f32_e32 v183, v86, v240
	v_max_f32_e32 v241, 0, v7
	v_fmac_f32_e32 v183, v87, v241
	v_max_f32_e32 v240, 0, v8
	v_fmac_f32_e32 v183, v88, v240
	v_max_f32_e32 v241, 0, v9
	v_fmac_f32_e32 v183, v89, v241
	v_mfma_f32_32x32x16_bf16 v[224:239], v[38:41], v[166:169], v[224:239]
	v_max_f32_e32 v240, 0, v10
	v_fmac_f32_e32 v183, v90, v240
	v_max_f32_e32 v241, 0, v11
	v_fmac_f32_e32 v183, v91, v241
	v_max_f32_e32 v240, 0, v12
	v_fmac_f32_e32 v183, v92, v240
	v_max_f32_e32 v241, 0, v13
	v_fmac_f32_e32 v183, v93, v241
	v_mfma_f32_32x32x16_bf16 v[224:239], v[46:49], v[162:165], v[224:239]
	v_max_f32_e32 v240, 0, v14
	v_fmac_f32_e32 v183, v94, v240
	v_max_f32_e32 v241, 0, v15
	v_fmac_f32_e32 v183, v95, v241
	v_max_f32_e32 v240, 0, v16
	v_fmac_f32_e32 v183, v96, v240
	v_max_f32_e32 v241, 0, v17
	v_fmac_f32_e32 v183, v97, v241
	v_lshl_add_u64 v[242:243], v[188:189], 2, v[196:197]
	global_store_dword v[242:243], v183, off nt
	s_nop 1
	v_mfma_f32_32x32x16_bf16 v[2:17], v[58:61], v[174:177], 0
	v_max_f32_e32 v240, 0, v224
	v_fma_f32 v183, v98, v240, 0
	v_max_f32_e32 v241, 0, v225
	v_fmac_f32_e32 v183, v99, v241
	v_max_f32_e32 v240, 0, v226
	v_fmac_f32_e32 v183, v100, v240
	v_max_f32_e32 v241, 0, v227
	v_fmac_f32_e32 v183, v101, v241
	v_mfma_f32_32x32x16_bf16 v[2:17], v[50:53], v[170:173], v[2:17]
	v_max_f32_e32 v240, 0, v228
	v_fmac_f32_e32 v183, v102, v240
	v_max_f32_e32 v241, 0, v229
	v_fmac_f32_e32 v183, v103, v241
	v_max_f32_e32 v240, 0, v230
	v_fmac_f32_e32 v183, v104, v240
	v_max_f32_e32 v241, 0, v231
	v_fmac_f32_e32 v183, v105, v241
	v_mfma_f32_32x32x16_bf16 v[2:17], v[54:57], v[166:169], v[2:17]
	v_max_f32_e32 v240, 0, v232
	v_fmac_f32_e32 v183, v106, v240
	v_max_f32_e32 v241, 0, v233
	v_fmac_f32_e32 v183, v107, v241
	v_max_f32_e32 v240, 0, v234
	v_fmac_f32_e32 v183, v108, v240
	v_max_f32_e32 v241, 0, v235
	v_fmac_f32_e32 v183, v109, v241
	v_mfma_f32_32x32x16_bf16 v[2:17], v[62:65], v[162:165], v[2:17]
	v_max_f32_e32 v240, 0, v236
	v_fmac_f32_e32 v183, v110, v240
	v_max_f32_e32 v241, 0, v237
	v_fmac_f32_e32 v183, v111, v241
	v_max_f32_e32 v240, 0, v238
	v_fmac_f32_e32 v183, v112, v240
	v_max_f32_e32 v241, 0, v239
	v_fmac_f32_e32 v183, v113, v241
	v_lshl_add_u64 v[242:243], v[190:191], 2, v[196:197]
	global_store_dword v[242:243], v183, off nt
	s_nop 1
	v_mfma_f32_32x32x16_bf16 v[224:239], v[74:77], v[174:177], 0
	v_max_f32_e32 v240, 0, v2
	v_fma_f32 v183, v114, v240, 0
	v_max_f32_e32 v241, 0, v3
	v_fmac_f32_e32 v183, v115, v241
	v_max_f32_e32 v240, 0, v4
	v_fmac_f32_e32 v183, v116, v240
	v_max_f32_e32 v241, 0, v5
	v_fmac_f32_e32 v183, v117, v241
	v_mfma_f32_32x32x16_bf16 v[224:239], v[66:69], v[170:173], v[224:239]
	v_max_f32_e32 v240, 0, v6
	v_fmac_f32_e32 v183, v118, v240
	v_max_f32_e32 v241, 0, v7
	v_fmac_f32_e32 v183, v119, v241
	v_max_f32_e32 v240, 0, v8
	v_fmac_f32_e32 v183, v120, v240
	v_max_f32_e32 v241, 0, v9
	v_fmac_f32_e32 v183, v121, v241
	v_mfma_f32_32x32x16_bf16 v[224:239], v[70:73], v[166:169], v[224:239]
	v_max_f32_e32 v240, 0, v10
	v_fmac_f32_e32 v183, v122, v240
	v_max_f32_e32 v241, 0, v11
	v_fmac_f32_e32 v183, v123, v241
	v_max_f32_e32 v240, 0, v12
	v_fmac_f32_e32 v183, v124, v240
	v_max_f32_e32 v241, 0, v13
	v_fmac_f32_e32 v183, v125, v241
	v_mfma_f32_32x32x16_bf16 v[224:239], v[78:81], v[162:165], v[224:239]
	v_max_f32_e32 v240, 0, v14
	v_fmac_f32_e32 v183, v126, v240
	v_max_f32_e32 v241, 0, v15
	v_fmac_f32_e32 v183, v127, v241
	v_max_f32_e32 v240, 0, v16
	v_fmac_f32_e32 v183, v128, v240
	v_max_f32_e32 v241, 0, v17
	v_fmac_f32_e32 v183, v129, v241
	v_lshl_add_u64 v[242:243], v[192:193], 2, v[196:197]
	global_store_dword v[242:243], v183, off nt
	s_nop 1
	s_waitcnt vmcnt(7)
	v_mfma_f32_32x32x16_bf16 v[2:17], v[26:29], v[154:157], 0
	v_max_f32_e32 v240, 0, v224
	v_fma_f32 v183, v130, v240, 0
	v_max_f32_e32 v241, 0, v225
	v_fmac_f32_e32 v183, v131, v241
	v_max_f32_e32 v240, 0, v226
	v_fmac_f32_e32 v183, v132, v240
	v_max_f32_e32 v241, 0, v227
	v_fmac_f32_e32 v183, v133, v241
	v_mfma_f32_32x32x16_bf16 v[2:17], v[18:21], v[150:153], v[2:17]
	v_max_f32_e32 v240, 0, v228
	v_fmac_f32_e32 v183, v134, v240
	v_max_f32_e32 v241, 0, v229
	v_fmac_f32_e32 v183, v135, v241
	v_max_f32_e32 v240, 0, v230
	v_fmac_f32_e32 v183, v136, v240
	v_max_f32_e32 v241, 0, v231
	v_fmac_f32_e32 v183, v137, v241
	v_mfma_f32_32x32x16_bf16 v[2:17], v[22:25], v[146:149], v[2:17]
	v_max_f32_e32 v240, 0, v232
	v_fmac_f32_e32 v183, v138, v240
	v_max_f32_e32 v241, 0, v233
	v_fmac_f32_e32 v183, v139, v241
	v_max_f32_e32 v240, 0, v234
	v_fmac_f32_e32 v183, v140, v240
	v_max_f32_e32 v241, 0, v235
	v_fmac_f32_e32 v183, v141, v241
	v_mfma_f32_32x32x16_bf16 v[2:17], v[30:33], v[158:161], v[2:17]
	v_max_f32_e32 v240, 0, v236
	v_fmac_f32_e32 v183, v142, v240
	v_max_f32_e32 v241, 0, v237
	v_fmac_f32_e32 v183, v143, v241
	v_max_f32_e32 v240, 0, v238
	v_fmac_f32_e32 v183, v144, v240
	v_max_f32_e32 v241, 0, v239
	v_fmac_f32_e32 v183, v145, v241
	v_lshl_add_u64 v[242:243], v[194:195], 2, v[196:197]
	global_store_dword v[242:243], v183, off nt
	s_nop 1
	s_cbranch_scc1 .LBB0_819
; #define MFMA(a, b, c) __builtin_amdgcn_mfma_f32_32x32x16_bf16((a), (b), (c), 0, 0, 0)
; DI void score_phase(const Params& p, char* smem) {
;     ...
; #pragma unroll 1
;     for (int nt2 = nt_lo; nt2 < nt_hi; ++nt2) {
;       const int k0 = nt2 * 32;
;       const int kn = (nt2 + 1 < nt_hi) ? (k0 + 32) : k0;
; #pragma unroll
;       for (int st = 0; st < 4; ++st) bnx[st] = *(const bf16x8*)(Hb + (size_t)(kn + r) * HLD + 4096 + st * 16 + 8 * h);
; #pragma unroll
;       for (int rt = 0; rt < 4; ++rt) {
;         f32x16 acc;
; #pragma unroll
;         for (int e = 0; e < 16; ++e) acc[e] = 0.f;
; #pragma unroll
;         for (int st = 0; st < 4; ++st) acc = MFMA(af[rt][st], bfr[st], acc);
;         float s = 0.f;
; #pragma unroll
;         for (int e4 = 0; e4 < 4; ++e4) {
;           const f32x4 wv = *(const f32x4*)(wl + (2 * rt + h) * 16 + e4 * 4);
; #pragma unroll
;           for (int i = 0; i < 4; ++i) s += fmaxf(acc[e4 * 4 + i], 0.f) * wv[i];
;         }
;         const int row = (t0 + 2 * rt + h) - blk * 64;
;         __builtin_nontemporal_store(s, scb + (size_t)row * n + k0 + r);
;       }
; #pragma unroll
;       for (int st = 0; st < 4; ++st) bfr[st] = bnx[st];
;     }
	s_add_i32 s15, s15, 1
	s_add_i32 s17, s8, 32
	s_add_i32 s19, s8, 64
	s_add_i32 s18, s15, 1
	s_cmp_lt_i32 s18, s16
	s_cselect_b32 s18, s19, s8
	v_or_b32_e32 v244, s18, v178
	v_mov_b64_e32 v[246:247], s[6:7]
	v_mad_i64_i32 v[246:247], s[18:19], v244, s22, v[246:247]
	v_lshl_add_u64 v[246:247], v[246:247], 0, v[0:1]
	v_lshl_add_u64 v[248:249], v[246:247], 0, s[24:25]
	v_add_co_u32_e32 v246, vcc, s23, v246
	s_nop 1
	v_addc_co_u32_e32 v247, vcc, 0, v247, vcc
	global_load_dwordx4 v[174:177], v[246:247], off
	global_load_dwordx4 v[170:173], v[248:249], off offset:32
	global_load_dwordx4 v[166:169], v[248:249], off offset:64
	global_load_dwordx4 v[162:165], v[248:249], off offset:96
	s_ashr_i32 s9, s8, 31
	v_lshl_add_u64 v[196:197], s[8:9], 2, v[186:187]
	s_cmp_ge_i32 s15, s16
	s_mov_b32 s8, s17
	v_mfma_f32_32x32x16_bf16 v[224:239], v[42:45], v[154:157], 0
	v_max_f32_e32 v240, 0, v2
	v_fma_f32 v183, v82, v240, 0
	v_max_f32_e32 v241, 0, v3
	v_fmac_f32_e32 v183, v83, v241
	v_max_f32_e32 v240, 0, v4
	v_fmac_f32_e32 v183, v84, v240
	v_max_f32_e32 v241, 0, v5
	v_fmac_f32_e32 v183, v85, v241
	v_mfma_f32_32x32x16_bf16 v[224:239], v[34:37], v[150:153], v[224:239]
	v_max_f32_e32 v240, 0, v6
	v_fmac_f32_e32 v183, v86, v240
	v_max_f32_e32 v241, 0, v7
	v_fmac_f32_e32 v183, v87, v241
	v_max_f32_e32 v240, 0, v8
	v_fmac_f32_e32 v183, v88, v240
	v_max_f32_e32 v241, 0, v9
	v_fmac_f32_e32 v183, v89, v241
	v_mfma_f32_32x32x16_bf16 v[224:239], v[38:41], v[146:149], v[224:239]
	v_max_f32_e32 v240, 0, v10
	v_fmac_f32_e32 v183, v90, v240
	v_max_f32_e32 v241, 0, v11
	v_fmac_f32_e32 v183, v91, v241
	v_max_f32_e32 v240, 0, v12
	v_fmac_f32_e32 v183, v92, v240
	v_max_f32_e32 v241, 0, v13
	v_fmac_f32_e32 v183, v93, v241
	v_mfma_f32_32x32x16_bf16 v[224:239], v[46:49], v[158:161], v[224:239]
	v_max_f32_e32 v240, 0, v14
	v_fmac_f32_e32 v183, v94, v240
	v_max_f32_e32 v241, 0, v15
	v_fmac_f32_e32 v183, v95, v241
	v_max_f32_e32 v240, 0, v16
	v_fmac_f32_e32 v183, v96, v240
	v_max_f32_e32 v241, 0, v17
	v_fmac_f32_e32 v183, v97, v241
	v_lshl_add_u64 v[242:243], v[188:189], 2, v[196:197]
	global_store_dword v[242:243], v183, off nt
	s_nop 1
	v_mfma_f32_32x32x16_bf16 v[2:17], v[58:61], v[154:157], 0
	v_max_f32_e32 v240, 0, v224
	v_fma_f32 v183, v98, v240, 0
	v_max_f32_e32 v241, 0, v225
	v_fmac_f32_e32 v183, v99, v241
	v_max_f32_e32 v240, 0, v226
	v_fmac_f32_e32 v183, v100, v240
	v_max_f32_e32 v241, 0, v227
	v_fmac_f32_e32 v183, v101, v241
	v_mfma_f32_32x32x16_bf16 v[2:17], v[50:53], v[150:153], v[2:17]
	v_max_f32_e32 v240, 0, v228
	v_fmac_f32_e32 v183, v102, v240
	v_max_f32_e32 v241, 0, v229
	v_fmac_f32_e32 v183, v103, v241
	v_max_f32_e32 v240, 0, v230
	v_fmac_f32_e32 v183, v104, v240
	v_max_f32_e32 v241, 0, v231
	v_fmac_f32_e32 v183, v105, v241
	v_mfma_f32_32x32x16_bf16 v[2:17], v[54:57], v[146:149], v[2:17]
	v_max_f32_e32 v240, 0, v232
	v_fmac_f32_e32 v183, v106, v240
	v_max_f32_e32 v241, 0, v233
	v_fmac_f32_e32 v183, v107, v241
	v_max_f32_e32 v240, 0, v234
	v_fmac_f32_e32 v183, v108, v240
	v_max_f32_e32 v241, 0, v235
	v_fmac_f32_e32 v183, v109, v241
	v_mfma_f32_32x32x16_bf16 v[2:17], v[62:65], v[158:161], v[2:17]
	v_max_f32_e32 v240, 0, v236
	v_fmac_f32_e32 v183, v110, v240
	v_max_f32_e32 v241, 0, v237
	v_fmac_f32_e32 v183, v111, v241
	v_max_f32_e32 v240, 0, v238
	v_fmac_f32_e32 v183, v112, v240
	v_max_f32_e32 v241, 0, v239
	v_fmac_f32_e32 v183, v113, v241
	v_lshl_add_u64 v[242:243], v[190:191], 2, v[196:197]
	global_store_dword v[242:243], v183, off nt
	s_nop 1
	v_mfma_f32_32x32x16_bf16 v[224:239], v[74:77], v[154:157], 0
	v_max_f32_e32 v240, 0, v2
	v_fma_f32 v183, v114, v240, 0
	v_max_f32_e32 v241, 0, v3
	v_fmac_f32_e32 v183, v115, v241
	v_max_f32_e32 v240, 0, v4
	v_fmac_f32_e32 v183, v116, v240
	v_max_f32_e32 v241, 0, v5
	v_fmac_f32_e32 v183, v117, v241
	v_mfma_f32_32x32x16_bf16 v[224:239], v[66:69], v[150:153], v[224:239]
	v_max_f32_e32 v240, 0, v6
	v_fmac_f32_e32 v183, v118, v240
	v_max_f32_e32 v241, 0, v7
	v_fmac_f32_e32 v183, v119, v241
	v_max_f32_e32 v240, 0, v8
	v_fmac_f32_e32 v183, v120, v240
	v_max_f32_e32 v241, 0, v9
	v_fmac_f32_e32 v183, v121, v241
	v_mfma_f32_32x32x16_bf16 v[224:239], v[70:73], v[146:149], v[224:239]
	v_max_f32_e32 v240, 0, v10
	v_fmac_f32_e32 v183, v122, v240
	v_max_f32_e32 v241, 0, v11
	v_fmac_f32_e32 v183, v123, v241
	v_max_f32_e32 v240, 0, v12
	v_fmac_f32_e32 v183, v124, v240
	v_max_f32_e32 v241, 0, v13
	v_fmac_f32_e32 v183, v125, v241
	v_mfma_f32_32x32x16_bf16 v[224:239], v[78:81], v[158:161], v[224:239]
	v_max_f32_e32 v240, 0, v14
	v_fmac_f32_e32 v183, v126, v240
	v_max_f32_e32 v241, 0, v15
	v_fmac_f32_e32 v183, v127, v241
	v_max_f32_e32 v240, 0, v16
	v_fmac_f32_e32 v183, v128, v240
	v_max_f32_e32 v241, 0, v17
	v_fmac_f32_e32 v183, v129, v241
	v_lshl_add_u64 v[242:243], v[192:193], 2, v[196:197]
	global_store_dword v[242:243], v183, off nt
	s_nop 1
	s_waitcnt vmcnt(7)
	v_mfma_f32_32x32x16_bf16 v[2:17], v[26:29], v[204:207], 0
	v_max_f32_e32 v240, 0, v224
	v_fma_f32 v183, v130, v240, 0
	v_max_f32_e32 v241, 0, v225
	v_fmac_f32_e32 v183, v131, v241
	v_max_f32_e32 v240, 0, v226
	v_fmac_f32_e32 v183, v132, v240
	v_max_f32_e32 v241, 0, v227
	v_fmac_f32_e32 v183, v133, v241
	v_mfma_f32_32x32x16_bf16 v[2:17], v[18:21], v[208:211], v[2:17]
	v_max_f32_e32 v240, 0, v228
	v_fmac_f32_e32 v183, v134, v240
	v_max_f32_e32 v241, 0, v229
	v_fmac_f32_e32 v183, v135, v241
	v_max_f32_e32 v240, 0, v230
	v_fmac_f32_e32 v183, v136, v240
	v_max_f32_e32 v241, 0, v231
	v_fmac_f32_e32 v183, v137, v241
	v_mfma_f32_32x32x16_bf16 v[2:17], v[22:25], v[212:215], v[2:17]
	v_max_f32_e32 v240, 0, v232
	v_fmac_f32_e32 v183, v138, v240
	v_max_f32_e32 v241, 0, v233
	v_fmac_f32_e32 v183, v139, v241
	v_max_f32_e32 v240, 0, v234
	v_fmac_f32_e32 v183, v140, v240
	v_max_f32_e32 v241, 0, v235
	v_fmac_f32_e32 v183, v141, v241
	v_mfma_f32_32x32x16_bf16 v[2:17], v[30:33], v[250:253], v[2:17]
	v_max_f32_e32 v240, 0, v236
	v_fmac_f32_e32 v183, v142, v240
	v_max_f32_e32 v241, 0, v237
	v_fmac_f32_e32 v183, v143, v241
	v_max_f32_e32 v240, 0, v238
	v_fmac_f32_e32 v183, v144, v240
	v_max_f32_e32 v241, 0, v239
	v_fmac_f32_e32 v183, v145, v241
	v_lshl_add_u64 v[242:243], v[194:195], 2, v[196:197]
	global_store_dword v[242:243], v183, off nt
	s_nop 1
	s_cbranch_scc1 .LBB0_819
; #define MFMA(a, b, c) __builtin_amdgcn_mfma_f32_32x32x16_bf16((a), (b), (c), 0, 0, 0)
; DI void score_phase(const Params& p, char* smem) {
;     ...
; #pragma unroll 1
;     for (int nt2 = nt_lo; nt2 < nt_hi; ++nt2) {
;       const int k0 = nt2 * 32;
;       const int kn = (nt2 + 1 < nt_hi) ? (k0 + 32) : k0;
; #pragma unroll
;       for (int st = 0; st < 4; ++st) bnx[st] = *(const bf16x8*)(Hb + (size_t)(kn + r) * HLD + 4096 + st * 16 + 8 * h);
; #pragma unroll
;       for (int rt = 0; rt < 4; ++rt) {
;         f32x16 acc;
; #pragma unroll
;         for (int e = 0; e < 16; ++e) acc[e] = 0.f;
; #pragma unroll
;         for (int st = 0; st < 4; ++st) acc = MFMA(af[rt][st], bfr[st], acc);
;         float s = 0.f;
; #pragma unroll
;         for (int e4 = 0; e4 < 4; ++e4) {
;           const f32x4 wv = *(const f32x4*)(wl + (2 * rt + h) * 16 + e4 * 4);
; #pragma unroll
;           for (int i = 0; i < 4; ++i) s += fmaxf(acc[e4 * 4 + i], 0.f) * wv[i];
;         }
;         const int row = (t0 + 2 * rt + h) - blk * 64;
;         __builtin_nontemporal_store(s, scb + (size_t)row * n + k0 + r);
;       }
; #pragma unroll
;       for (int st = 0; st < 4; ++st) bfr[st] = bnx[st];
;     }
	s_add_i32 s15, s15, 1
	s_add_i32 s17, s8, 32
	s_add_i32 s19, s8, 64
	s_add_i32 s18, s15, 1
	s_cmp_lt_i32 s18, s16
	s_cselect_b32 s18, s19, s8
	v_or_b32_e32 v244, s18, v178
	v_mov_b64_e32 v[246:247], s[6:7]
	v_mad_i64_i32 v[246:247], s[18:19], v244, s22, v[246:247]
	v_lshl_add_u64 v[246:247], v[246:247], 0, v[0:1]
	v_lshl_add_u64 v[248:249], v[246:247], 0, s[24:25]
	v_add_co_u32_e32 v246, vcc, s23, v246
	s_nop 1
	v_addc_co_u32_e32 v247, vcc, 0, v247, vcc
	global_load_dwordx4 v[154:157], v[246:247], off
	global_load_dwordx4 v[150:153], v[248:249], off offset:32
	global_load_dwordx4 v[146:149], v[248:249], off offset:64
	global_load_dwordx4 v[158:161], v[248:249], off offset:96
	s_ashr_i32 s9, s8, 31
	v_lshl_add_u64 v[196:197], s[8:9], 2, v[186:187]
	s_cmp_ge_i32 s15, s16
	s_mov_b32 s8, s17
	v_mfma_f32_32x32x16_bf16 v[224:239], v[42:45], v[204:207], 0
	v_max_f32_e32 v240, 0, v2
	v_fma_f32 v183, v82, v240, 0
	v_max_f32_e32 v241, 0, v3
	v_fmac_f32_e32 v183, v83, v241
	v_max_f32_e32 v240, 0, v4
	v_fmac_f32_e32 v183, v84, v240
	v_max_f32_e32 v241, 0, v5
	v_fmac_f32_e32 v183, v85, v241
	v_mfma_f32_32x32x16_bf16 v[224:239], v[34:37], v[208:211], v[224:239]
	v_max_f32_e32 v240, 0, v6
	v_fmac_f32_e32 v183, v86, v240
	v_max_f32_e32 v241, 0, v7
	v_fmac_f32_e32 v183, v87, v241
	v_max_f32_e32 v240, 0, v8
	v_fmac_f32_e32 v183, v88, v240
	v_max_f32_e32 v241, 0, v9
	v_fmac_f32_e32 v183, v89, v241
	v_mfma_f32_32x32x16_bf16 v[224:239], v[38:41], v[212:215], v[224:239]
	v_max_f32_e32 v240, 0, v10
	v_fmac_f32_e32 v183, v90, v240
	v_max_f32_e32 v241, 0, v11
	v_fmac_f32_e32 v183, v91, v241
	v_max_f32_e32 v240, 0, v12
	v_fmac_f32_e32 v183, v92, v240
	v_max_f32_e32 v241, 0, v13
	v_fmac_f32_e32 v183, v93, v241
	v_mfma_f32_32x32x16_bf16 v[224:239], v[46:49], v[250:253], v[224:239]
	v_max_f32_e32 v240, 0, v14
	v_fmac_f32_e32 v183, v94, v240
	v_max_f32_e32 v241, 0, v15
	v_fmac_f32_e32 v183, v95, v241
	v_max_f32_e32 v240, 0, v16
	v_fmac_f32_e32 v183, v96, v240
	v_max_f32_e32 v241, 0, v17
	v_fmac_f32_e32 v183, v97, v241
	v_lshl_add_u64 v[242:243], v[188:189], 2, v[196:197]
	global_store_dword v[242:243], v183, off nt
	s_nop 1
	v_mfma_f32_32x32x16_bf16 v[2:17], v[58:61], v[204:207], 0
	v_max_f32_e32 v240, 0, v224
	v_fma_f32 v183, v98, v240, 0
	v_max_f32_e32 v241, 0, v225
	v_fmac_f32_e32 v183, v99, v241
	v_max_f32_e32 v240, 0, v226
	v_fmac_f32_e32 v183, v100, v240
	v_max_f32_e32 v241, 0, v227
	v_fmac_f32_e32 v183, v101, v241
	v_mfma_f32_32x32x16_bf16 v[2:17], v[50:53], v[208:211], v[2:17]
	v_max_f32_e32 v240, 0, v228
	v_fmac_f32_e32 v183, v102, v240
	v_max_f32_e32 v241, 0, v229
	v_fmac_f32_e32 v183, v103, v241
	v_max_f32_e32 v240, 0, v230
	v_fmac_f32_e32 v183, v104, v240
	v_max_f32_e32 v241, 0, v231
	v_fmac_f32_e32 v183, v105, v241
	v_mfma_f32_32x32x16_bf16 v[2:17], v[54:57], v[212:215], v[2:17]
	v_max_f32_e32 v240, 0, v232
	v_fmac_f32_e32 v183, v106, v240
	v_max_f32_e32 v241, 0, v233
	v_fmac_f32_e32 v183, v107, v241
	v_max_f32_e32 v240, 0, v234
	v_fmac_f32_e32 v183, v108, v240
	v_max_f32_e32 v241, 0, v235
	v_fmac_f32_e32 v183, v109, v241
	v_mfma_f32_32x32x16_bf16 v[2:17], v[62:65], v[250:253], v[2:17]
	v_max_f32_e32 v240, 0, v236
	v_fmac_f32_e32 v183, v110, v240
	v_max_f32_e32 v241, 0, v237
	v_fmac_f32_e32 v183, v111, v241
	v_max_f32_e32 v240, 0, v238
	v_fmac_f32_e32 v183, v112, v240
	v_max_f32_e32 v241, 0, v239
	v_fmac_f32_e32 v183, v113, v241
	v_lshl_add_u64 v[242:243], v[190:191], 2, v[196:197]
	global_store_dword v[242:243], v183, off nt
	s_nop 1
	v_mfma_f32_32x32x16_bf16 v[224:239], v[74:77], v[204:207], 0
	v_max_f32_e32 v240, 0, v2
	v_fma_f32 v183, v114, v240, 0
	v_max_f32_e32 v241, 0, v3
	v_fmac_f32_e32 v183, v115, v241
	v_max_f32_e32 v240, 0, v4
	v_fmac_f32_e32 v183, v116, v240
	v_max_f32_e32 v241, 0, v5
	v_fmac_f32_e32 v183, v117, v241
	v_mfma_f32_32x32x16_bf16 v[224:239], v[66:69], v[208:211], v[224:239]
	v_max_f32_e32 v240, 0, v6
	v_fmac_f32_e32 v183, v118, v240
	v_max_f32_e32 v241, 0, v7
	v_fmac_f32_e32 v183, v119, v241
	v_max_f32_e32 v240, 0, v8
	v_fmac_f32_e32 v183, v120, v240
	v_max_f32_e32 v241, 0, v9
	v_fmac_f32_e32 v183, v121, v241
	v_mfma_f32_32x32x16_bf16 v[224:239], v[70:73], v[212:215], v[224:239]
	v_max_f32_e32 v240, 0, v10
	v_fmac_f32_e32 v183, v122, v240
	v_max_f32_e32 v241, 0, v11
	v_fmac_f32_e32 v183, v123, v241
	v_max_f32_e32 v240, 0, v12
	v_fmac_f32_e32 v183, v124, v240
	v_max_f32_e32 v241, 0, v13
	v_fmac_f32_e32 v183, v125, v241
	v_mfma_f32_32x32x16_bf16 v[224:239], v[78:81], v[250:253], v[224:239]
	v_max_f32_e32 v240, 0, v14
	v_fmac_f32_e32 v183, v126, v240
	v_max_f32_e32 v241, 0, v15
	v_fmac_f32_e32 v183, v127, v241
	v_max_f32_e32 v240, 0, v16
	v_fmac_f32_e32 v183, v128, v240
	v_max_f32_e32 v241, 0, v17
	v_fmac_f32_e32 v183, v129, v241
	v_lshl_add_u64 v[242:243], v[192:193], 2, v[196:197]
	global_store_dword v[242:243], v183, off nt
	s_nop 1
	s_waitcnt vmcnt(7)
	v_mfma_f32_32x32x16_bf16 v[2:17], v[26:29], v[174:177], 0
	v_max_f32_e32 v240, 0, v224
	v_fma_f32 v183, v130, v240, 0
	v_max_f32_e32 v241, 0, v225
	v_fmac_f32_e32 v183, v131, v241
	v_max_f32_e32 v240, 0, v226
	v_fmac_f32_e32 v183, v132, v240
	v_max_f32_e32 v241, 0, v227
	v_fmac_f32_e32 v183, v133, v241
	v_mfma_f32_32x32x16_bf16 v[2:17], v[18:21], v[170:173], v[2:17]
	v_max_f32_e32 v240, 0, v228
	v_fmac_f32_e32 v183, v134, v240
	v_max_f32_e32 v241, 0, v229
	v_fmac_f32_e32 v183, v135, v241
	v_max_f32_e32 v240, 0, v230
	v_fmac_f32_e32 v183, v136, v240
	v_max_f32_e32 v241, 0, v231
	v_fmac_f32_e32 v183, v137, v241
	v_mfma_f32_32x32x16_bf16 v[2:17], v[22:25], v[166:169], v[2:17]
	v_max_f32_e32 v240, 0, v232
	v_fmac_f32_e32 v183, v138, v240
	v_max_f32_e32 v241, 0, v233
	v_fmac_f32_e32 v183, v139, v241
	v_max_f32_e32 v240, 0, v234
	v_fmac_f32_e32 v183, v140, v240
	v_max_f32_e32 v241, 0, v235
	v_fmac_f32_e32 v183, v141, v241
	v_mfma_f32_32x32x16_bf16 v[2:17], v[30:33], v[162:165], v[2:17]
	v_max_f32_e32 v240, 0, v236
	v_fmac_f32_e32 v183, v142, v240
	v_max_f32_e32 v241, 0, v237
	v_fmac_f32_e32 v183, v143, v241
	v_max_f32_e32 v240, 0, v238
	v_fmac_f32_e32 v183, v144, v240
	v_max_f32_e32 v241, 0, v239
	v_fmac_f32_e32 v183, v145, v241
	v_lshl_add_u64 v[242:243], v[194:195], 2, v[196:197]
	global_store_dword v[242:243], v183, off nt
	s_nop 1
	s_cbranch_scc0 .LBB0_822
	s_branch .LBB0_819
